# A/B: back-to-back s_setprio 0 / s_setprio 1 pairs between the two 16-MFMA groups of each GEMM sub-phase deleted (priority stays 1 across the 32 MFMAs), 32 sites
# speedup vs baseline: 1.0156x; 1.0041x over previous
; #define PG8_STAGE(bufoff, gbase, voff) do { _Pragma("unroll") for (int _i = 0; _i < 2; ++_i) \
;         __builtin_amdgcn_global_load_lds((const unsigned*)((const char*)(gbase) + (voff)[_i]), (PG8_LAS unsigned*)(lds + (bufoff) + ldsw + _i * 8192), 16, 0, 0); } while (0)
; #define PG8_LDA(dst, b, h) do { _Pragma("unroll") for (int m = 0; m < 4; ++m) _Pragma("unroll") for (int k = 0; k < 2; ++k) dst[m][k] = *(const PG8_LAS bf16x8*)(lds + PG8_SA(b, h) + aoff + m * 2048 + k * 1024); } while (0)
; #define PG8_LDB(dst, b, h) do { _Pragma("unroll") for (int n = 0; n < 2; ++n) _Pragma("unroll") for (int k = 0; k < 2; ++k) dst[n][k] = *(const PG8_LAS bf16x8*)(lds + PG8_SB(b, h) + boff + n * 2048 + k * 1024); } while (0)
; #define PG8_MMA(ai, bj, At, Bt) do { __builtin_amdgcn_s_setprio(1); _Pragma("unroll") for (int m = 0; m < 4; ++m) _Pragma("unroll") for (int n = 0; n < 2; ++n) _Pragma("unroll") for (int k = 0; k < 2; ++k) \
;         acc[ai][bj][m][n] = __builtin_amdgcn_mfma_f32_16x16x32_bf16(Bt[n][k], At[m][k], acc[ai][bj][m][n], 0, 0, 0); __builtin_amdgcn_s_setprio(0); } while (0)
; #define PG8_WAIT_V(n) asm volatile("s_waitcnt vmcnt(" #n ")" ::: "memory")
; #define PG8_WAIT_L(n) asm volatile("s_waitcnt lgkmcnt(" #n ")" ::: "memory")
; template <class Epi, class Sched, bool ALIGN_EPI = false, bool SP2 = false>
; __device__ __forceinline__ void gemm_phase(PG8_LAS unsigned char* lds, const Gemm g, const Sched& S, const Epi& E, const int tid) {
;     ...
;             const bool last = (t == nt - 2);
;             const char* a1 = cA + (size_t)(t + 1) * kstep;
;             const char* a2 = last ? nA : cA + (size_t)(t + 2) * kstep; const char* b2 = last ? nB : cB + (size_t)(t + 2) * kstep;
;             const char* a3 = a2 + kstep; const char* b3 = b2 + kstep;
;             if (last && has_next) S.a_ready(nxt);
;             if constexpr (SP2) {
;             PG8_LDB(B0, 0, 0); PG8_LDB(B1, 0, 1); PG8_SCHED; PG8_LDA(At, 0, 0); PG8_STAGE(PG8_SA(1, 1), a1 + hstep, voffA);
;             PG8_WAIT_V(8); PG8_WAIT_L(0); PG8_BAR; PG8_MMA(0, 0, At, B0); PG8_MMA(0, 1, At, B1); PG8_BAR; PG8_SCHED;
;             PG8_LDA(At, 0, 1); PG8_STAGE(PG8_SB(0, 0), b2, voffB); PG8_STAGE(PG8_SB(0, 1), b2 + hstep, voffB); PG8_STAGE(PG8_SA(0, 0), a2, voffA);
;             PG8_WAIT_V(8); PG8_WAIT_L(0); PG8_BAR; PG8_MMA(1, 0, At, B0); PG8_MMA(1, 1, At, B1); PG8_BAR; PG8_SCHED;
.LBB0_137:
	s_add_u32 s16, s10, s14
	s_addc_u32 s17, s11, s15
	s_add_u32 s16, s16, 0x100
	s_addc_u32 s17, s17, 0
	s_add_u32 s52, s49, s14
	s_addc_u32 s53, s50, s15
	s_add_i32 s54, 0, 0x10000
	s_cmpk_eq_i32 s14, 0x1500
	s_cselect_b32 s19, s13, s17
	s_cselect_b32 s18, s12, s16
	v_add_u32_e32 v147, s54, v145
	s_cselect_b32 s17, s5, s53
	s_cselect_b32 s16, s4, s52
	s_add_i32 s55, 0, 0x14000
	ds_read_b128 v[148:151], v147
	ds_read_b128 v[152:155], v147 offset:1024
	ds_read_b128 v[160:163], v147 offset:2048
	ds_read_b128 v[164:167], v147 offset:3072
	v_add_u32_e32 v147, s55, v145
	ds_read_b128 v[168:171], v147
	ds_read_b128 v[172:175], v147 offset:1024
	ds_read_b128 v[176:179], v147 offset:2048
	ds_read_b128 v[180:183], v147 offset:3072
	v_lshl_add_u64 v[156:157], v[142:143], 0, s[14:15]
	s_add_i32 m0, s29, 0xc000
	ds_read_b128 v[184:187], v146
	ds_read_b128 v[188:191], v146 offset:1024
	ds_read_b128 v[192:195], v146 offset:2048
	ds_read_b128 v[196:199], v146 offset:3072
	ds_read_b128 v[200:203], v146 offset:4096
	ds_read_b128 v[206:209], v146 offset:5120
	ds_read_b128 v[214:217], v146 offset:6144
	ds_read_b128 v[218:221], v146 offset:7168
	global_load_lds_dwordx4 v[156:157], off
	v_lshl_add_u64 v[156:157], v[140:141], 0, s[14:15]
	s_add_i32 m0, s29, 0xe000
	s_nop 0
	global_load_lds_dwordx4 v[156:157], off
	s_waitcnt vmcnt(8)
	s_waitcnt lgkmcnt(0)
	s_barrier
	s_setprio 1
	v_mfma_f32_16x16x32_bf16 v[32:35], v[148:151], v[184:187], v[32:35]
	v_mfma_f32_16x16x32_bf16 v[36:39], v[160:163], v[184:187], v[36:39]
	v_mfma_f32_16x16x32_bf16 v[48:51], v[148:151], v[192:195], v[48:51]
	v_mfma_f32_16x16x32_bf16 v[52:55], v[160:163], v[192:195], v[52:55]
	v_mfma_f32_16x16x32_bf16 v[56:59], v[148:151], v[200:203], v[56:59]
	v_mfma_f32_16x16x32_bf16 v[60:63], v[160:163], v[200:203], v[60:63]
	v_mfma_f32_16x16x32_bf16 v[74:77], v[148:151], v[214:217], v[74:77]
	v_mfma_f32_16x16x32_bf16 v[78:81], v[160:163], v[214:217], v[78:81]
	v_mfma_f32_16x16x32_bf16 v[32:35], v[152:155], v[188:191], v[32:35]
	v_mfma_f32_16x16x32_bf16 v[36:39], v[164:167], v[188:191], v[36:39]
	v_mfma_f32_16x16x32_bf16 v[48:51], v[152:155], v[196:199], v[48:51]
	v_mfma_f32_16x16x32_bf16 v[52:55], v[164:167], v[196:199], v[52:55]
	v_mfma_f32_16x16x32_bf16 v[56:59], v[152:155], v[206:209], v[56:59]
	v_mfma_f32_16x16x32_bf16 v[60:63], v[164:167], v[206:209], v[60:63]
	v_mfma_f32_16x16x32_bf16 v[74:77], v[152:155], v[218:221], v[74:77]
	v_mfma_f32_16x16x32_bf16 v[78:81], v[164:167], v[218:221], v[78:81]
	v_mfma_f32_16x16x32_bf16 v[106:109], v[168:171], v[184:187], v[106:109]
	v_mfma_f32_16x16x32_bf16 v[110:113], v[176:179], v[184:187], v[110:113]
	v_mfma_f32_16x16x32_bf16 v[102:105], v[168:171], v[192:195], v[102:105]
	v_mfma_f32_16x16x32_bf16 v[98:101], v[176:179], v[192:195], v[98:101]
	v_mfma_f32_16x16x32_bf16 v[70:73], v[168:171], v[200:203], v[70:73]
	v_mfma_f32_16x16x32_bf16 v[66:69], v[176:179], v[200:203], v[66:69]
	v_mfma_f32_16x16x32_bf16 v[44:47], v[168:171], v[214:217], v[44:47]
	v_mfma_f32_16x16x32_bf16 v[40:43], v[176:179], v[214:217], v[40:43]
	v_mfma_f32_16x16x32_bf16 v[106:109], v[172:175], v[188:191], v[106:109]
	v_mfma_f32_16x16x32_bf16 v[110:113], v[180:183], v[188:191], v[110:113]
	v_mfma_f32_16x16x32_bf16 v[102:105], v[172:175], v[196:199], v[102:105]
	v_mfma_f32_16x16x32_bf16 v[98:101], v[180:183], v[196:199], v[98:101]
	v_mfma_f32_16x16x32_bf16 v[70:73], v[172:175], v[206:209], v[70:73]
	v_mfma_f32_16x16x32_bf16 v[66:69], v[180:183], v[206:209], v[66:69]
	v_mfma_f32_16x16x32_bf16 v[44:47], v[172:175], v[218:221], v[44:47]
	v_mfma_f32_16x16x32_bf16 v[40:43], v[180:183], v[218:221], v[40:43]
	s_setprio 0
	s_barrier
	s_add_i32 s52, s54, s28
	v_lshl_add_u64 v[156:157], s[16:17], 0, v[64:65]
	s_mov_b32 m0, s52
	ds_read_b128 v[184:187], v146 offset:16384
	ds_read_b128 v[188:191], v146 offset:17408
	ds_read_b128 v[192:195], v146 offset:18432
	ds_read_b128 v[196:199], v146 offset:19456
	ds_read_b128 v[200:203], v146 offset:20480
	ds_read_b128 v[206:209], v146 offset:21504
	ds_read_b128 v[214:217], v146 offset:22528
	ds_read_b128 v[218:221], v146 offset:23552
	global_load_lds_dwordx4 v[156:157], off
	s_add_i32 m0, s52, 0x2000
	s_add_u32 s52, s16, 0xb0000
	v_lshl_add_u64 v[210:211], s[16:17], 0, v[130:131]
	s_addc_u32 s53, s17, 0
	s_add_i32 s54, s55, s28
	global_load_lds_dwordx4 v[210:211], off
	v_lshl_add_u64 v[222:223], s[52:53], 0, v[64:65]
	s_mov_b32 m0, s54
	v_lshl_add_u64 v[224:225], s[18:19], 0, v[132:133]
	global_load_lds_dwordx4 v[222:223], off
	v_lshl_add_u64 v[222:223], s[52:53], 0, v[130:131]
	s_add_i32 m0, s54, 0x2000
	s_nop 0
	global_load_lds_dwordx4 v[222:223], off
	v_lshl_add_u64 v[222:223], s[18:19], 0, v[134:135]
	s_mov_b32 m0, s29
	s_nop 0
	global_load_lds_dwordx4 v[222:223], off
	s_mov_b32 m0, s30
	s_nop 0
	global_load_lds_dwordx4 v[224:225], off
	s_waitcnt vmcnt(8)
	s_waitcnt lgkmcnt(0)
	s_barrier
; #define PG8_STAGE(bufoff, gbase, voff) do { _Pragma("unroll") for (int _i = 0; _i < 2; ++_i) \
;         __builtin_amdgcn_global_load_lds((const unsigned*)((const char*)(gbase) + (voff)[_i]), (PG8_LAS unsigned*)(lds + (bufoff) + ldsw + _i * 8192), 16, 0, 0); } while (0)
; #define PG8_LDA(dst, b, h) do { _Pragma("unroll") for (int m = 0; m < 4; ++m) _Pragma("unroll") for (int k = 0; k < 2; ++k) dst[m][k] = *(const PG8_LAS bf16x8*)(lds + PG8_SA(b, h) + aoff + m * 2048 + k * 1024); } while (0)
; #define PG8_LDB(dst, b, h) do { _Pragma("unroll") for (int n = 0; n < 2; ++n) _Pragma("unroll") for (int k = 0; k < 2; ++k) dst[n][k] = *(const PG8_LAS bf16x8*)(lds + PG8_SB(b, h) + boff + n * 2048 + k * 1024); } while (0)
; #define PG8_MMA(ai, bj, At, Bt) do { __builtin_amdgcn_s_setprio(1); _Pragma("unroll") for (int m = 0; m < 4; ++m) _Pragma("unroll") for (int n = 0; n < 2; ++n) _Pragma("unroll") for (int k = 0; k < 2; ++k) \
;         acc[ai][bj][m][n] = __builtin_amdgcn_mfma_f32_16x16x32_bf16(Bt[n][k], At[m][k], acc[ai][bj][m][n], 0, 0, 0); __builtin_amdgcn_s_setprio(0); } while (0)
; #define PG8_WAIT_V(n) asm volatile("s_waitcnt vmcnt(" #n ")" ::: "memory")
; #define PG8_WAIT_L(n) asm volatile("s_waitcnt lgkmcnt(" #n ")" ::: "memory")
; #define PG8_BAR __builtin_amdgcn_s_barrier()
; #define PG8_SCHED __builtin_amdgcn_sched_barrier(0)
; template <class Epi, class Sched, bool ALIGN_EPI = false, bool SP2 = false>
; __device__ __forceinline__ void gemm_phase(PG8_LAS unsigned char* lds, const Gemm g, const Sched& S, const Epi& E, const int tid) {
;     ...
;             PG8_WAIT_V(8); PG8_WAIT_L(0); PG8_BAR; PG8_MMA(1, 0, At, B0); PG8_MMA(1, 1, At, B1); PG8_BAR; PG8_SCHED;
;             PG8_LDB(B0, 1, 0); PG8_LDB(B1, 1, 1); PG8_SCHED; PG8_LDA(At, 1, 0); PG8_STAGE(PG8_SA(0, 1), a2 + hstep, voffA);
;             PG8_WAIT_V(8); PG8_WAIT_L(0); PG8_BAR; PG8_MMA(0, 0, At, B0); PG8_MMA(0, 1, At, B1); PG8_BAR; PG8_SCHED;
	s_setprio 1
	v_mfma_f32_16x16x32_bf16 v[82:85], v[148:151], v[184:187], v[82:85]
	v_mfma_f32_16x16x32_bf16 v[86:89], v[160:163], v[184:187], v[86:89]
	v_mfma_f32_16x16x32_bf16 v[90:93], v[148:151], v[192:195], v[90:93]
	v_mfma_f32_16x16x32_bf16 v[94:97], v[160:163], v[192:195], v[94:97]
	v_mfma_f32_16x16x32_bf16 v[114:117], v[148:151], v[200:203], v[114:117]
	v_mfma_f32_16x16x32_bf16 v[118:121], v[160:163], v[200:203], v[118:121]
	v_mfma_f32_16x16x32_bf16 v[122:125], v[148:151], v[214:217], v[122:125]
	v_mfma_f32_16x16x32_bf16 v[126:129], v[160:163], v[214:217], v[126:129]
	v_mfma_f32_16x16x32_bf16 v[82:85], v[152:155], v[188:191], v[82:85]
	v_mfma_f32_16x16x32_bf16 v[86:89], v[164:167], v[188:191], v[86:89]
	v_mfma_f32_16x16x32_bf16 v[90:93], v[152:155], v[196:199], v[90:93]
	v_mfma_f32_16x16x32_bf16 v[94:97], v[164:167], v[196:199], v[94:97]
	v_mfma_f32_16x16x32_bf16 v[114:117], v[152:155], v[206:209], v[114:117]
	v_mfma_f32_16x16x32_bf16 v[118:121], v[164:167], v[206:209], v[118:121]
	v_mfma_f32_16x16x32_bf16 v[122:125], v[152:155], v[218:221], v[122:125]
	v_mfma_f32_16x16x32_bf16 v[126:129], v[164:167], v[218:221], v[126:129]
	v_mfma_f32_16x16x32_bf16 v[28:31], v[168:171], v[184:187], v[28:31]
	v_mfma_f32_16x16x32_bf16 v[24:27], v[176:179], v[184:187], v[24:27]
	v_mfma_f32_16x16x32_bf16 v[20:23], v[168:171], v[192:195], v[20:23]
	v_mfma_f32_16x16x32_bf16 v[16:19], v[176:179], v[192:195], v[16:19]
	v_mfma_f32_16x16x32_bf16 v[12:15], v[168:171], v[200:203], v[12:15]
	v_mfma_f32_16x16x32_bf16 v[8:11], v[176:179], v[200:203], v[8:11]
	v_mfma_f32_16x16x32_bf16 v[4:7], v[168:171], v[214:217], v[4:7]
	v_mfma_f32_16x16x32_bf16 v[0:3], v[176:179], v[214:217], v[0:3]
	v_mfma_f32_16x16x32_bf16 v[28:31], v[172:175], v[188:191], v[28:31]
	v_mfma_f32_16x16x32_bf16 v[24:27], v[180:183], v[188:191], v[24:27]
	v_mfma_f32_16x16x32_bf16 v[20:23], v[172:175], v[196:199], v[20:23]
	v_mfma_f32_16x16x32_bf16 v[16:19], v[180:183], v[196:199], v[16:19]
	v_mfma_f32_16x16x32_bf16 v[12:15], v[172:175], v[206:209], v[12:15]
	v_mfma_f32_16x16x32_bf16 v[8:11], v[180:183], v[206:209], v[8:11]
	v_mfma_f32_16x16x32_bf16 v[4:7], v[172:175], v[218:221], v[4:7]
	v_mfma_f32_16x16x32_bf16 v[0:3], v[180:183], v[218:221], v[0:3]
	s_setprio 0
	s_barrier
	s_add_i32 s52, 0, 0x18000
	v_add_u32_e32 v147, s52, v145
	s_add_i32 s53, 0, 0x1c000
	ds_read_b128 v[148:151], v147
	ds_read_b128 v[152:155], v147 offset:1024
	ds_read_b128 v[160:163], v147 offset:2048
	ds_read_b128 v[164:167], v147 offset:3072
	v_add_u32_e32 v147, s53, v145
	ds_read_b128 v[168:171], v147
	ds_read_b128 v[172:175], v147 offset:1024
	ds_read_b128 v[176:179], v147 offset:2048
	ds_read_b128 v[180:183], v147 offset:3072
	s_add_u32 s18, s18, 0xb0000
	s_addc_u32 s19, s19, 0
	s_mov_b32 m0, s31
	v_lshl_add_u64 v[226:227], s[18:19], 0, v[134:135]
	ds_read_b128 v[184:187], v146 offset:32768
	ds_read_b128 v[188:191], v146 offset:33792
	ds_read_b128 v[192:195], v146 offset:34816
	ds_read_b128 v[196:199], v146 offset:35840
	ds_read_b128 v[200:203], v146 offset:36864
	ds_read_b128 v[206:209], v146 offset:37888
	ds_read_b128 v[214:217], v146 offset:38912
	ds_read_b128 v[218:221], v146 offset:39936
	global_load_lds_dwordx4 v[226:227], off
	v_lshl_add_u64 v[226:227], s[18:19], 0, v[132:133]
	s_mov_b32 m0, s34
	s_nop 0
	global_load_lds_dwordx4 v[226:227], off
	s_waitcnt vmcnt(8)
	s_waitcnt lgkmcnt(0)
	s_barrier
	s_setprio 1
	v_mfma_f32_16x16x32_bf16 v[32:35], v[148:151], v[184:187], v[32:35]
	v_mfma_f32_16x16x32_bf16 v[36:39], v[160:163], v[184:187], v[36:39]
	v_mfma_f32_16x16x32_bf16 v[48:51], v[148:151], v[192:195], v[48:51]
	v_mfma_f32_16x16x32_bf16 v[52:55], v[160:163], v[192:195], v[52:55]
	v_mfma_f32_16x16x32_bf16 v[56:59], v[148:151], v[200:203], v[56:59]
	v_mfma_f32_16x16x32_bf16 v[60:63], v[160:163], v[200:203], v[60:63]
	v_mfma_f32_16x16x32_bf16 v[74:77], v[148:151], v[214:217], v[74:77]
	v_mfma_f32_16x16x32_bf16 v[78:81], v[160:163], v[214:217], v[78:81]
	v_mfma_f32_16x16x32_bf16 v[32:35], v[152:155], v[188:191], v[32:35]
	v_mfma_f32_16x16x32_bf16 v[36:39], v[164:167], v[188:191], v[36:39]
	v_mfma_f32_16x16x32_bf16 v[48:51], v[152:155], v[196:199], v[48:51]
	v_mfma_f32_16x16x32_bf16 v[52:55], v[164:167], v[196:199], v[52:55]
	v_mfma_f32_16x16x32_bf16 v[56:59], v[152:155], v[206:209], v[56:59]
	v_mfma_f32_16x16x32_bf16 v[60:63], v[164:167], v[206:209], v[60:63]
	v_mfma_f32_16x16x32_bf16 v[74:77], v[152:155], v[218:221], v[74:77]
	v_mfma_f32_16x16x32_bf16 v[78:81], v[164:167], v[218:221], v[78:81]
	v_mfma_f32_16x16x32_bf16 v[106:109], v[168:171], v[184:187], v[106:109]
	v_mfma_f32_16x16x32_bf16 v[110:113], v[176:179], v[184:187], v[110:113]
	v_mfma_f32_16x16x32_bf16 v[102:105], v[168:171], v[192:195], v[102:105]
	v_mfma_f32_16x16x32_bf16 v[98:101], v[176:179], v[192:195], v[98:101]
	v_mfma_f32_16x16x32_bf16 v[70:73], v[168:171], v[200:203], v[70:73]
	v_mfma_f32_16x16x32_bf16 v[66:69], v[176:179], v[200:203], v[66:69]
	v_mfma_f32_16x16x32_bf16 v[44:47], v[168:171], v[214:217], v[44:47]
	v_mfma_f32_16x16x32_bf16 v[40:43], v[176:179], v[214:217], v[40:43]
	v_mfma_f32_16x16x32_bf16 v[106:109], v[172:175], v[188:191], v[106:109]
	v_mfma_f32_16x16x32_bf16 v[110:113], v[180:183], v[188:191], v[110:113]
	v_mfma_f32_16x16x32_bf16 v[102:105], v[172:175], v[196:199], v[102:105]
	v_mfma_f32_16x16x32_bf16 v[98:101], v[180:183], v[196:199], v[98:101]
	v_mfma_f32_16x16x32_bf16 v[70:73], v[172:175], v[206:209], v[70:73]
	v_mfma_f32_16x16x32_bf16 v[66:69], v[180:183], v[206:209], v[66:69]
	v_mfma_f32_16x16x32_bf16 v[44:47], v[172:175], v[218:221], v[44:47]
	v_mfma_f32_16x16x32_bf16 v[40:43], v[180:183], v[218:221], v[40:43]
	s_setprio 0
	s_barrier
; #define PG8_BAR __builtin_amdgcn_s_barrier()
; template <class Epi, class Sched, bool ALIGN_EPI = false, bool SP2 = false>
; __device__ __forceinline__ void gemm_phase(PG8_LAS unsigned char* lds, const Gemm g, const Sched& S, const Epi& E, const int tid) {
;     ...
;         for (int t = 0; t < nt; t += 2) {
;             const bool last = (t == nt - 2);
;             const char* a1 = cA + (size_t)(t + 1) * kstep;
;             const char* a2 = last ? nA : cA + (size_t)(t + 2) * kstep; const char* b2 = last ? nB : cB + (size_t)(t + 2) * kstep;
;             const char* a3 = a2 + kstep; const char* b3 = b2 + kstep;
;             if (last && has_next) S.a_ready(nxt);
;             if constexpr (SP2) {
;             PG8_LDB(B0, 0, 0); PG8_LDB(B1, 0, 1); PG8_SCHED; PG8_LDA(At, 0, 0); PG8_STAGE(PG8_SA(1, 1), a1 + hstep, voffA);
;             PG8_WAIT_V(8); PG8_WAIT_L(0); PG8_BAR; PG8_MMA(0, 0, At, B0); PG8_MMA(0, 1, At, B1); PG8_BAR; PG8_SCHED;
;             PG8_LDA(At, 0, 1); PG8_STAGE(PG8_SB(0, 0), b2, voffB); PG8_STAGE(PG8_SB(0, 1), b2 + hstep, voffB); PG8_STAGE(PG8_SA(0, 0), a2, voffA);
;             PG8_WAIT_V(8); PG8_WAIT_L(0); PG8_BAR; PG8_MMA(1, 0, At, B0); PG8_MMA(1, 1, At, B1); PG8_BAR; PG8_SCHED;
;             PG8_LDB(B0, 1, 0); PG8_LDB(B1, 1, 1); PG8_SCHED; PG8_LDA(At, 1, 0); PG8_STAGE(PG8_SA(0, 1), a2 + hstep, voffA);
;             PG8_WAIT_V(8); PG8_WAIT_L(0); PG8_BAR; PG8_MMA(0, 0, At, B0); PG8_MMA(0, 1, At, B1); PG8_BAR; PG8_SCHED;
;             PG8_LDA(At, 1, 1); PG8_STAGE(PG8_SB(1, 0), b3, voffB); PG8_STAGE(PG8_SB(1, 1), b3 + hstep, voffB); PG8_STAGE(PG8_SA(1, 0), a3, voffA);
;             PG8_WAIT_V(8); PG8_WAIT_L(0); PG8_BAR; PG8_MMA(1, 0, At, B0); PG8_MMA(1, 1, At, B1); PG8_BAR; PG8_SCHED;
;             } else {
;             PG8_LDB(B0, 0, 0); PG8_SCHED; PG8_LDA(At, 0, 0); PG8_STAGE(PG8_SA(1, 1), a1 + hstep, voffA);
;             PG8_WAIT_L(8); PG8_BAR; PG8_WAIT_L(0); PG8_MMA(0, 0, At, B0); PG8_BAR; PG8_SCHED;
;             PG8_LDB(B1, 0, 1); PG8_STAGE(PG8_SB(0, 0), b2, voffB);
;             PG8_BAR; PG8_WAIT_L(0); PG8_MMA(0, 1, At, B1); PG8_BAR;
;             PG8_LDA(At, 0, 1); PG8_STAGE(PG8_SA(0, 0), a2, voffA);
;             PG8_BAR; PG8_WAIT_L(0); PG8_MMA(1, 0, At, B0); PG8_BAR; PG8_SCHED;
;             PG8_STAGE(PG8_SB(0, 1), b2 + hstep, voffB);
;             PG8_WAIT_V(6); PG8_BAR; PG8_MMA(1, 1, At, B1); PG8_BAR;
	s_add_i32 s18, s52, s28
	v_lshl_add_u64 v[156:157], v[156:157], 0, s[94:95]
	s_mov_b32 m0, s18
	ds_read_b128 v[184:187], v146 offset:49152
	ds_read_b128 v[188:191], v146 offset:50176
	ds_read_b128 v[192:195], v146 offset:51200
	ds_read_b128 v[196:199], v146 offset:52224
	ds_read_b128 v[200:203], v146 offset:53248
	ds_read_b128 v[206:209], v146 offset:54272
	ds_read_b128 v[214:217], v146 offset:55296
	ds_read_b128 v[218:221], v146 offset:56320
	global_load_lds_dwordx4 v[156:157], off
	s_add_i32 m0, s18, 0x2000
	s_add_u32 s16, s16, 0xb0080
	v_lshl_add_u64 v[156:157], v[210:211], 0, s[94:95]
	s_addc_u32 s17, s17, 0
	s_add_i32 s18, s53, s28
	global_load_lds_dwordx4 v[156:157], off
	v_lshl_add_u64 v[156:157], s[16:17], 0, v[64:65]
	s_mov_b32 m0, s18
	s_nop 0
	global_load_lds_dwordx4 v[156:157], off
	v_lshl_add_u64 v[156:157], s[16:17], 0, v[130:131]
	s_add_i32 m0, s18, 0x2000
	s_nop 0
	global_load_lds_dwordx4 v[156:157], off
	v_lshl_add_u64 v[156:157], v[222:223], 0, s[94:95]
	s_mov_b32 m0, s42
	s_nop 0
	global_load_lds_dwordx4 v[156:157], off
	v_lshl_add_u64 v[156:157], v[224:225], 0, s[94:95]
	s_mov_b32 m0, s44
	s_nop 0
	global_load_lds_dwordx4 v[156:157], off
	s_waitcnt vmcnt(8)
	s_waitcnt lgkmcnt(0)
	s_barrier
	s_setprio 1
	v_mfma_f32_16x16x32_bf16 v[82:85], v[148:151], v[184:187], v[82:85]
	v_mfma_f32_16x16x32_bf16 v[86:89], v[160:163], v[184:187], v[86:89]
	v_mfma_f32_16x16x32_bf16 v[90:93], v[148:151], v[192:195], v[90:93]
	v_mfma_f32_16x16x32_bf16 v[94:97], v[160:163], v[192:195], v[94:97]
	v_mfma_f32_16x16x32_bf16 v[114:117], v[148:151], v[200:203], v[114:117]
	v_mfma_f32_16x16x32_bf16 v[118:121], v[160:163], v[200:203], v[118:121]
	v_mfma_f32_16x16x32_bf16 v[122:125], v[148:151], v[214:217], v[122:125]
	v_mfma_f32_16x16x32_bf16 v[126:129], v[160:163], v[214:217], v[126:129]
	v_mfma_f32_16x16x32_bf16 v[82:85], v[152:155], v[188:191], v[82:85]
	v_mfma_f32_16x16x32_bf16 v[86:89], v[164:167], v[188:191], v[86:89]
	v_mfma_f32_16x16x32_bf16 v[90:93], v[152:155], v[196:199], v[90:93]
	v_mfma_f32_16x16x32_bf16 v[94:97], v[164:167], v[196:199], v[94:97]
	v_mfma_f32_16x16x32_bf16 v[114:117], v[152:155], v[206:209], v[114:117]
	v_mfma_f32_16x16x32_bf16 v[118:121], v[164:167], v[206:209], v[118:121]
	v_mfma_f32_16x16x32_bf16 v[122:125], v[152:155], v[218:221], v[122:125]
	v_mfma_f32_16x16x32_bf16 v[126:129], v[164:167], v[218:221], v[126:129]
	v_mfma_f32_16x16x32_bf16 v[28:31], v[168:171], v[184:187], v[28:31]
	v_mfma_f32_16x16x32_bf16 v[24:27], v[176:179], v[184:187], v[24:27]
	v_mfma_f32_16x16x32_bf16 v[20:23], v[168:171], v[192:195], v[20:23]
	v_mfma_f32_16x16x32_bf16 v[16:19], v[176:179], v[192:195], v[16:19]
	v_mfma_f32_16x16x32_bf16 v[12:15], v[168:171], v[200:203], v[12:15]
	v_mfma_f32_16x16x32_bf16 v[8:11], v[176:179], v[200:203], v[8:11]
	v_mfma_f32_16x16x32_bf16 v[4:7], v[168:171], v[214:217], v[4:7]
	v_mfma_f32_16x16x32_bf16 v[0:3], v[176:179], v[214:217], v[0:3]
	v_mfma_f32_16x16x32_bf16 v[28:31], v[172:175], v[188:191], v[28:31]
	v_mfma_f32_16x16x32_bf16 v[24:27], v[180:183], v[188:191], v[24:27]
	v_mfma_f32_16x16x32_bf16 v[20:23], v[172:175], v[196:199], v[20:23]
	v_mfma_f32_16x16x32_bf16 v[16:19], v[180:183], v[196:199], v[16:19]
	v_mfma_f32_16x16x32_bf16 v[12:15], v[172:175], v[206:209], v[12:15]
	v_mfma_f32_16x16x32_bf16 v[8:11], v[180:183], v[206:209], v[8:11]
	v_mfma_f32_16x16x32_bf16 v[4:7], v[172:175], v[218:221], v[4:7]
	v_mfma_f32_16x16x32_bf16 v[0:3], v[180:183], v[218:221], v[0:3]
	s_setprio 0
	s_barrier
	s_add_i32 s51, s51, 2
	s_add_u32 s14, s14, 0x100
	s_addc_u32 s15, s15, 0
	s_cmp_gt_u32 s51, 41
	s_cbranch_scc0 .LBB0_137
	s_add_u32 s14, s49, 0xffffff00
	s_addc_u32 s15, s50, -1
	s_and_b64 vcc, exec, s[2:3]
	s_cbranch_vccnz .LBB0_140
	v_mov_b32_e32 v0, 0
	s_mov_b32 s8, s46
	s_mov_b32 s22, s47
	s_mov_b64 s[10:11], s[12:13]
	s_mov_b32 s45, s48
	v_mov_b32_e32 v1, v0
	v_mov_b32_e32 v2, v0
	v_mov_b32_e32 v3, v0
	v_mov_b32_e32 v4, v0
	v_mov_b32_e32 v5, v0
	v_mov_b32_e32 v6, v0
	v_mov_b32_e32 v7, v0
	v_mov_b32_e32 v8, v0
	v_mov_b32_e32 v9, v0
	v_mov_b32_e32 v10, v0
	v_mov_b32_e32 v11, v0
	v_mov_b32_e32 v12, v0
	v_mov_b32_e32 v13, v0
	v_mov_b32_e32 v14, v0
	v_mov_b32_e32 v15, v0
	v_mov_b32_e32 v16, v0
	v_mov_b32_e32 v17, v0
	v_mov_b32_e32 v18, v0
	v_mov_b32_e32 v19, v0
	v_mov_b32_e32 v20, v0
	v_mov_b32_e32 v21, v0
	v_mov_b32_e32 v22, v0
	v_mov_b32_e32 v23, v0
	v_mov_b32_e32 v24, v0
	v_mov_b32_e32 v25, v0
	v_mov_b32_e32 v26, v0
	v_mov_b32_e32 v27, v0
	v_mov_b32_e32 v28, v0
	v_mov_b32_e32 v29, v0
	v_mov_b32_e32 v30, v0
	v_mov_b32_e32 v31, v0
	v_mov_b32_e32 v126, v0
	v_mov_b32_e32 v127, v0
	v_mov_b32_e32 v128, v0
	v_mov_b32_e32 v129, v0
	v_mov_b32_e32 v122, v0
	v_mov_b32_e32 v123, v0
	v_mov_b32_e32 v124, v0
	v_mov_b32_e32 v125, v0
	v_mov_b32_e32 v118, v0
	v_mov_b32_e32 v119, v0
	v_mov_b32_e32 v120, v0
	v_mov_b32_e32 v121, v0
	v_mov_b32_e32 v114, v0
	v_mov_b32_e32 v115, v0
	v_mov_b32_e32 v116, v0
	v_mov_b32_e32 v117, v0
	v_mov_b32_e32 v94, v0
	v_mov_b32_e32 v95, v0
	v_mov_b32_e32 v96, v0
	v_mov_b32_e32 v97, v0
	v_mov_b32_e32 v90, v0
	v_mov_b32_e32 v91, v0
	v_mov_b32_e32 v92, v0
	v_mov_b32_e32 v93, v0
	v_mov_b32_e32 v86, v0
	v_mov_b32_e32 v87, v0
	v_mov_b32_e32 v88, v0
	v_mov_b32_e32 v89, v0
	v_mov_b32_e32 v82, v0
	v_mov_b32_e32 v83, v0
	v_mov_b32_e32 v84, v0
	v_mov_b32_e32 v85, v0
	v_mov_b32_e32 v40, v0
	v_mov_b32_e32 v41, v0
	v_mov_b32_e32 v42, v0
	v_mov_b32_e32 v43, v0
	v_mov_b32_e32 v44, v0
	v_mov_b32_e32 v45, v0
	v_mov_b32_e32 v46, v0
	v_mov_b32_e32 v47, v0
	v_mov_b32_e32 v66, v0
	v_mov_b32_e32 v67, v0
	v_mov_b32_e32 v68, v0
	v_mov_b32_e32 v69, v0
	v_mov_b32_e32 v70, v0
	v_mov_b32_e32 v71, v0
	v_mov_b32_e32 v72, v0
	v_mov_b32_e32 v73, v0
	v_mov_b32_e32 v98, v0
	v_mov_b32_e32 v99, v0
	v_mov_b32_e32 v100, v0
	v_mov_b32_e32 v101, v0
	v_mov_b32_e32 v102, v0
	v_mov_b32_e32 v103, v0
	v_mov_b32_e32 v104, v0
	v_mov_b32_e32 v105, v0
	v_mov_b32_e32 v110, v0
	v_mov_b32_e32 v111, v0
	v_mov_b32_e32 v112, v0
	v_mov_b32_e32 v113, v0
	v_mov_b32_e32 v106, v0
	v_mov_b32_e32 v107, v0
	v_mov_b32_e32 v108, v0
	v_mov_b32_e32 v109, v0
	v_mov_b32_e32 v78, v0
	v_mov_b32_e32 v79, v0
	v_mov_b32_e32 v80, v0
	v_mov_b32_e32 v81, v0
	v_mov_b32_e32 v74, v0
	v_mov_b32_e32 v75, v0
	v_mov_b32_e32 v76, v0
	v_mov_b32_e32 v77, v0
	v_mov_b32_e32 v60, v0
	v_mov_b32_e32 v61, v0
	v_mov_b32_e32 v62, v0
	v_mov_b32_e32 v63, v0
	v_mov_b32_e32 v56, v0
	v_mov_b32_e32 v57, v0
	v_mov_b32_e32 v58, v0
	v_mov_b32_e32 v59, v0
	v_mov_b32_e32 v52, v0
	v_mov_b32_e32 v53, v0
	v_mov_b32_e32 v54, v0
	v_mov_b32_e32 v55, v0
	v_mov_b32_e32 v48, v0
	v_mov_b32_e32 v49, v0
	v_mov_b32_e32 v50, v0
	v_mov_b32_e32 v51, v0
	v_mov_b32_e32 v36, v0
	v_mov_b32_e32 v37, v0
	v_mov_b32_e32 v38, v0
	v_mov_b32_e32 v39, v0
	v_mov_b32_e32 v32, v0
	v_mov_b32_e32 v33, v0
	v_mov_b32_e32 v34, v0
	v_mov_b32_e32 v35, v0
	s_andn2_b64 vcc, exec, s[0:1]
	s_cbranch_vccnz .LBB0_141
	s_branch .LBB0_142

; #define PG8_STAGE(bufoff, gbase, voff) do { _Pragma("unroll") for (int _i = 0; _i < 2; ++_i) \
;         __builtin_amdgcn_global_load_lds((const unsigned*)((const char*)(gbase) + (voff)[_i]), (PG8_LAS unsigned*)(lds + (bufoff) + ldsw + _i * 8192), 16, 0, 0); } while (0)
; #define PG8_LDA(dst, b, h) do { _Pragma("unroll") for (int m = 0; m < 4; ++m) _Pragma("unroll") for (int k = 0; k < 2; ++k) dst[m][k] = *(const PG8_LAS bf16x8*)(lds + PG8_SA(b, h) + aoff + m * 2048 + k * 1024); } while (0)
; #define PG8_LDB(dst, b, h) do { _Pragma("unroll") for (int n = 0; n < 2; ++n) _Pragma("unroll") for (int k = 0; k < 2; ++k) dst[n][k] = *(const PG8_LAS bf16x8*)(lds + PG8_SB(b, h) + boff + n * 2048 + k * 1024); } while (0)
; #define PG8_MMA(ai, bj, At, Bt) do { __builtin_amdgcn_s_setprio(1); _Pragma("unroll") for (int m = 0; m < 4; ++m) _Pragma("unroll") for (int n = 0; n < 2; ++n) _Pragma("unroll") for (int k = 0; k < 2; ++k) \
;         acc[ai][bj][m][n] = __builtin_amdgcn_mfma_f32_16x16x32_bf16(Bt[n][k], At[m][k], acc[ai][bj][m][n], 0, 0, 0); __builtin_amdgcn_s_setprio(0); } while (0)
; #define PG8_WAIT_V(n) asm volatile("s_waitcnt vmcnt(" #n ")" ::: "memory")
; #define PG8_WAIT_L(n) asm volatile("s_waitcnt lgkmcnt(" #n ")" ::: "memory")
; template <class Epi, class Sched, bool ALIGN_EPI = false, bool SP2 = false>
; __device__ __forceinline__ void gemm_phase(PG8_LAS unsigned char* lds, const Gemm g, const Sched& S, const Epi& E, const int tid) {
;     ...
;             const bool last = (t == nt - 2);
;             const char* a1 = cA + (size_t)(t + 1) * kstep;
;             const char* a2 = last ? nA : cA + (size_t)(t + 2) * kstep; const char* b2 = last ? nB : cB + (size_t)(t + 2) * kstep;
;             const char* a3 = a2 + kstep; const char* b3 = b2 + kstep;
;             if (last && has_next) S.a_ready(nxt);
;             if constexpr (SP2) {
;             PG8_LDB(B0, 0, 0); PG8_LDB(B1, 0, 1); PG8_SCHED; PG8_LDA(At, 0, 0); PG8_STAGE(PG8_SA(1, 1), a1 + hstep, voffA);
;             PG8_WAIT_V(8); PG8_WAIT_L(0); PG8_BAR; PG8_MMA(0, 0, At, B0); PG8_MMA(0, 1, At, B1); PG8_BAR; PG8_SCHED;
;             PG8_LDA(At, 0, 1); PG8_STAGE(PG8_SB(0, 0), b2, voffB); PG8_STAGE(PG8_SB(0, 1), b2 + hstep, voffB); PG8_STAGE(PG8_SA(0, 0), a2, voffA);
;             PG8_WAIT_V(8); PG8_WAIT_L(0); PG8_BAR; PG8_MMA(1, 0, At, B0); PG8_MMA(1, 1, At, B1); PG8_BAR; PG8_SCHED;
.LBB0_254:
	s_add_u32 s18, s16, 0xfffc0080
	s_addc_u32 s19, s17, -1
	s_add_i32 s48, 0, 0x10000
	s_cmp_eq_u32 s47, 12
	s_cselect_b32 s21, s11, s19
	s_cselect_b32 s20, s42, s18
	v_add_u32_e32 v64, s48, v143
	s_cselect_b32 s19, s9, s46
	s_cselect_b32 s18, s44, s45
	s_add_i32 s50, 0, 0x14000
	ds_read_b128 v[146:149], v64
	ds_read_b128 v[150:153], v64 offset:1024
	ds_read_b128 v[154:157], v64 offset:2048
	ds_read_b128 v[158:161], v64 offset:3072
	v_add_u32_e32 v64, s50, v143
	ds_read_b128 v[162:165], v64
	ds_read_b128 v[166:169], v64 offset:1024
	ds_read_b128 v[170:173], v64 offset:2048
	ds_read_b128 v[174:177], v64 offset:3072
	v_lshl_add_u64 v[202:203], s[16:17], 0, v[140:141]
	s_add_i32 m0, s25, 0xc000
	ds_read_b128 v[178:181], v145
	ds_read_b128 v[182:185], v145 offset:1024
	ds_read_b128 v[186:189], v145 offset:2048
	ds_read_b128 v[190:193], v145 offset:3072
	ds_read_b128 v[194:197], v145 offset:4096
	ds_read_b128 v[198:201], v145 offset:5120
	ds_read_b128 v[206:209], v145 offset:6144
	ds_read_b128 v[214:217], v145 offset:7168
	global_load_lds_dwordx4 v[202:203], off
	v_lshl_add_u64 v[202:203], s[16:17], 0, v[138:139]
	s_add_i32 m0, s25, 0xe000
	s_nop 0
	global_load_lds_dwordx4 v[202:203], off
	s_waitcnt vmcnt(8)
	s_waitcnt lgkmcnt(0)
	s_barrier
	s_setprio 1
	v_mfma_f32_16x16x32_bf16 v[126:129], v[146:149], v[178:181], v[126:129]
	v_mfma_f32_16x16x32_bf16 v[122:125], v[154:157], v[178:181], v[122:125]
	v_mfma_f32_16x16x32_bf16 v[110:113], v[146:149], v[186:189], v[110:113]
	v_mfma_f32_16x16x32_bf16 v[106:109], v[154:157], v[186:189], v[106:109]
	v_mfma_f32_16x16x32_bf16 v[94:97], v[146:149], v[194:197], v[94:97]
	v_mfma_f32_16x16x32_bf16 v[90:93], v[154:157], v[194:197], v[90:93]
	v_mfma_f32_16x16x32_bf16 v[78:81], v[146:149], v[206:209], v[78:81]
	v_mfma_f32_16x16x32_bf16 v[74:77], v[154:157], v[206:209], v[74:77]
	v_mfma_f32_16x16x32_bf16 v[126:129], v[150:153], v[182:185], v[126:129]
	v_mfma_f32_16x16x32_bf16 v[122:125], v[158:161], v[182:185], v[122:125]
	v_mfma_f32_16x16x32_bf16 v[110:113], v[150:153], v[190:193], v[110:113]
	v_mfma_f32_16x16x32_bf16 v[106:109], v[158:161], v[190:193], v[106:109]
	v_mfma_f32_16x16x32_bf16 v[94:97], v[150:153], v[198:201], v[94:97]
	v_mfma_f32_16x16x32_bf16 v[90:93], v[158:161], v[198:201], v[90:93]
	v_mfma_f32_16x16x32_bf16 v[78:81], v[150:153], v[214:217], v[78:81]
	v_mfma_f32_16x16x32_bf16 v[74:77], v[158:161], v[214:217], v[74:77]
	v_mfma_f32_16x16x32_bf16 v[118:121], v[162:165], v[178:181], v[118:121]
	v_mfma_f32_16x16x32_bf16 v[114:117], v[170:173], v[178:181], v[114:117]
	v_mfma_f32_16x16x32_bf16 v[102:105], v[162:165], v[186:189], v[102:105]
	v_mfma_f32_16x16x32_bf16 v[98:101], v[170:173], v[186:189], v[98:101]
	v_mfma_f32_16x16x32_bf16 v[86:89], v[162:165], v[194:197], v[86:89]
	v_mfma_f32_16x16x32_bf16 v[82:85], v[170:173], v[194:197], v[82:85]
	v_mfma_f32_16x16x32_bf16 v[70:73], v[162:165], v[206:209], v[70:73]
	v_mfma_f32_16x16x32_bf16 v[66:69], v[170:173], v[206:209], v[66:69]
	v_mfma_f32_16x16x32_bf16 v[118:121], v[166:169], v[182:185], v[118:121]
	v_mfma_f32_16x16x32_bf16 v[114:117], v[174:177], v[182:185], v[114:117]
	v_mfma_f32_16x16x32_bf16 v[102:105], v[166:169], v[190:193], v[102:105]
	v_mfma_f32_16x16x32_bf16 v[98:101], v[174:177], v[190:193], v[98:101]
	v_mfma_f32_16x16x32_bf16 v[86:89], v[166:169], v[198:201], v[86:89]
	v_mfma_f32_16x16x32_bf16 v[82:85], v[174:177], v[198:201], v[82:85]
	v_mfma_f32_16x16x32_bf16 v[70:73], v[166:169], v[214:217], v[70:73]
	v_mfma_f32_16x16x32_bf16 v[66:69], v[174:177], v[214:217], v[66:69]
	s_setprio 0
	s_barrier
	s_add_i32 s48, s48, s24
	v_lshl_add_u64 v[202:203], s[18:19], 0, v[134:135]
	s_mov_b32 m0, s48
	ds_read_b128 v[178:181], v145 offset:16384
	ds_read_b128 v[182:185], v145 offset:17408
	ds_read_b128 v[186:189], v145 offset:18432
	ds_read_b128 v[190:193], v145 offset:19456
	ds_read_b128 v[194:197], v145 offset:20480
	ds_read_b128 v[198:201], v145 offset:21504
	ds_read_b128 v[206:209], v145 offset:22528
	ds_read_b128 v[214:217], v145 offset:23552
	global_load_lds_dwordx4 v[202:203], off
	s_add_i32 m0, s48, 0x2000
	s_add_u32 s48, s18, 0x40000
	v_lshl_add_u64 v[210:211], s[18:19], 0, v[130:131]
	s_addc_u32 s49, s19, 0
	s_add_i32 s50, s50, s24
	global_load_lds_dwordx4 v[210:211], off
	v_lshl_add_u64 v[218:219], s[48:49], 0, v[134:135]
	s_mov_b32 m0, s50
	v_lshl_add_u64 v[220:221], s[20:21], 0, v[132:133]
	global_load_lds_dwordx4 v[218:219], off
	v_lshl_add_u64 v[218:219], s[48:49], 0, v[130:131]
	s_add_i32 m0, s50, 0x2000
	s_nop 0
	global_load_lds_dwordx4 v[218:219], off
	v_lshl_add_u64 v[218:219], s[20:21], 0, v[136:137]
	s_mov_b32 m0, s25
	s_nop 0
	global_load_lds_dwordx4 v[218:219], off
	s_mov_b32 m0, s26
	s_nop 0
	global_load_lds_dwordx4 v[220:221], off
	s_waitcnt vmcnt(8)
	s_waitcnt lgkmcnt(0)
	s_barrier
; #define PG8_STAGE(bufoff, gbase, voff) do { _Pragma("unroll") for (int _i = 0; _i < 2; ++_i) \
;         __builtin_amdgcn_global_load_lds((const unsigned*)((const char*)(gbase) + (voff)[_i]), (PG8_LAS unsigned*)(lds + (bufoff) + ldsw + _i * 8192), 16, 0, 0); } while (0)
; #define PG8_LDA(dst, b, h) do { _Pragma("unroll") for (int m = 0; m < 4; ++m) _Pragma("unroll") for (int k = 0; k < 2; ++k) dst[m][k] = *(const PG8_LAS bf16x8*)(lds + PG8_SA(b, h) + aoff + m * 2048 + k * 1024); } while (0)
; #define PG8_LDB(dst, b, h) do { _Pragma("unroll") for (int n = 0; n < 2; ++n) _Pragma("unroll") for (int k = 0; k < 2; ++k) dst[n][k] = *(const PG8_LAS bf16x8*)(lds + PG8_SB(b, h) + boff + n * 2048 + k * 1024); } while (0)
; #define PG8_MMA(ai, bj, At, Bt) do { __builtin_amdgcn_s_setprio(1); _Pragma("unroll") for (int m = 0; m < 4; ++m) _Pragma("unroll") for (int n = 0; n < 2; ++n) _Pragma("unroll") for (int k = 0; k < 2; ++k) \
;         acc[ai][bj][m][n] = __builtin_amdgcn_mfma_f32_16x16x32_bf16(Bt[n][k], At[m][k], acc[ai][bj][m][n], 0, 0, 0); __builtin_amdgcn_s_setprio(0); } while (0)
; #define PG8_WAIT_V(n) asm volatile("s_waitcnt vmcnt(" #n ")" ::: "memory")
; #define PG8_WAIT_L(n) asm volatile("s_waitcnt lgkmcnt(" #n ")" ::: "memory")
; #define PG8_BAR __builtin_amdgcn_s_barrier()
; #define PG8_SCHED __builtin_amdgcn_sched_barrier(0)
; template <class Epi, class Sched, bool ALIGN_EPI = false, bool SP2 = false>
; __device__ __forceinline__ void gemm_phase(PG8_LAS unsigned char* lds, const Gemm g, const Sched& S, const Epi& E, const int tid) {
;     ...
;             PG8_WAIT_V(8); PG8_WAIT_L(0); PG8_BAR; PG8_MMA(1, 0, At, B0); PG8_MMA(1, 1, At, B1); PG8_BAR; PG8_SCHED;
;             PG8_LDB(B0, 1, 0); PG8_LDB(B1, 1, 1); PG8_SCHED; PG8_LDA(At, 1, 0); PG8_STAGE(PG8_SA(0, 1), a2 + hstep, voffA);
;             PG8_WAIT_V(8); PG8_WAIT_L(0); PG8_BAR; PG8_MMA(0, 0, At, B0); PG8_MMA(0, 1, At, B1); PG8_BAR; PG8_SCHED;
	s_setprio 1
	v_mfma_f32_16x16x32_bf16 v[60:63], v[146:149], v[178:181], v[60:63]
	v_mfma_f32_16x16x32_bf16 v[56:59], v[154:157], v[178:181], v[56:59]
	v_mfma_f32_16x16x32_bf16 v[44:47], v[146:149], v[186:189], v[44:47]
	v_mfma_f32_16x16x32_bf16 v[40:43], v[154:157], v[186:189], v[40:43]
	v_mfma_f32_16x16x32_bf16 v[28:31], v[146:149], v[194:197], v[28:31]
	v_mfma_f32_16x16x32_bf16 v[24:27], v[154:157], v[194:197], v[24:27]
	v_mfma_f32_16x16x32_bf16 v[12:15], v[146:149], v[206:209], v[12:15]
	v_mfma_f32_16x16x32_bf16 v[8:11], v[154:157], v[206:209], v[8:11]
	v_mfma_f32_16x16x32_bf16 v[60:63], v[150:153], v[182:185], v[60:63]
	v_mfma_f32_16x16x32_bf16 v[56:59], v[158:161], v[182:185], v[56:59]
	v_mfma_f32_16x16x32_bf16 v[44:47], v[150:153], v[190:193], v[44:47]
	v_mfma_f32_16x16x32_bf16 v[40:43], v[158:161], v[190:193], v[40:43]
	v_mfma_f32_16x16x32_bf16 v[28:31], v[150:153], v[198:201], v[28:31]
	v_mfma_f32_16x16x32_bf16 v[24:27], v[158:161], v[198:201], v[24:27]
	v_mfma_f32_16x16x32_bf16 v[12:15], v[150:153], v[214:217], v[12:15]
	v_mfma_f32_16x16x32_bf16 v[8:11], v[158:161], v[214:217], v[8:11]
	v_mfma_f32_16x16x32_bf16 v[52:55], v[162:165], v[178:181], v[52:55]
	v_mfma_f32_16x16x32_bf16 v[48:51], v[170:173], v[178:181], v[48:51]
	v_mfma_f32_16x16x32_bf16 v[36:39], v[162:165], v[186:189], v[36:39]
	v_mfma_f32_16x16x32_bf16 v[32:35], v[170:173], v[186:189], v[32:35]
	v_mfma_f32_16x16x32_bf16 v[20:23], v[162:165], v[194:197], v[20:23]
	v_mfma_f32_16x16x32_bf16 v[16:19], v[170:173], v[194:197], v[16:19]
	v_mfma_f32_16x16x32_bf16 v[4:7], v[162:165], v[206:209], v[4:7]
	v_mfma_f32_16x16x32_bf16 v[0:3], v[170:173], v[206:209], v[0:3]
	v_mfma_f32_16x16x32_bf16 v[52:55], v[166:169], v[182:185], v[52:55]
	v_mfma_f32_16x16x32_bf16 v[48:51], v[174:177], v[182:185], v[48:51]
	v_mfma_f32_16x16x32_bf16 v[36:39], v[166:169], v[190:193], v[36:39]
	v_mfma_f32_16x16x32_bf16 v[32:35], v[174:177], v[190:193], v[32:35]
	v_mfma_f32_16x16x32_bf16 v[20:23], v[166:169], v[198:201], v[20:23]
	v_mfma_f32_16x16x32_bf16 v[16:19], v[174:177], v[198:201], v[16:19]
	v_mfma_f32_16x16x32_bf16 v[4:7], v[166:169], v[214:217], v[4:7]
	v_mfma_f32_16x16x32_bf16 v[0:3], v[174:177], v[214:217], v[0:3]
	s_setprio 0
	s_barrier
	s_add_i32 s48, 0, 0x18000
	v_add_u32_e32 v64, s48, v143
	s_add_i32 s49, 0, 0x1c000
	ds_read_b128 v[146:149], v64
	ds_read_b128 v[150:153], v64 offset:1024
	ds_read_b128 v[154:157], v64 offset:2048
	ds_read_b128 v[158:161], v64 offset:3072
	v_add_u32_e32 v64, s49, v143
	ds_read_b128 v[162:165], v64
	ds_read_b128 v[166:169], v64 offset:1024
	ds_read_b128 v[170:173], v64 offset:2048
	ds_read_b128 v[174:177], v64 offset:3072
	s_add_u32 s20, s20, 0x40000
	s_addc_u32 s21, s21, 0
	s_mov_b32 m0, s27
	v_lshl_add_u64 v[222:223], s[20:21], 0, v[136:137]
	ds_read_b128 v[178:181], v145 offset:32768
	ds_read_b128 v[182:185], v145 offset:33792
	ds_read_b128 v[186:189], v145 offset:34816
	ds_read_b128 v[190:193], v145 offset:35840
	ds_read_b128 v[194:197], v145 offset:36864
	ds_read_b128 v[198:201], v145 offset:37888
	ds_read_b128 v[206:209], v145 offset:38912
	ds_read_b128 v[214:217], v145 offset:39936
	global_load_lds_dwordx4 v[222:223], off
	v_lshl_add_u64 v[222:223], s[20:21], 0, v[132:133]
	s_mov_b32 m0, s28
	s_nop 0
	global_load_lds_dwordx4 v[222:223], off
	s_waitcnt vmcnt(8)
	s_waitcnt lgkmcnt(0)
	s_barrier
	s_setprio 1
	v_mfma_f32_16x16x32_bf16 v[126:129], v[146:149], v[178:181], v[126:129]
	v_mfma_f32_16x16x32_bf16 v[122:125], v[154:157], v[178:181], v[122:125]
	v_mfma_f32_16x16x32_bf16 v[110:113], v[146:149], v[186:189], v[110:113]
	v_mfma_f32_16x16x32_bf16 v[106:109], v[154:157], v[186:189], v[106:109]
	v_mfma_f32_16x16x32_bf16 v[94:97], v[146:149], v[194:197], v[94:97]
	v_mfma_f32_16x16x32_bf16 v[90:93], v[154:157], v[194:197], v[90:93]
	v_mfma_f32_16x16x32_bf16 v[78:81], v[146:149], v[206:209], v[78:81]
	v_mfma_f32_16x16x32_bf16 v[74:77], v[154:157], v[206:209], v[74:77]
	v_mfma_f32_16x16x32_bf16 v[126:129], v[150:153], v[182:185], v[126:129]
	v_mfma_f32_16x16x32_bf16 v[122:125], v[158:161], v[182:185], v[122:125]
	v_mfma_f32_16x16x32_bf16 v[110:113], v[150:153], v[190:193], v[110:113]
	v_mfma_f32_16x16x32_bf16 v[106:109], v[158:161], v[190:193], v[106:109]
	v_mfma_f32_16x16x32_bf16 v[94:97], v[150:153], v[198:201], v[94:97]
	v_mfma_f32_16x16x32_bf16 v[90:93], v[158:161], v[198:201], v[90:93]
	v_mfma_f32_16x16x32_bf16 v[78:81], v[150:153], v[214:217], v[78:81]
	v_mfma_f32_16x16x32_bf16 v[74:77], v[158:161], v[214:217], v[74:77]
	v_mfma_f32_16x16x32_bf16 v[118:121], v[162:165], v[178:181], v[118:121]
	v_mfma_f32_16x16x32_bf16 v[114:117], v[170:173], v[178:181], v[114:117]
	v_mfma_f32_16x16x32_bf16 v[102:105], v[162:165], v[186:189], v[102:105]
	v_mfma_f32_16x16x32_bf16 v[98:101], v[170:173], v[186:189], v[98:101]
	v_mfma_f32_16x16x32_bf16 v[86:89], v[162:165], v[194:197], v[86:89]
	v_mfma_f32_16x16x32_bf16 v[82:85], v[170:173], v[194:197], v[82:85]
	v_mfma_f32_16x16x32_bf16 v[70:73], v[162:165], v[206:209], v[70:73]
	v_mfma_f32_16x16x32_bf16 v[66:69], v[170:173], v[206:209], v[66:69]
	v_mfma_f32_16x16x32_bf16 v[118:121], v[166:169], v[182:185], v[118:121]
	v_mfma_f32_16x16x32_bf16 v[114:117], v[174:177], v[182:185], v[114:117]
	v_mfma_f32_16x16x32_bf16 v[102:105], v[166:169], v[190:193], v[102:105]
	v_mfma_f32_16x16x32_bf16 v[98:101], v[174:177], v[190:193], v[98:101]
	v_mfma_f32_16x16x32_bf16 v[86:89], v[166:169], v[198:201], v[86:89]
	v_mfma_f32_16x16x32_bf16 v[82:85], v[174:177], v[198:201], v[82:85]
	v_mfma_f32_16x16x32_bf16 v[70:73], v[166:169], v[214:217], v[70:73]
	v_mfma_f32_16x16x32_bf16 v[66:69], v[174:177], v[214:217], v[66:69]
	s_setprio 0
	s_barrier
; #define PG8_STAGE(bufoff, gbase, voff) do { _Pragma("unroll") for (int _i = 0; _i < 2; ++_i) \
;         __builtin_amdgcn_global_load_lds((const unsigned*)((const char*)(gbase) + (voff)[_i]), (PG8_LAS unsigned*)(lds + (bufoff) + ldsw + _i * 8192), 16, 0, 0); } while (0)
; #define PG8_LDA(dst, b, h) do { _Pragma("unroll") for (int m = 0; m < 4; ++m) _Pragma("unroll") for (int k = 0; k < 2; ++k) dst[m][k] = *(const PG8_LAS bf16x8*)(lds + PG8_SA(b, h) + aoff + m * 2048 + k * 1024); } while (0)
; #define PG8_WAIT_V(n) asm volatile("s_waitcnt vmcnt(" #n ")" ::: "memory")
; #define PG8_WAIT_L(n) asm volatile("s_waitcnt lgkmcnt(" #n ")" ::: "memory")
; template <class Epi, class Sched, bool ALIGN_EPI = false, bool SP2 = false>
; __device__ __forceinline__ void gemm_phase(PG8_LAS unsigned char* lds, const Gemm g, const Sched& S, const Epi& E, const int tid) {
;     ...
;         for (int t = 0; t < nt; t += 2) {
;             const bool last = (t == nt - 2);
;             const char* a1 = cA + (size_t)(t + 1) * kstep;
;             const char* a2 = last ? nA : cA + (size_t)(t + 2) * kstep; const char* b2 = last ? nB : cB + (size_t)(t + 2) * kstep;
;             const char* a3 = a2 + kstep; const char* b3 = b2 + kstep;
;             if (last && has_next) S.a_ready(nxt);
;             if constexpr (SP2) {
;             PG8_LDB(B0, 0, 0); PG8_LDB(B1, 0, 1); PG8_SCHED; PG8_LDA(At, 0, 0); PG8_STAGE(PG8_SA(1, 1), a1 + hstep, voffA);
;             PG8_WAIT_V(8); PG8_WAIT_L(0); PG8_BAR; PG8_MMA(0, 0, At, B0); PG8_MMA(0, 1, At, B1); PG8_BAR; PG8_SCHED;
;             PG8_LDA(At, 0, 1); PG8_STAGE(PG8_SB(0, 0), b2, voffB); PG8_STAGE(PG8_SB(0, 1), b2 + hstep, voffB); PG8_STAGE(PG8_SA(0, 0), a2, voffA);
;             PG8_WAIT_V(8); PG8_WAIT_L(0); PG8_BAR; PG8_MMA(1, 0, At, B0); PG8_MMA(1, 1, At, B1); PG8_BAR; PG8_SCHED;
;             PG8_LDB(B0, 1, 0); PG8_LDB(B1, 1, 1); PG8_SCHED; PG8_LDA(At, 1, 0); PG8_STAGE(PG8_SA(0, 1), a2 + hstep, voffA);
;             PG8_WAIT_V(8); PG8_WAIT_L(0); PG8_BAR; PG8_MMA(0, 0, At, B0); PG8_MMA(0, 1, At, B1); PG8_BAR; PG8_SCHED;
;             PG8_LDA(At, 1, 1); PG8_STAGE(PG8_SB(1, 0), b3, voffB); PG8_STAGE(PG8_SB(1, 1), b3 + hstep, voffB); PG8_STAGE(PG8_SA(1, 0), a3, voffA);
;             PG8_WAIT_V(8); PG8_WAIT_L(0); PG8_BAR; PG8_MMA(1, 0, At, B0); PG8_MMA(1, 1, At, B1); PG8_BAR; PG8_SCHED;
;     ...
;         if constexpr (ALIGN_EPI) { if (wr == 0) PG8_BAR; }
	s_add_i32 s20, s48, s24
	v_lshl_add_u64 v[202:203], v[202:203], 0, s[94:95]
	s_mov_b32 m0, s20
	ds_read_b128 v[178:181], v145 offset:49152
	ds_read_b128 v[182:185], v145 offset:50176
	ds_read_b128 v[186:189], v145 offset:51200
	ds_read_b128 v[190:193], v145 offset:52224
	ds_read_b128 v[194:197], v145 offset:53248
	ds_read_b128 v[198:201], v145 offset:54272
	ds_read_b128 v[206:209], v145 offset:55296
	ds_read_b128 v[214:217], v145 offset:56320
	global_load_lds_dwordx4 v[202:203], off
	s_add_i32 m0, s20, 0x2000
	s_add_u32 s18, s18, 0x40080
	v_lshl_add_u64 v[202:203], v[210:211], 0, s[94:95]
	s_addc_u32 s19, s19, 0
	s_add_i32 s20, s49, s24
	global_load_lds_dwordx4 v[202:203], off
	v_lshl_add_u64 v[202:203], s[18:19], 0, v[134:135]
	s_mov_b32 m0, s20
	s_nop 0
	global_load_lds_dwordx4 v[202:203], off
	v_lshl_add_u64 v[202:203], s[18:19], 0, v[130:131]
	s_add_i32 m0, s20, 0x2000
	s_nop 0
	global_load_lds_dwordx4 v[202:203], off
	v_lshl_add_u64 v[202:203], v[218:219], 0, s[94:95]
	s_mov_b32 m0, s29
	s_nop 0
	global_load_lds_dwordx4 v[202:203], off
	v_lshl_add_u64 v[202:203], v[220:221], 0, s[94:95]
	s_mov_b32 m0, s30
	s_nop 0
	global_load_lds_dwordx4 v[202:203], off
	s_waitcnt vmcnt(8)
	s_waitcnt lgkmcnt(0)
	s_barrier
	s_setprio 1
	v_mfma_f32_16x16x32_bf16 v[60:63], v[146:149], v[178:181], v[60:63]
	v_mfma_f32_16x16x32_bf16 v[56:59], v[154:157], v[178:181], v[56:59]
	v_mfma_f32_16x16x32_bf16 v[44:47], v[146:149], v[186:189], v[44:47]
	v_mfma_f32_16x16x32_bf16 v[40:43], v[154:157], v[186:189], v[40:43]
	v_mfma_f32_16x16x32_bf16 v[28:31], v[146:149], v[194:197], v[28:31]
	v_mfma_f32_16x16x32_bf16 v[24:27], v[154:157], v[194:197], v[24:27]
	v_mfma_f32_16x16x32_bf16 v[12:15], v[146:149], v[206:209], v[12:15]
	v_mfma_f32_16x16x32_bf16 v[8:11], v[154:157], v[206:209], v[8:11]
	v_mfma_f32_16x16x32_bf16 v[60:63], v[150:153], v[182:185], v[60:63]
	v_mfma_f32_16x16x32_bf16 v[56:59], v[158:161], v[182:185], v[56:59]
	v_mfma_f32_16x16x32_bf16 v[44:47], v[150:153], v[190:193], v[44:47]
	v_mfma_f32_16x16x32_bf16 v[40:43], v[158:161], v[190:193], v[40:43]
	v_mfma_f32_16x16x32_bf16 v[28:31], v[150:153], v[198:201], v[28:31]
	v_mfma_f32_16x16x32_bf16 v[24:27], v[158:161], v[198:201], v[24:27]
	v_mfma_f32_16x16x32_bf16 v[12:15], v[150:153], v[214:217], v[12:15]
	v_mfma_f32_16x16x32_bf16 v[8:11], v[158:161], v[214:217], v[8:11]
	v_mfma_f32_16x16x32_bf16 v[52:55], v[162:165], v[178:181], v[52:55]
	v_mfma_f32_16x16x32_bf16 v[48:51], v[170:173], v[178:181], v[48:51]
	v_mfma_f32_16x16x32_bf16 v[36:39], v[162:165], v[186:189], v[36:39]
	v_mfma_f32_16x16x32_bf16 v[32:35], v[170:173], v[186:189], v[32:35]
	v_mfma_f32_16x16x32_bf16 v[20:23], v[162:165], v[194:197], v[20:23]
	v_mfma_f32_16x16x32_bf16 v[16:19], v[170:173], v[194:197], v[16:19]
	v_mfma_f32_16x16x32_bf16 v[4:7], v[162:165], v[206:209], v[4:7]
	v_mfma_f32_16x16x32_bf16 v[0:3], v[170:173], v[206:209], v[0:3]
	v_mfma_f32_16x16x32_bf16 v[52:55], v[166:169], v[182:185], v[52:55]
	v_mfma_f32_16x16x32_bf16 v[48:51], v[174:177], v[182:185], v[48:51]
	v_mfma_f32_16x16x32_bf16 v[36:39], v[166:169], v[190:193], v[36:39]
	v_mfma_f32_16x16x32_bf16 v[32:35], v[174:177], v[190:193], v[32:35]
	v_mfma_f32_16x16x32_bf16 v[20:23], v[166:169], v[198:201], v[20:23]
	v_mfma_f32_16x16x32_bf16 v[16:19], v[174:177], v[198:201], v[16:19]
	v_mfma_f32_16x16x32_bf16 v[4:7], v[166:169], v[214:217], v[4:7]
	v_mfma_f32_16x16x32_bf16 v[0:3], v[174:177], v[214:217], v[0:3]
	s_setprio 0
	s_barrier
	s_add_i32 s47, s47, 2
	s_add_u32 s45, s45, 0x100
	s_addc_u32 s46, s46, 0
	s_add_u32 s16, s16, 0x100
	s_addc_u32 s17, s17, 0
	s_cmp_gt_u32 s47, 13
	s_cbranch_scc0 .LBB0_254
	s_and_b64 vcc, exec, s[4:5]
	s_cbranch_vccz .LBB0_257
	s_barrier

; #define PG8_STAGE(bufoff, gbase, voff) do { _Pragma("unroll") for (int _i = 0; _i < 2; ++_i) \
;         __builtin_amdgcn_global_load_lds((const unsigned*)((const char*)(gbase) + (voff)[_i]), (PG8_LAS unsigned*)(lds + (bufoff) + ldsw + _i * 8192), 16, 0, 0); } while (0)
; #define PG8_LDA(dst, b, h) do { _Pragma("unroll") for (int m = 0; m < 4; ++m) _Pragma("unroll") for (int k = 0; k < 2; ++k) dst[m][k] = *(const PG8_LAS bf16x8*)(lds + PG8_SA(b, h) + aoff + m * 2048 + k * 1024); } while (0)
; #define PG8_LDB(dst, b, h) do { _Pragma("unroll") for (int n = 0; n < 2; ++n) _Pragma("unroll") for (int k = 0; k < 2; ++k) dst[n][k] = *(const PG8_LAS bf16x8*)(lds + PG8_SB(b, h) + boff + n * 2048 + k * 1024); } while (0)
; #define PG8_MMA(ai, bj, At, Bt) do { __builtin_amdgcn_s_setprio(1); _Pragma("unroll") for (int m = 0; m < 4; ++m) _Pragma("unroll") for (int n = 0; n < 2; ++n) _Pragma("unroll") for (int k = 0; k < 2; ++k) \
;         acc[ai][bj][m][n] = __builtin_amdgcn_mfma_f32_16x16x32_bf16(Bt[n][k], At[m][k], acc[ai][bj][m][n], 0, 0, 0); __builtin_amdgcn_s_setprio(0); } while (0)
; #define PG8_WAIT_V(n) asm volatile("s_waitcnt vmcnt(" #n ")" ::: "memory")
; #define PG8_WAIT_L(n) asm volatile("s_waitcnt lgkmcnt(" #n ")" ::: "memory")
; template <class Epi, class Sched, bool ALIGN_EPI = false, bool SP2 = false>
; __device__ __forceinline__ void gemm_phase(PG8_LAS unsigned char* lds, const Gemm g, const Sched& S, const Epi& E, const int tid) {
;     ...
;             const bool last = (t == nt - 2);
;             const char* a1 = cA + (size_t)(t + 1) * kstep;
;             const char* a2 = last ? nA : cA + (size_t)(t + 2) * kstep; const char* b2 = last ? nB : cB + (size_t)(t + 2) * kstep;
;             const char* a3 = a2 + kstep; const char* b3 = b2 + kstep;
;             if (last && has_next) S.a_ready(nxt);
;             if constexpr (SP2) {
;             PG8_LDB(B0, 0, 0); PG8_LDB(B1, 0, 1); PG8_SCHED; PG8_LDA(At, 0, 0); PG8_STAGE(PG8_SA(1, 1), a1 + hstep, voffA);
;             PG8_WAIT_V(8); PG8_WAIT_L(0); PG8_BAR; PG8_MMA(0, 0, At, B0); PG8_MMA(0, 1, At, B1); PG8_BAR; PG8_SCHED;
;             PG8_LDA(At, 0, 1); PG8_STAGE(PG8_SB(0, 0), b2, voffB); PG8_STAGE(PG8_SB(0, 1), b2 + hstep, voffB); PG8_STAGE(PG8_SA(0, 0), a2, voffA);
;             PG8_WAIT_V(8); PG8_WAIT_L(0); PG8_BAR; PG8_MMA(1, 0, At, B0); PG8_MMA(1, 1, At, B1); PG8_BAR; PG8_SCHED;
.LBB0_286:
	s_add_u32 s20, s8, s18
	s_addc_u32 s21, s9, s19
	s_add_u32 s20, s20, 0x100
	s_addc_u32 s21, s21, 0
	s_add_u32 s54, s49, s18
	s_addc_u32 s55, s50, s19
	s_add_i32 s56, 0, 0x10000
	s_cmpk_eq_i32 s18, 0x700
	s_cselect_b32 s23, s13, s21
	s_cselect_b32 s22, s51, s20
	s_cselect_b32 s21, s11, s55
	s_cselect_b32 s20, s52, s54
	s_add_i32 s57, 0, 0x14000
	v_add_u32_e32 v86, s56, v72
	v_add_u32_e32 v110, s57, v72
	ds_read_b128 v[74:77], v86
	ds_read_b128 v[78:81], v86 offset:1024
	ds_read_b128 v[82:85], v86 offset:2048
	ds_read_b128 v[86:89], v86 offset:3072
	ds_read_b128 v[90:93], v110
	ds_read_b128 v[94:97], v110 offset:1024
	ds_read_b128 v[106:109], v110 offset:2048
	ds_read_b128 v[110:113], v110 offset:3072
	v_lshl_add_u64 v[202:203], v[70:71], 0, s[18:19]
	s_add_i32 m0, s31, 0xc000
	ds_read_b128 v[114:117], v73
	ds_read_b128 v[118:121], v73 offset:1024
	ds_read_b128 v[122:125], v73 offset:2048
	ds_read_b128 v[126:129], v73 offset:3072
	ds_read_b128 v[194:197], v73 offset:4096
	ds_read_b128 v[198:201], v73 offset:5120
	ds_read_b128 v[206:209], v73 offset:6144
	ds_read_b128 v[214:217], v73 offset:7168
	global_load_lds_dwordx4 v[202:203], off
	v_lshl_add_u64 v[202:203], v[68:69], 0, s[18:19]
	s_add_i32 m0, s31, 0xe000
	s_nop 0
	global_load_lds_dwordx4 v[202:203], off
	s_waitcnt vmcnt(8)
	s_waitcnt lgkmcnt(0)
	s_barrier
	s_setprio 1
	v_mfma_f32_16x16x32_bf16 v[190:193], v[74:77], v[114:117], v[190:193]
	v_mfma_f32_16x16x32_bf16 v[186:189], v[82:85], v[114:117], v[186:189]
	v_mfma_f32_16x16x32_bf16 v[182:185], v[74:77], v[122:125], v[182:185]
	v_mfma_f32_16x16x32_bf16 v[178:181], v[82:85], v[122:125], v[178:181]
	v_mfma_f32_16x16x32_bf16 v[174:177], v[74:77], v[194:197], v[174:177]
	v_mfma_f32_16x16x32_bf16 v[170:173], v[82:85], v[194:197], v[170:173]
	v_mfma_f32_16x16x32_bf16 v[166:169], v[74:77], v[206:209], v[166:169]
	v_mfma_f32_16x16x32_bf16 v[162:165], v[82:85], v[206:209], v[162:165]
	v_mfma_f32_16x16x32_bf16 v[190:193], v[78:81], v[118:121], v[190:193]
	v_mfma_f32_16x16x32_bf16 v[186:189], v[86:89], v[118:121], v[186:189]
	v_mfma_f32_16x16x32_bf16 v[182:185], v[78:81], v[126:129], v[182:185]
	v_mfma_f32_16x16x32_bf16 v[178:181], v[86:89], v[126:129], v[178:181]
	v_mfma_f32_16x16x32_bf16 v[174:177], v[78:81], v[198:201], v[174:177]
	v_mfma_f32_16x16x32_bf16 v[170:173], v[86:89], v[198:201], v[170:173]
	v_mfma_f32_16x16x32_bf16 v[166:169], v[78:81], v[214:217], v[166:169]
	v_mfma_f32_16x16x32_bf16 v[162:165], v[86:89], v[214:217], v[162:165]
	v_mfma_f32_16x16x32_bf16 v[102:105], v[90:93], v[114:117], v[102:105]
	v_mfma_f32_16x16x32_bf16 v[98:101], v[106:109], v[114:117], v[98:101]
	v_mfma_f32_16x16x32_bf16 v[56:59], v[90:93], v[122:125], v[56:59]
	v_mfma_f32_16x16x32_bf16 v[48:51], v[106:109], v[122:125], v[48:51]
	v_mfma_f32_16x16x32_bf16 v[44:47], v[90:93], v[194:197], v[44:47]
	v_mfma_f32_16x16x32_bf16 v[40:43], v[106:109], v[194:197], v[40:43]
	v_mfma_f32_16x16x32_bf16 v[36:39], v[90:93], v[206:209], v[36:39]
	v_mfma_f32_16x16x32_bf16 v[32:35], v[106:109], v[206:209], v[32:35]
	v_mfma_f32_16x16x32_bf16 v[102:105], v[94:97], v[118:121], v[102:105]
	v_mfma_f32_16x16x32_bf16 v[98:101], v[110:113], v[118:121], v[98:101]
	v_mfma_f32_16x16x32_bf16 v[56:59], v[94:97], v[126:129], v[56:59]
	v_mfma_f32_16x16x32_bf16 v[48:51], v[110:113], v[126:129], v[48:51]
	v_mfma_f32_16x16x32_bf16 v[44:47], v[94:97], v[198:201], v[44:47]
	v_mfma_f32_16x16x32_bf16 v[40:43], v[110:113], v[198:201], v[40:43]
	v_mfma_f32_16x16x32_bf16 v[36:39], v[94:97], v[214:217], v[36:39]
	v_mfma_f32_16x16x32_bf16 v[32:35], v[110:113], v[214:217], v[32:35]
	s_setprio 0
	s_barrier
	s_add_i32 s54, s56, s30
	v_lshl_add_u64 v[202:203], s[20:21], 0, v[64:65]
	s_mov_b32 m0, s54
	ds_read_b128 v[114:117], v73 offset:16384
	ds_read_b128 v[118:121], v73 offset:17408
	ds_read_b128 v[122:125], v73 offset:18432
	ds_read_b128 v[126:129], v73 offset:19456
	ds_read_b128 v[194:197], v73 offset:20480
	ds_read_b128 v[198:201], v73 offset:21504
	ds_read_b128 v[206:209], v73 offset:22528
	ds_read_b128 v[214:217], v73 offset:23552
	global_load_lds_dwordx4 v[202:203], off
	s_add_i32 m0, s54, 0x2000
	s_add_u32 s54, s20, 0x40000
	v_lshl_add_u64 v[210:211], s[20:21], 0, v[52:53]
	s_addc_u32 s55, s21, 0
	s_add_i32 s56, s57, s30
	global_load_lds_dwordx4 v[210:211], off
	v_lshl_add_u64 v[218:219], s[54:55], 0, v[64:65]
	s_mov_b32 m0, s56
	v_lshl_add_u64 v[226:227], s[22:23], 0, v[60:61]
	global_load_lds_dwordx4 v[218:219], off
	v_lshl_add_u64 v[218:219], s[54:55], 0, v[52:53]
	s_add_i32 m0, s56, 0x2000
	v_lshl_add_u64 v[228:229], s[22:23], 0, v[54:55]
	global_load_lds_dwordx4 v[218:219], off
	s_mov_b32 m0, s31
	s_nop 0
	global_load_lds_dwordx4 v[226:227], off
	s_mov_b32 m0, s35
	s_nop 0
	global_load_lds_dwordx4 v[228:229], off
	s_waitcnt vmcnt(8)
	s_waitcnt lgkmcnt(0)
	s_barrier
; #define PG8_STAGE(bufoff, gbase, voff) do { _Pragma("unroll") for (int _i = 0; _i < 2; ++_i) \
;         __builtin_amdgcn_global_load_lds((const unsigned*)((const char*)(gbase) + (voff)[_i]), (PG8_LAS unsigned*)(lds + (bufoff) + ldsw + _i * 8192), 16, 0, 0); } while (0)
; #define PG8_LDA(dst, b, h) do { _Pragma("unroll") for (int m = 0; m < 4; ++m) _Pragma("unroll") for (int k = 0; k < 2; ++k) dst[m][k] = *(const PG8_LAS bf16x8*)(lds + PG8_SA(b, h) + aoff + m * 2048 + k * 1024); } while (0)
; #define PG8_LDB(dst, b, h) do { _Pragma("unroll") for (int n = 0; n < 2; ++n) _Pragma("unroll") for (int k = 0; k < 2; ++k) dst[n][k] = *(const PG8_LAS bf16x8*)(lds + PG8_SB(b, h) + boff + n * 2048 + k * 1024); } while (0)
; #define PG8_MMA(ai, bj, At, Bt) do { __builtin_amdgcn_s_setprio(1); _Pragma("unroll") for (int m = 0; m < 4; ++m) _Pragma("unroll") for (int n = 0; n < 2; ++n) _Pragma("unroll") for (int k = 0; k < 2; ++k) \
;         acc[ai][bj][m][n] = __builtin_amdgcn_mfma_f32_16x16x32_bf16(Bt[n][k], At[m][k], acc[ai][bj][m][n], 0, 0, 0); __builtin_amdgcn_s_setprio(0); } while (0)
; #define PG8_WAIT_V(n) asm volatile("s_waitcnt vmcnt(" #n ")" ::: "memory")
; #define PG8_WAIT_L(n) asm volatile("s_waitcnt lgkmcnt(" #n ")" ::: "memory")
; #define PG8_BAR __builtin_amdgcn_s_barrier()
; #define PG8_SCHED __builtin_amdgcn_sched_barrier(0)
; template <class Epi, class Sched, bool ALIGN_EPI = false, bool SP2 = false>
; __device__ __forceinline__ void gemm_phase(PG8_LAS unsigned char* lds, const Gemm g, const Sched& S, const Epi& E, const int tid) {
;     ...
;             PG8_WAIT_V(8); PG8_WAIT_L(0); PG8_BAR; PG8_MMA(1, 0, At, B0); PG8_MMA(1, 1, At, B1); PG8_BAR; PG8_SCHED;
;             PG8_LDB(B0, 1, 0); PG8_LDB(B1, 1, 1); PG8_SCHED; PG8_LDA(At, 1, 0); PG8_STAGE(PG8_SA(0, 1), a2 + hstep, voffA);
;             PG8_WAIT_V(8); PG8_WAIT_L(0); PG8_BAR; PG8_MMA(0, 0, At, B0); PG8_MMA(0, 1, At, B1); PG8_BAR; PG8_SCHED;
	s_setprio 1
	v_mfma_f32_16x16x32_bf16 v[158:161], v[74:77], v[114:117], v[158:161]
	v_mfma_f32_16x16x32_bf16 v[154:157], v[82:85], v[114:117], v[154:157]
	v_mfma_f32_16x16x32_bf16 v[150:153], v[74:77], v[122:125], v[150:153]
	v_mfma_f32_16x16x32_bf16 v[146:149], v[82:85], v[122:125], v[146:149]
	v_mfma_f32_16x16x32_bf16 v[142:145], v[74:77], v[194:197], v[142:145]
	v_mfma_f32_16x16x32_bf16 v[138:141], v[82:85], v[194:197], v[138:141]
	v_mfma_f32_16x16x32_bf16 v[74:77], v[74:77], v[206:209], v[134:137]
	v_mfma_f32_16x16x32_bf16 v[158:161], v[78:81], v[118:121], v[158:161]
	v_mfma_f32_16x16x32_bf16 v[154:157], v[86:89], v[118:121], v[154:157]
	v_mfma_f32_16x16x32_bf16 v[150:153], v[78:81], v[126:129], v[150:153]
	v_mfma_f32_16x16x32_bf16 v[146:149], v[86:89], v[126:129], v[146:149]
	v_mfma_f32_16x16x32_bf16 v[142:145], v[78:81], v[198:201], v[142:145]
	v_mfma_f32_16x16x32_bf16 v[138:141], v[86:89], v[198:201], v[138:141]
	v_mfma_f32_16x16x32_bf16 v[74:77], v[78:81], v[214:217], v[74:77]
	v_mfma_f32_16x16x32_bf16 v[78:81], v[82:85], v[206:209], v[130:133]
	v_mfma_f32_16x16x32_bf16 v[78:81], v[86:89], v[214:217], v[78:81]
	v_mfma_f32_16x16x32_bf16 v[28:31], v[90:93], v[114:117], v[28:31]
	v_mfma_f32_16x16x32_bf16 v[24:27], v[106:109], v[114:117], v[24:27]
	v_mfma_f32_16x16x32_bf16 v[20:23], v[90:93], v[122:125], v[20:23]
	v_mfma_f32_16x16x32_bf16 v[16:19], v[106:109], v[122:125], v[16:19]
	v_mfma_f32_16x16x32_bf16 v[12:15], v[90:93], v[194:197], v[12:15]
	v_mfma_f32_16x16x32_bf16 v[8:11], v[106:109], v[194:197], v[8:11]
	v_mfma_f32_16x16x32_bf16 v[4:7], v[90:93], v[206:209], v[4:7]
	v_mfma_f32_16x16x32_bf16 v[0:3], v[106:109], v[206:209], v[0:3]
	v_mfma_f32_16x16x32_bf16 v[28:31], v[94:97], v[118:121], v[28:31]
	v_mfma_f32_16x16x32_bf16 v[24:27], v[110:113], v[118:121], v[24:27]
	v_mfma_f32_16x16x32_bf16 v[20:23], v[94:97], v[126:129], v[20:23]
	v_mfma_f32_16x16x32_bf16 v[16:19], v[110:113], v[126:129], v[16:19]
	v_mfma_f32_16x16x32_bf16 v[12:15], v[94:97], v[198:201], v[12:15]
	v_mfma_f32_16x16x32_bf16 v[8:11], v[110:113], v[198:201], v[8:11]
	v_mfma_f32_16x16x32_bf16 v[4:7], v[94:97], v[214:217], v[4:7]
	v_mfma_f32_16x16x32_bf16 v[0:3], v[110:113], v[214:217], v[0:3]
	s_setprio 0
	s_barrier
	s_add_i32 s54, 0, 0x18000
	s_add_i32 s55, 0, 0x1c000
	v_add_u32_e32 v94, s54, v72
	v_add_u32_e32 v118, s55, v72
	ds_read_b128 v[82:85], v94
	ds_read_b128 v[86:89], v94 offset:1024
	ds_read_b128 v[90:93], v94 offset:2048
	ds_read_b128 v[94:97], v94 offset:3072
	ds_read_b128 v[106:109], v118
	ds_read_b128 v[110:113], v118 offset:1024
	ds_read_b128 v[114:117], v118 offset:2048
	ds_read_b128 v[118:121], v118 offset:3072
	s_add_u32 s22, s22, 0x40000
	s_addc_u32 s23, s23, 0
	s_mov_b32 m0, s42
	v_lshl_add_u64 v[218:219], s[22:23], 0, v[60:61]
	ds_read_b128 v[122:125], v73 offset:32768
	ds_read_b128 v[126:129], v73 offset:33792
	ds_read_b128 v[130:133], v73 offset:34816
	ds_read_b128 v[134:137], v73 offset:35840
	ds_read_b128 v[194:197], v73 offset:36864
	ds_read_b128 v[198:201], v73 offset:37888
	ds_read_b128 v[206:209], v73 offset:38912
	ds_read_b128 v[214:217], v73 offset:39936
	global_load_lds_dwordx4 v[218:219], off
	v_lshl_add_u64 v[218:219], s[22:23], 0, v[54:55]
	s_mov_b32 m0, s44
	s_nop 0
	global_load_lds_dwordx4 v[218:219], off
	s_waitcnt vmcnt(8)
	s_waitcnt lgkmcnt(0)
	s_barrier
	s_setprio 1
	v_mfma_f32_16x16x32_bf16 v[190:193], v[82:85], v[122:125], v[190:193]
	v_mfma_f32_16x16x32_bf16 v[186:189], v[90:93], v[122:125], v[186:189]
	v_mfma_f32_16x16x32_bf16 v[182:185], v[82:85], v[130:133], v[182:185]
	v_mfma_f32_16x16x32_bf16 v[178:181], v[90:93], v[130:133], v[178:181]
	v_mfma_f32_16x16x32_bf16 v[174:177], v[82:85], v[194:197], v[174:177]
	v_mfma_f32_16x16x32_bf16 v[170:173], v[90:93], v[194:197], v[170:173]
	v_mfma_f32_16x16x32_bf16 v[166:169], v[82:85], v[206:209], v[166:169]
	v_mfma_f32_16x16x32_bf16 v[162:165], v[90:93], v[206:209], v[162:165]
	v_mfma_f32_16x16x32_bf16 v[190:193], v[86:89], v[126:129], v[190:193]
	v_mfma_f32_16x16x32_bf16 v[186:189], v[94:97], v[126:129], v[186:189]
	v_mfma_f32_16x16x32_bf16 v[182:185], v[86:89], v[134:137], v[182:185]
	v_mfma_f32_16x16x32_bf16 v[178:181], v[94:97], v[134:137], v[178:181]
	v_mfma_f32_16x16x32_bf16 v[174:177], v[86:89], v[198:201], v[174:177]
	v_mfma_f32_16x16x32_bf16 v[170:173], v[94:97], v[198:201], v[170:173]
	v_mfma_f32_16x16x32_bf16 v[166:169], v[86:89], v[214:217], v[166:169]
	v_mfma_f32_16x16x32_bf16 v[162:165], v[94:97], v[214:217], v[162:165]
	v_mfma_f32_16x16x32_bf16 v[102:105], v[106:109], v[122:125], v[102:105]
	v_mfma_f32_16x16x32_bf16 v[98:101], v[114:117], v[122:125], v[98:101]
	v_mfma_f32_16x16x32_bf16 v[56:59], v[106:109], v[130:133], v[56:59]
	v_mfma_f32_16x16x32_bf16 v[48:51], v[114:117], v[130:133], v[48:51]
	v_mfma_f32_16x16x32_bf16 v[44:47], v[106:109], v[194:197], v[44:47]
	v_mfma_f32_16x16x32_bf16 v[40:43], v[114:117], v[194:197], v[40:43]
	v_mfma_f32_16x16x32_bf16 v[36:39], v[106:109], v[206:209], v[36:39]
	v_mfma_f32_16x16x32_bf16 v[32:35], v[114:117], v[206:209], v[32:35]
	v_mfma_f32_16x16x32_bf16 v[102:105], v[110:113], v[126:129], v[102:105]
	v_mfma_f32_16x16x32_bf16 v[98:101], v[118:121], v[126:129], v[98:101]
	v_mfma_f32_16x16x32_bf16 v[56:59], v[110:113], v[134:137], v[56:59]
	v_mfma_f32_16x16x32_bf16 v[48:51], v[118:121], v[134:137], v[48:51]
	v_mfma_f32_16x16x32_bf16 v[44:47], v[110:113], v[198:201], v[44:47]
	v_mfma_f32_16x16x32_bf16 v[40:43], v[118:121], v[198:201], v[40:43]
	v_mfma_f32_16x16x32_bf16 v[36:39], v[110:113], v[214:217], v[36:39]
	v_mfma_f32_16x16x32_bf16 v[32:35], v[118:121], v[214:217], v[32:35]
	s_setprio 0
	s_barrier
; #define PG8_WAIT_V(n) asm volatile("s_waitcnt vmcnt(" #n ")" ::: "memory")
; template <class Epi, class Sched, bool ALIGN_EPI = false, bool SP2 = false>
; __device__ __forceinline__ void gemm_phase(PG8_LAS unsigned char* lds, const Gemm g, const Sched& S, const Epi& E, const int tid) {
;     ...
;             PG8_LDA(At, 1, 1); PG8_STAGE(PG8_SB(1, 0), b3, voffB); PG8_STAGE(PG8_SB(1, 1), b3 + hstep, voffB); PG8_STAGE(PG8_SA(1, 0), a3, voffA);
;             PG8_WAIT_V(8); PG8_WAIT_L(0); PG8_BAR; PG8_MMA(1, 0, At, B0); PG8_MMA(1, 1, At, B1); PG8_BAR; PG8_SCHED;
;             } else {
;             PG8_LDB(B0, 0, 0); PG8_SCHED; PG8_LDA(At, 0, 0); PG8_STAGE(PG8_SA(1, 1), a1 + hstep, voffA);
;             PG8_WAIT_L(8); PG8_BAR; PG8_WAIT_L(0); PG8_MMA(0, 0, At, B0); PG8_BAR; PG8_SCHED;
;             PG8_LDB(B1, 0, 1); PG8_STAGE(PG8_SB(0, 0), b2, voffB);
;             PG8_BAR; PG8_WAIT_L(0); PG8_MMA(0, 1, At, B1); PG8_BAR;
;             PG8_LDA(At, 0, 1); PG8_STAGE(PG8_SA(0, 0), a2, voffA);
;             PG8_BAR; PG8_WAIT_L(0); PG8_MMA(1, 0, At, B0); PG8_BAR; PG8_SCHED;
;             PG8_STAGE(PG8_SB(0, 1), b2 + hstep, voffB);
;             PG8_WAIT_V(6); PG8_BAR; PG8_MMA(1, 1, At, B1); PG8_BAR;
;             PG8_LDB(B0, 1, 0); PG8_SCHED; PG8_LDA(At, 1, 0); PG8_STAGE(PG8_SA(0, 1), a2 + hstep, voffA);
;             PG8_WAIT_L(8); PG8_BAR; PG8_WAIT_L(0); PG8_MMA(0, 0, At, B0); PG8_BAR; PG8_SCHED;
;             PG8_LDB(B1, 1, 1); PG8_STAGE(PG8_SB(1, 0), b3, voffB);
;             PG8_BAR; PG8_WAIT_L(0); PG8_MMA(0, 1, At, B1); PG8_BAR;
;             PG8_LDA(At, 1, 1); PG8_STAGE(PG8_SA(1, 0), a3, voffA);
;             PG8_BAR; PG8_WAIT_L(0); PG8_MMA(1, 0, At, B0); PG8_BAR; PG8_SCHED;
;             PG8_STAGE(PG8_SB(1, 1), b3 + hstep, voffB);
;             PG8_WAIT_V(6); PG8_BAR; PG8_MMA(1, 1, At, B1); PG8_BAR;
;             }
;         }
;         if constexpr (ALIGN_EPI) { if (wr == 0) PG8_BAR; }
;         if constexpr (!Epi::AFTER_DRAIN) { E(acc, cur, wr, wc, fr, fq); S.done(cur); }
;         if (!has_next) break;
; #pragma unroll
;         for (int a = 0; a < 2; ++a)
; #pragma unroll
;             for (int b = 0; b < 2; ++b)
; #pragma unroll
;                 for (int m = 0; m < 4; ++m)
; #pragma unroll
;                     for (int n = 0; n < 2; ++n) acc[a][b][m][n] = (f32x4){0.f, 0.f, 0.f, 0.f};
;         cur = nxt; cA = nA; cB = nB; ++ui;
	s_add_i32 s22, s54, s30
	v_lshl_add_u64 v[130:131], v[202:203], 0, s[94:95]
	s_mov_b32 m0, s22
	ds_read_b128 v[122:125], v73 offset:49152
	ds_read_b128 v[126:129], v73 offset:50176
	ds_read_b128 v[194:197], v73 offset:51200
	ds_read_b128 v[198:201], v73 offset:52224
	ds_read_b128 v[206:209], v73 offset:53248
	ds_read_b128 v[214:217], v73 offset:54272
	ds_read_b128 v[218:221], v73 offset:55296
	ds_read_b128 v[222:225], v73 offset:56320
	global_load_lds_dwordx4 v[130:131], off
	s_add_i32 m0, s22, 0x2000
	s_add_u32 s20, s20, 0x40080
	v_lshl_add_u64 v[130:131], v[210:211], 0, s[94:95]
	s_addc_u32 s21, s21, 0
	s_add_i32 s22, s55, s30
	global_load_lds_dwordx4 v[130:131], off
	v_lshl_add_u64 v[130:131], s[20:21], 0, v[64:65]
	s_mov_b32 m0, s22
	s_nop 0
	global_load_lds_dwordx4 v[130:131], off
	v_lshl_add_u64 v[130:131], s[20:21], 0, v[52:53]
	s_add_i32 m0, s22, 0x2000
	s_nop 0
	global_load_lds_dwordx4 v[130:131], off
	v_lshl_add_u64 v[130:131], v[226:227], 0, s[94:95]
	s_mov_b32 m0, s45
	s_nop 0
	global_load_lds_dwordx4 v[130:131], off
	v_lshl_add_u64 v[130:131], v[228:229], 0, s[94:95]
	s_mov_b32 m0, s46
	s_nop 0
	global_load_lds_dwordx4 v[130:131], off
	s_waitcnt vmcnt(8)
	s_waitcnt lgkmcnt(0)
	s_barrier
	s_setprio 1
	v_mfma_f32_16x16x32_bf16 v[130:133], v[82:85], v[122:125], v[158:161]
	v_mfma_f32_16x16x32_bf16 v[158:161], v[86:89], v[126:129], v[130:133]
	v_mfma_f32_16x16x32_bf16 v[130:133], v[90:93], v[122:125], v[154:157]
	v_mfma_f32_16x16x32_bf16 v[154:157], v[94:97], v[126:129], v[130:133]
	v_mfma_f32_16x16x32_bf16 v[130:133], v[82:85], v[194:197], v[150:153]
	v_mfma_f32_16x16x32_bf16 v[150:153], v[86:89], v[198:201], v[130:133]
	v_mfma_f32_16x16x32_bf16 v[130:133], v[90:93], v[194:197], v[146:149]
	v_mfma_f32_16x16x32_bf16 v[146:149], v[94:97], v[198:201], v[130:133]
	v_mfma_f32_16x16x32_bf16 v[130:133], v[82:85], v[206:209], v[142:145]
	v_mfma_f32_16x16x32_bf16 v[74:77], v[82:85], v[218:221], v[74:77]
	v_mfma_f32_16x16x32_bf16 v[142:145], v[86:89], v[214:217], v[130:133]
	v_mfma_f32_16x16x32_bf16 v[130:133], v[90:93], v[206:209], v[138:141]
	v_mfma_f32_16x16x32_bf16 v[134:137], v[86:89], v[222:225], v[74:77]
	v_mfma_f32_16x16x32_bf16 v[74:77], v[90:93], v[218:221], v[78:81]
	v_mfma_f32_16x16x32_bf16 v[138:141], v[94:97], v[214:217], v[130:133]
	v_mfma_f32_16x16x32_bf16 v[130:133], v[94:97], v[222:225], v[74:77]
	v_mfma_f32_16x16x32_bf16 v[28:31], v[106:109], v[122:125], v[28:31]
	v_mfma_f32_16x16x32_bf16 v[24:27], v[114:117], v[122:125], v[24:27]
	v_mfma_f32_16x16x32_bf16 v[20:23], v[106:109], v[194:197], v[20:23]
	v_mfma_f32_16x16x32_bf16 v[16:19], v[114:117], v[194:197], v[16:19]
	v_mfma_f32_16x16x32_bf16 v[12:15], v[106:109], v[206:209], v[12:15]
	v_mfma_f32_16x16x32_bf16 v[8:11], v[114:117], v[206:209], v[8:11]
	v_mfma_f32_16x16x32_bf16 v[4:7], v[106:109], v[218:221], v[4:7]
	v_mfma_f32_16x16x32_bf16 v[0:3], v[114:117], v[218:221], v[0:3]
	v_mfma_f32_16x16x32_bf16 v[28:31], v[110:113], v[126:129], v[28:31]
	v_mfma_f32_16x16x32_bf16 v[24:27], v[118:121], v[126:129], v[24:27]
	v_mfma_f32_16x16x32_bf16 v[20:23], v[110:113], v[198:201], v[20:23]
	v_mfma_f32_16x16x32_bf16 v[16:19], v[118:121], v[198:201], v[16:19]
	v_mfma_f32_16x16x32_bf16 v[12:15], v[110:113], v[214:217], v[12:15]
	v_mfma_f32_16x16x32_bf16 v[8:11], v[118:121], v[214:217], v[8:11]
	v_mfma_f32_16x16x32_bf16 v[4:7], v[110:113], v[222:225], v[4:7]
	v_mfma_f32_16x16x32_bf16 v[0:3], v[118:121], v[222:225], v[0:3]
	s_setprio 0
	s_barrier
	s_add_i32 s53, s53, 2
	s_add_u32 s18, s18, 0x100
	s_addc_u32 s19, s19, 0
	s_cmp_gt_u32 s53, 13
	s_cbranch_scc0 .LBB0_286
	s_add_u32 s18, s49, 0xffffff00
	s_addc_u32 s19, s50, -1
	s_andn2_b64 vcc, exec, s[2:3]
	s_cbranch_vccnz .LBB0_289
	v_mov_b32_e32 v0, 0
	s_mov_b32 s4, s10
	s_mov_b32 s24, s12
	s_mov_b64 s[8:9], s[16:17]
	s_mov_b32 s47, s48
	v_mov_b32_e32 v1, v0
	v_mov_b32_e32 v2, v0
	v_mov_b32_e32 v3, v0
	v_mov_b32_e32 v4, v0
	v_mov_b32_e32 v5, v0
	v_mov_b32_e32 v6, v0
	v_mov_b32_e32 v7, v0
	v_mov_b32_e32 v8, v0
	v_mov_b32_e32 v9, v0
	v_mov_b32_e32 v10, v0
	v_mov_b32_e32 v11, v0
	v_mov_b32_e32 v12, v0
	v_mov_b32_e32 v13, v0
	v_mov_b32_e32 v14, v0
	v_mov_b32_e32 v15, v0
	v_mov_b32_e32 v16, v0
	v_mov_b32_e32 v17, v0
	v_mov_b32_e32 v18, v0
	v_mov_b32_e32 v19, v0
	v_mov_b32_e32 v20, v0
	v_mov_b32_e32 v21, v0
	v_mov_b32_e32 v22, v0
	v_mov_b32_e32 v23, v0
	v_mov_b32_e32 v24, v0
	v_mov_b32_e32 v25, v0
	v_mov_b32_e32 v26, v0
	v_mov_b32_e32 v27, v0
	v_mov_b32_e32 v28, v0
	v_mov_b32_e32 v29, v0
	v_mov_b32_e32 v30, v0
	v_mov_b32_e32 v31, v0
	v_mov_b32_e32 v130, v0
	v_mov_b32_e32 v131, v0
	v_mov_b32_e32 v132, v0
	v_mov_b32_e32 v133, v0
	v_mov_b32_e32 v134, v0
	v_mov_b32_e32 v135, v0
	v_mov_b32_e32 v136, v0
	v_mov_b32_e32 v137, v0
	v_mov_b32_e32 v138, v0
	v_mov_b32_e32 v139, v0
	v_mov_b32_e32 v140, v0
	v_mov_b32_e32 v141, v0
	v_mov_b32_e32 v142, v0
	v_mov_b32_e32 v143, v0
	v_mov_b32_e32 v144, v0
	v_mov_b32_e32 v145, v0
	v_mov_b32_e32 v146, v0
	v_mov_b32_e32 v147, v0
	v_mov_b32_e32 v148, v0
	v_mov_b32_e32 v149, v0
	v_mov_b32_e32 v150, v0
	v_mov_b32_e32 v151, v0
	v_mov_b32_e32 v152, v0
	v_mov_b32_e32 v153, v0
	v_mov_b32_e32 v154, v0
	v_mov_b32_e32 v155, v0
	v_mov_b32_e32 v156, v0
	v_mov_b32_e32 v157, v0
	v_mov_b32_e32 v158, v0
	v_mov_b32_e32 v159, v0
	v_mov_b32_e32 v160, v0
	v_mov_b32_e32 v161, v0
	v_mov_b32_e32 v32, v0
	v_mov_b32_e32 v33, v0
	v_mov_b32_e32 v34, v0
	v_mov_b32_e32 v35, v0
	v_mov_b32_e32 v36, v0
	v_mov_b32_e32 v37, v0
	v_mov_b32_e32 v38, v0
	v_mov_b32_e32 v39, v0
	v_mov_b32_e32 v40, v0
	v_mov_b32_e32 v41, v0
	v_mov_b32_e32 v42, v0
	v_mov_b32_e32 v43, v0
	v_mov_b32_e32 v44, v0
	v_mov_b32_e32 v45, v0
	v_mov_b32_e32 v46, v0
	v_mov_b32_e32 v47, v0
	v_mov_b32_e32 v48, v0
	v_mov_b32_e32 v49, v0
	v_mov_b32_e32 v50, v0
	v_mov_b32_e32 v51, v0
	v_mov_b32_e32 v56, v0
	v_mov_b32_e32 v57, v0
	v_mov_b32_e32 v58, v0
	v_mov_b32_e32 v59, v0
	v_mov_b32_e32 v98, v0
	v_mov_b32_e32 v99, v0
	v_mov_b32_e32 v100, v0
	v_mov_b32_e32 v101, v0
	v_mov_b32_e32 v102, v0
	v_mov_b32_e32 v103, v0
	v_mov_b32_e32 v104, v0
	v_mov_b32_e32 v105, v0
	v_mov_b32_e32 v162, v0
	v_mov_b32_e32 v163, v0
	v_mov_b32_e32 v164, v0
	v_mov_b32_e32 v165, v0
	v_mov_b32_e32 v166, v0
	v_mov_b32_e32 v167, v0
	v_mov_b32_e32 v168, v0
	v_mov_b32_e32 v169, v0
	v_mov_b32_e32 v170, v0
	v_mov_b32_e32 v171, v0
	v_mov_b32_e32 v172, v0
	v_mov_b32_e32 v173, v0
	v_mov_b32_e32 v174, v0
	v_mov_b32_e32 v175, v0
	v_mov_b32_e32 v176, v0
	v_mov_b32_e32 v177, v0
	v_mov_b32_e32 v178, v0
	v_mov_b32_e32 v179, v0
	v_mov_b32_e32 v180, v0
	v_mov_b32_e32 v181, v0
	v_mov_b32_e32 v182, v0
	v_mov_b32_e32 v183, v0
	v_mov_b32_e32 v184, v0
	v_mov_b32_e32 v185, v0
	v_mov_b32_e32 v186, v0
	v_mov_b32_e32 v187, v0
	v_mov_b32_e32 v188, v0
	v_mov_b32_e32 v189, v0
	v_mov_b32_e32 v190, v0
	v_mov_b32_e32 v191, v0
	v_mov_b32_e32 v192, v0
	v_mov_b32_e32 v193, v0
	s_andn2_b64 vcc, exec, s[0:1]
	s_cbranch_vccnz .LBB0_290
	s_branch .LBB0_291

; #define PG8_STAGE(bufoff, gbase, voff) do { _Pragma("unroll") for (int _i = 0; _i < 2; ++_i) \
;         __builtin_amdgcn_global_load_lds((const unsigned*)((const char*)(gbase) + (voff)[_i]), (PG8_LAS unsigned*)(lds + (bufoff) + ldsw + _i * 8192), 16, 0, 0); } while (0)
; #define PG8_LDA(dst, b, h) do { _Pragma("unroll") for (int m = 0; m < 4; ++m) _Pragma("unroll") for (int k = 0; k < 2; ++k) dst[m][k] = *(const PG8_LAS bf16x8*)(lds + PG8_SA(b, h) + aoff + m * 2048 + k * 1024); } while (0)
; #define PG8_LDB(dst, b, h) do { _Pragma("unroll") for (int n = 0; n < 2; ++n) _Pragma("unroll") for (int k = 0; k < 2; ++k) dst[n][k] = *(const PG8_LAS bf16x8*)(lds + PG8_SB(b, h) + boff + n * 2048 + k * 1024); } while (0)
; #define PG8_MMA(ai, bj, At, Bt) do { __builtin_amdgcn_s_setprio(1); _Pragma("unroll") for (int m = 0; m < 4; ++m) _Pragma("unroll") for (int n = 0; n < 2; ++n) _Pragma("unroll") for (int k = 0; k < 2; ++k) \
;         acc[ai][bj][m][n] = __builtin_amdgcn_mfma_f32_16x16x32_bf16(Bt[n][k], At[m][k], acc[ai][bj][m][n], 0, 0, 0); __builtin_amdgcn_s_setprio(0); } while (0)
; #define PG8_WAIT_V(n) asm volatile("s_waitcnt vmcnt(" #n ")" ::: "memory")
; #define PG8_WAIT_L(n) asm volatile("s_waitcnt lgkmcnt(" #n ")" ::: "memory")
; #define PG8_BAR __builtin_amdgcn_s_barrier()
; #define PG8_SCHED __builtin_amdgcn_sched_barrier(0)
; template <class Epi, class Sched, bool ALIGN_EPI = false, bool SP2 = false>
; __device__ __forceinline__ void gemm_phase(PG8_LAS unsigned char* lds, const Gemm g, const Sched& S, const Epi& E, const int tid) {
;     ...
;     f32x4 acc[2][2][4][2];
; #pragma unroll
;     for (int a = 0; a < 2; ++a)
; #pragma unroll
;         for (int b = 0; b < 2; ++b)
; #pragma unroll
;             for (int m = 0; m < 4; ++m)
; #pragma unroll
;                 for (int n = 0; n < 2; ++n) acc[a][b][m][n] = (f32x4){0.f, 0.f, 0.f, 0.f};
;     ...
;             PG8_LDB(B0, 0, 0); PG8_LDB(B1, 0, 1); PG8_SCHED; PG8_LDA(At, 0, 0); PG8_STAGE(PG8_SA(1, 1), a1 + hstep, voffA);
;             PG8_WAIT_V(8); PG8_WAIT_L(0); PG8_BAR; PG8_MMA(0, 0, At, B0); PG8_MMA(0, 1, At, B1); PG8_BAR; PG8_SCHED;
;             PG8_LDA(At, 0, 1); PG8_STAGE(PG8_SB(0, 0), b2, voffB); PG8_STAGE(PG8_SB(0, 1), b2 + hstep, voffB); PG8_STAGE(PG8_SA(0, 0), a2, voffA);
;             PG8_WAIT_V(8); PG8_WAIT_L(0); PG8_BAR; PG8_MMA(1, 0, At, B0); PG8_MMA(1, 1, At, B1); PG8_BAR; PG8_SCHED;
.LBB0_348:
	s_add_i32 s47, 0, 0x10000
	s_add_i32 s45, 0, 0x14000
	v_add_u32_e32 v8, s47, v141
	v_add_u32_e32 v9, s45, v141
	ds_read_b128 v[10:13], v8
	ds_read_b128 v[14:17], v8 offset:1024
	ds_read_b128 v[18:21], v8 offset:2048
	ds_read_b128 v[22:25], v8 offset:3072
	ds_read_b128 v[26:29], v9
	ds_read_b128 v[30:33], v9 offset:1024
	ds_read_b128 v[34:37], v9 offset:2048
	ds_read_b128 v[38:41], v9 offset:3072
	s_add_u32 s2, s14, 0x18080
	s_addc_u32 s3, s15, 0
	s_add_i32 s50, s23, 0xc000
	v_lshl_add_u64 v[62:63], s[2:3], 0, v[136:137]
	s_mov_b32 m0, s50
	ds_read_b128 v[0:3], v142
	ds_read_b128 v[4:7], v142 offset:1024
	ds_read_b128 v[42:45], v142 offset:2048
	ds_read_b128 v[46:49], v142 offset:3072
	ds_read_b128 v[50:53], v142 offset:4096
	ds_read_b128 v[54:57], v142 offset:5120
	ds_read_b128 v[58:61], v142 offset:6144
	ds_read_b128 v[66:69], v142 offset:7168
	global_load_lds_dwordx4 v[62:63], off
	v_lshl_add_u64 v[62:63], s[2:3], 0, v[132:133]
	s_add_i32 s2, s23, 0xe000
	s_mov_b32 m0, s2
	s_nop 0
	global_load_lds_dwordx4 v[62:63], off
	s_waitcnt vmcnt(8)
	s_waitcnt lgkmcnt(0)
	s_barrier
	s_setprio 1
	v_mfma_f32_16x16x32_bf16 v[70:73], v[10:13], v[0:3], 0
	v_mfma_f32_16x16x32_bf16 v[74:77], v[18:21], v[0:3], 0
	v_mfma_f32_16x16x32_bf16 v[78:81], v[10:13], v[42:45], 0
	v_mfma_f32_16x16x32_bf16 v[82:85], v[18:21], v[42:45], 0
	v_mfma_f32_16x16x32_bf16 v[86:89], v[10:13], v[50:53], 0
	v_mfma_f32_16x16x32_bf16 v[90:93], v[18:21], v[50:53], 0
	v_mfma_f32_16x16x32_bf16 v[94:97], v[10:13], v[58:61], 0
	v_mfma_f32_16x16x32_bf16 v[98:101], v[18:21], v[58:61], 0
	v_mfma_f32_16x16x32_bf16 v[70:73], v[14:17], v[4:7], v[70:73]
	v_mfma_f32_16x16x32_bf16 v[74:77], v[22:25], v[4:7], v[74:77]
	v_mfma_f32_16x16x32_bf16 v[78:81], v[14:17], v[46:49], v[78:81]
	v_mfma_f32_16x16x32_bf16 v[82:85], v[22:25], v[46:49], v[82:85]
	v_mfma_f32_16x16x32_bf16 v[86:89], v[14:17], v[54:57], v[86:89]
	v_mfma_f32_16x16x32_bf16 v[90:93], v[22:25], v[54:57], v[90:93]
	v_mfma_f32_16x16x32_bf16 v[94:97], v[14:17], v[66:69], v[94:97]
	v_mfma_f32_16x16x32_bf16 v[98:101], v[22:25], v[66:69], v[98:101]
	v_mfma_f32_16x16x32_bf16 v[102:105], v[26:29], v[0:3], 0
	v_mfma_f32_16x16x32_bf16 v[0:3], v[34:37], v[0:3], 0
	v_mfma_f32_16x16x32_bf16 v[106:109], v[38:41], v[4:7], v[0:3]
	v_mfma_f32_16x16x32_bf16 v[0:3], v[26:29], v[42:45], 0
	v_mfma_f32_16x16x32_bf16 v[110:113], v[30:33], v[46:49], v[0:3]
	v_mfma_f32_16x16x32_bf16 v[0:3], v[34:37], v[42:45], 0
	v_mfma_f32_16x16x32_bf16 v[42:45], v[38:41], v[46:49], v[0:3]
	v_mfma_f32_16x16x32_bf16 v[0:3], v[26:29], v[50:53], 0
	v_mfma_f32_16x16x32_bf16 v[46:49], v[30:33], v[54:57], v[0:3]
	v_mfma_f32_16x16x32_bf16 v[0:3], v[34:37], v[50:53], 0
	v_mfma_f32_16x16x32_bf16 v[50:53], v[38:41], v[54:57], v[0:3]
	v_mfma_f32_16x16x32_bf16 v[0:3], v[26:29], v[58:61], 0
	v_mfma_f32_16x16x32_bf16 v[54:57], v[30:33], v[66:69], v[0:3]
	v_mfma_f32_16x16x32_bf16 v[0:3], v[34:37], v[58:61], 0
	v_mfma_f32_16x16x32_bf16 v[102:105], v[30:33], v[4:7], v[102:105]
	v_mfma_f32_16x16x32_bf16 v[58:61], v[38:41], v[66:69], v[0:3]
	s_setprio 0
	s_barrier
	s_nop 3
	v_lshl_add_u64 v[0:1], s[16:17], 0, v[134:135]
	s_mov_b64 s[52:53], 0x100
	s_add_i32 s47, s47, s22
	v_lshl_add_u64 v[2:3], v[0:1], 0, s[52:53]
	s_mov_b32 m0, s47
	s_add_i32 s3, s47, 0x2000
	ds_read_b128 v[66:69], v142 offset:16384
	ds_read_b128 v[114:117], v142 offset:17408
	ds_read_b128 v[118:121], v142 offset:18432
	ds_read_b128 v[122:125], v142 offset:19456
	ds_read_b128 v[126:129], v142 offset:20480
	ds_read_b128 v[144:147], v142 offset:21504
	ds_read_b128 v[148:151], v142 offset:22528
	ds_read_b128 v[152:155], v142 offset:23552
	global_load_lds_dwordx4 v[2:3], off
	v_lshl_add_u64 v[2:3], s[16:17], 0, v[130:131]
	s_add_u32 s48, s16, 0x18100
	v_lshl_add_u64 v[4:5], v[2:3], 0, s[52:53]
	s_mov_b32 m0, s3
	s_addc_u32 s49, s17, 0
	s_add_i32 s45, s45, s22
	global_load_lds_dwordx4 v[4:5], off
	v_lshl_add_u64 v[4:5], s[48:49], 0, v[134:135]
	s_mov_b32 m0, s45
	s_add_i32 s46, s45, 0x2000
	global_load_lds_dwordx4 v[4:5], off
	v_lshl_add_u64 v[4:5], s[48:49], 0, v[130:131]
	s_mov_b32 m0, s46
	s_nop 0
	global_load_lds_dwordx4 v[4:5], off
	v_lshl_add_u64 v[4:5], s[14:15], 0, v[136:137]
	v_lshl_add_u64 v[6:7], v[4:5], 0, s[52:53]
	s_mov_b32 m0, s23
	s_nop 0
	global_load_lds_dwordx4 v[6:7], off
	v_lshl_add_u64 v[6:7], s[14:15], 0, v[132:133]
	v_lshl_add_u64 v[62:63], v[6:7], 0, s[52:53]
	s_mov_b32 m0, s24
	s_nop 0
	global_load_lds_dwordx4 v[62:63], off
	s_waitcnt vmcnt(8)
	s_waitcnt lgkmcnt(0)
	s_barrier
	s_setprio 1
	v_mfma_f32_16x16x32_bf16 v[156:159], v[10:13], v[66:69], 0
	v_mfma_f32_16x16x32_bf16 v[164:167], v[10:13], v[118:121], 0
	v_mfma_f32_16x16x32_bf16 v[172:175], v[10:13], v[126:129], 0
	v_mfma_f32_16x16x32_bf16 v[10:13], v[10:13], v[148:151], 0
	v_mfma_f32_16x16x32_bf16 v[156:159], v[14:17], v[114:117], v[156:159]
	v_mfma_f32_16x16x32_bf16 v[160:163], v[18:21], v[66:69], 0
	v_mfma_f32_16x16x32_bf16 v[164:167], v[14:17], v[122:125], v[164:167]
	v_mfma_f32_16x16x32_bf16 v[168:171], v[18:21], v[118:121], 0
	v_mfma_f32_16x16x32_bf16 v[172:175], v[14:17], v[144:147], v[172:175]
	v_mfma_f32_16x16x32_bf16 v[176:179], v[18:21], v[126:129], 0
	v_mfma_f32_16x16x32_bf16 v[12:15], v[14:17], v[152:155], v[10:13]
	v_mfma_f32_16x16x32_bf16 v[16:19], v[18:21], v[148:151], 0
	v_mfma_f32_16x16x32_bf16 v[16:19], v[22:25], v[152:155], v[16:19]
	v_mfma_f32_16x16x32_bf16 v[160:163], v[22:25], v[114:117], v[160:163]
	v_mfma_f32_16x16x32_bf16 v[168:171], v[22:25], v[122:125], v[168:171]
	v_mfma_f32_16x16x32_bf16 v[176:179], v[22:25], v[144:147], v[176:179]
	v_mfma_f32_16x16x32_bf16 v[20:23], v[26:29], v[66:69], 0
	v_mfma_f32_16x16x32_bf16 v[66:69], v[34:37], v[66:69], 0
	v_mfma_f32_16x16x32_bf16 v[20:23], v[30:33], v[114:117], v[20:23]
	v_mfma_f32_16x16x32_bf16 v[66:69], v[38:41], v[114:117], v[66:69]
	v_mfma_f32_16x16x32_bf16 v[114:117], v[26:29], v[118:121], 0
	v_mfma_f32_16x16x32_bf16 v[118:121], v[34:37], v[118:121], 0
	v_mfma_f32_16x16x32_bf16 v[114:117], v[30:33], v[122:125], v[114:117]
	v_mfma_f32_16x16x32_bf16 v[118:121], v[38:41], v[122:125], v[118:121]
	v_mfma_f32_16x16x32_bf16 v[122:125], v[26:29], v[126:129], 0
	v_mfma_f32_16x16x32_bf16 v[24:27], v[26:29], v[148:151], 0
	v_mfma_f32_16x16x32_bf16 v[122:125], v[30:33], v[144:147], v[122:125]
	v_mfma_f32_16x16x32_bf16 v[126:129], v[34:37], v[126:129], 0
	v_mfma_f32_16x16x32_bf16 v[24:27], v[30:33], v[152:155], v[24:27]
	v_mfma_f32_16x16x32_bf16 v[28:31], v[34:37], v[148:151], 0
	v_mfma_f32_16x16x32_bf16 v[126:129], v[38:41], v[144:147], v[126:129]
	v_mfma_f32_16x16x32_bf16 v[28:31], v[38:41], v[152:155], v[28:31]
	s_setprio 0
	s_barrier
; #define PG8_STAGE(bufoff, gbase, voff) do { _Pragma("unroll") for (int _i = 0; _i < 2; ++_i) \
;         __builtin_amdgcn_global_load_lds((const unsigned*)((const char*)(gbase) + (voff)[_i]), (PG8_LAS unsigned*)(lds + (bufoff) + ldsw + _i * 8192), 16, 0, 0); } while (0)
; #define PG8_LDA(dst, b, h) do { _Pragma("unroll") for (int m = 0; m < 4; ++m) _Pragma("unroll") for (int k = 0; k < 2; ++k) dst[m][k] = *(const PG8_LAS bf16x8*)(lds + PG8_SA(b, h) + aoff + m * 2048 + k * 1024); } while (0)
; #define PG8_LDB(dst, b, h) do { _Pragma("unroll") for (int n = 0; n < 2; ++n) _Pragma("unroll") for (int k = 0; k < 2; ++k) dst[n][k] = *(const PG8_LAS bf16x8*)(lds + PG8_SB(b, h) + boff + n * 2048 + k * 1024); } while (0)
; #define PG8_MMA(ai, bj, At, Bt) do { __builtin_amdgcn_s_setprio(1); _Pragma("unroll") for (int m = 0; m < 4; ++m) _Pragma("unroll") for (int n = 0; n < 2; ++n) _Pragma("unroll") for (int k = 0; k < 2; ++k) \
;         acc[ai][bj][m][n] = __builtin_amdgcn_mfma_f32_16x16x32_bf16(Bt[n][k], At[m][k], acc[ai][bj][m][n], 0, 0, 0); __builtin_amdgcn_s_setprio(0); } while (0)
; #define PG8_WAIT_V(n) asm volatile("s_waitcnt vmcnt(" #n ")" ::: "memory")
; #define PG8_WAIT_L(n) asm volatile("s_waitcnt lgkmcnt(" #n ")" ::: "memory")
; #define PG8_BAR __builtin_amdgcn_s_barrier()
; #define PG8_SCHED __builtin_amdgcn_sched_barrier(0)
; template <class Epi, class Sched, bool ALIGN_EPI = false, bool SP2 = false>
; __device__ __forceinline__ void gemm_phase(PG8_LAS unsigned char* lds, const Gemm g, const Sched& S, const Epi& E, const int tid) {
;     ...
;             PG8_LDB(B0, 1, 0); PG8_LDB(B1, 1, 1); PG8_SCHED; PG8_LDA(At, 1, 0); PG8_STAGE(PG8_SA(0, 1), a2 + hstep, voffA);
;             PG8_WAIT_V(8); PG8_WAIT_L(0); PG8_BAR; PG8_MMA(0, 0, At, B0); PG8_MMA(0, 1, At, B1); PG8_BAR; PG8_SCHED;
;             PG8_LDA(At, 1, 1); PG8_STAGE(PG8_SB(1, 0), b3, voffB); PG8_STAGE(PG8_SB(1, 1), b3 + hstep, voffB); PG8_STAGE(PG8_SA(1, 0), a3, voffA);
	s_add_i32 s52, 0, 0x18000
	s_add_i32 s51, 0, 0x1c000
	v_add_u32_e32 v10, s52, v141
	v_add_u32_e32 v11, s51, v141
	ds_read_b128 v[32:35], v10
	ds_read_b128 v[36:39], v10 offset:1024
	ds_read_b128 v[144:147], v10 offset:2048
	ds_read_b128 v[148:151], v10 offset:3072
	ds_read_b128 v[152:155], v11
	ds_read_b128 v[180:183], v11 offset:1024
	ds_read_b128 v[184:187], v11 offset:2048
	ds_read_b128 v[188:191], v11 offset:3072
	s_add_u32 s48, s14, 0x18100
	s_addc_u32 s49, s15, 0
	s_mov_b32 m0, s25
	v_lshl_add_u64 v[40:41], s[48:49], 0, v[136:137]
	ds_read_b128 v[192:195], v142 offset:32768
	ds_read_b128 v[196:199], v142 offset:33792
	ds_read_b128 v[214:217], v142 offset:34816
	ds_read_b128 v[218:221], v142 offset:35840
	ds_read_b128 v[222:225], v142 offset:36864
	ds_read_b128 v[226:229], v142 offset:37888
	ds_read_b128 v[248:251], v142 offset:38912
	ds_read_b128 v[206:209], v142 offset:39936
	global_load_lds_dwordx4 v[40:41], off
	v_lshl_add_u64 v[40:41], s[48:49], 0, v[132:133]
	s_mov_b32 m0, s26
	s_nop 0
	global_load_lds_dwordx4 v[40:41], off
	s_waitcnt vmcnt(8)
	s_waitcnt lgkmcnt(0)
	s_barrier
	s_setprio 1
	v_mfma_f32_16x16x32_bf16 v[70:73], v[32:35], v[192:195], v[70:73]
	v_mfma_f32_16x16x32_bf16 v[74:77], v[144:147], v[192:195], v[74:77]
	v_mfma_f32_16x16x32_bf16 v[78:81], v[32:35], v[214:217], v[78:81]
	v_mfma_f32_16x16x32_bf16 v[82:85], v[144:147], v[214:217], v[82:85]
	v_mfma_f32_16x16x32_bf16 v[86:89], v[32:35], v[222:225], v[86:89]
	v_mfma_f32_16x16x32_bf16 v[90:93], v[144:147], v[222:225], v[90:93]
	v_mfma_f32_16x16x32_bf16 v[94:97], v[32:35], v[248:251], v[94:97]
	v_mfma_f32_16x16x32_bf16 v[98:101], v[144:147], v[248:251], v[98:101]
	v_mfma_f32_16x16x32_bf16 v[70:73], v[36:39], v[196:199], v[70:73]
	v_mfma_f32_16x16x32_bf16 v[74:77], v[148:151], v[196:199], v[74:77]
	v_mfma_f32_16x16x32_bf16 v[78:81], v[36:39], v[218:221], v[78:81]
	v_mfma_f32_16x16x32_bf16 v[82:85], v[148:151], v[218:221], v[82:85]
	v_mfma_f32_16x16x32_bf16 v[86:89], v[36:39], v[226:229], v[86:89]
	v_mfma_f32_16x16x32_bf16 v[90:93], v[148:151], v[226:229], v[90:93]
	v_mfma_f32_16x16x32_bf16 v[94:97], v[36:39], v[206:209], v[94:97]
	v_mfma_f32_16x16x32_bf16 v[98:101], v[148:151], v[206:209], v[98:101]
	v_mfma_f32_16x16x32_bf16 v[102:105], v[152:155], v[192:195], v[102:105]
	v_mfma_f32_16x16x32_bf16 v[106:109], v[184:187], v[192:195], v[106:109]
	v_mfma_f32_16x16x32_bf16 v[110:113], v[152:155], v[214:217], v[110:113]
	v_mfma_f32_16x16x32_bf16 v[40:43], v[184:187], v[214:217], v[42:45]
	v_mfma_f32_16x16x32_bf16 v[44:47], v[152:155], v[222:225], v[46:49]
	v_mfma_f32_16x16x32_bf16 v[48:51], v[184:187], v[222:225], v[50:53]
	v_mfma_f32_16x16x32_bf16 v[52:55], v[152:155], v[248:251], v[54:57]
	v_mfma_f32_16x16x32_bf16 v[56:59], v[184:187], v[248:251], v[58:61]
	v_mfma_f32_16x16x32_bf16 v[102:105], v[180:183], v[196:199], v[102:105]
	v_mfma_f32_16x16x32_bf16 v[106:109], v[188:191], v[196:199], v[106:109]
	v_mfma_f32_16x16x32_bf16 v[110:113], v[180:183], v[218:221], v[110:113]
	v_mfma_f32_16x16x32_bf16 v[40:43], v[188:191], v[218:221], v[40:43]
	v_mfma_f32_16x16x32_bf16 v[44:47], v[180:183], v[226:229], v[44:47]
	v_mfma_f32_16x16x32_bf16 v[48:51], v[188:191], v[226:229], v[48:51]
	v_mfma_f32_16x16x32_bf16 v[52:55], v[180:183], v[206:209], v[52:55]
	v_mfma_f32_16x16x32_bf16 v[56:59], v[188:191], v[206:209], v[56:59]
	s_setprio 0
	s_barrier
	s_add_i32 s52, s52, s22
	s_mov_b64 s[56:57], 0x180
	s_add_i32 s48, s52, 0x2000
	v_lshl_add_u64 v[138:139], v[0:1], 0, s[56:57]
	s_mov_b32 m0, s52
	s_add_u32 s54, s16, 0x18180
	ds_read_b128 v[60:63], v142 offset:49152
	ds_read_b128 v[192:195], v142 offset:50176
	ds_read_b128 v[196:199], v142 offset:51200
	ds_read_b128 v[206:209], v142 offset:52224
	ds_read_b128 v[214:217], v142 offset:53248
	ds_read_b128 v[218:221], v142 offset:54272
	ds_read_b128 v[222:225], v142 offset:55296
	ds_read_b128 v[226:229], v142 offset:56320
	global_load_lds_dwordx4 v[138:139], off
	v_lshl_add_u64 v[138:139], v[2:3], 0, s[56:57]
	s_mov_b32 m0, s48
	s_addc_u32 s55, s17, 0
	s_add_i32 s49, s51, s22
	global_load_lds_dwordx4 v[138:139], off
	v_lshl_add_u64 v[138:139], s[54:55], 0, v[134:135]
	s_mov_b32 m0, s49
	s_add_i32 s51, s49, 0x2000
	global_load_lds_dwordx4 v[138:139], off
	v_lshl_add_u64 v[138:139], s[54:55], 0, v[130:131]
	s_mov_b32 m0, s51
	s_nop 0
	global_load_lds_dwordx4 v[138:139], off
	v_lshl_add_u64 v[138:139], v[4:5], 0, s[56:57]
	s_mov_b32 m0, s28
	s_nop 0
	global_load_lds_dwordx4 v[138:139], off
	v_lshl_add_u64 v[138:139], v[6:7], 0, s[56:57]
	s_mov_b32 m0, s29
	s_nop 0
	global_load_lds_dwordx4 v[138:139], off
	s_waitcnt vmcnt(8)
	s_waitcnt lgkmcnt(0)
	s_barrier
; #define PG8_STAGE(bufoff, gbase, voff) do { _Pragma("unroll") for (int _i = 0; _i < 2; ++_i) \
;         __builtin_amdgcn_global_load_lds((const unsigned*)((const char*)(gbase) + (voff)[_i]), (PG8_LAS unsigned*)(lds + (bufoff) + ldsw + _i * 8192), 16, 0, 0); } while (0)
; #define PG8_LDA(dst, b, h) do { _Pragma("unroll") for (int m = 0; m < 4; ++m) _Pragma("unroll") for (int k = 0; k < 2; ++k) dst[m][k] = *(const PG8_LAS bf16x8*)(lds + PG8_SA(b, h) + aoff + m * 2048 + k * 1024); } while (0)
; #define PG8_LDB(dst, b, h) do { _Pragma("unroll") for (int n = 0; n < 2; ++n) _Pragma("unroll") for (int k = 0; k < 2; ++k) dst[n][k] = *(const PG8_LAS bf16x8*)(lds + PG8_SB(b, h) + boff + n * 2048 + k * 1024); } while (0)
; #define PG8_MMA(ai, bj, At, Bt) do { __builtin_amdgcn_s_setprio(1); _Pragma("unroll") for (int m = 0; m < 4; ++m) _Pragma("unroll") for (int n = 0; n < 2; ++n) _Pragma("unroll") for (int k = 0; k < 2; ++k) \
;         acc[ai][bj][m][n] = __builtin_amdgcn_mfma_f32_16x16x32_bf16(Bt[n][k], At[m][k], acc[ai][bj][m][n], 0, 0, 0); __builtin_amdgcn_s_setprio(0); } while (0)
; #define PG8_BAR __builtin_amdgcn_s_barrier()
; template <class Epi, class Sched, bool ALIGN_EPI = false, bool SP2 = false>
; __device__ __forceinline__ void gemm_phase(PG8_LAS unsigned char* lds, const Gemm g, const Sched& S, const Epi& E, const int tid) {
;     ...
;             PG8_LDB(B0, 0, 0); PG8_LDB(B1, 0, 1); PG8_SCHED; PG8_LDA(At, 0, 0); PG8_STAGE(PG8_SA(1, 1), a1 + hstep, voffA);
;             PG8_WAIT_V(8); PG8_WAIT_L(0); PG8_BAR; PG8_MMA(0, 0, At, B0); PG8_MMA(0, 1, At, B1); PG8_BAR; PG8_SCHED;
;             PG8_LDA(At, 0, 1); PG8_STAGE(PG8_SB(0, 0), b2, voffB); PG8_STAGE(PG8_SB(0, 1), b2 + hstep, voffB); PG8_STAGE(PG8_SA(0, 0), a2, voffA);
;             PG8_WAIT_V(8); PG8_WAIT_L(0); PG8_BAR; PG8_MMA(1, 0, At, B0); PG8_MMA(1, 1, At, B1); PG8_BAR; PG8_SCHED;
;             PG8_LDB(B0, 1, 0); PG8_LDB(B1, 1, 1); PG8_SCHED; PG8_LDA(At, 1, 0); PG8_STAGE(PG8_SA(0, 1), a2 + hstep, voffA);
;             PG8_WAIT_V(8); PG8_WAIT_L(0); PG8_BAR; PG8_MMA(0, 0, At, B0); PG8_MMA(0, 1, At, B1); PG8_BAR; PG8_SCHED;
;             PG8_LDA(At, 1, 1); PG8_STAGE(PG8_SB(1, 0), b3, voffB); PG8_STAGE(PG8_SB(1, 1), b3 + hstep, voffB); PG8_STAGE(PG8_SA(1, 0), a3, voffA);
;             PG8_WAIT_V(8); PG8_WAIT_L(0); PG8_BAR; PG8_MMA(1, 0, At, B0); PG8_MMA(1, 1, At, B1); PG8_BAR; PG8_SCHED;
	s_setprio 1
	v_mfma_f32_16x16x32_bf16 v[12:15], v[32:35], v[222:225], v[12:15]
	v_mfma_f32_16x16x32_bf16 v[16:19], v[144:147], v[222:225], v[16:19]
	v_mfma_f32_16x16x32_bf16 v[156:159], v[32:35], v[60:63], v[156:159]
	v_mfma_f32_16x16x32_bf16 v[160:163], v[144:147], v[60:63], v[160:163]
	v_mfma_f32_16x16x32_bf16 v[164:167], v[32:35], v[196:199], v[164:167]
	v_mfma_f32_16x16x32_bf16 v[168:171], v[144:147], v[196:199], v[168:171]
	v_mfma_f32_16x16x32_bf16 v[172:175], v[32:35], v[214:217], v[172:175]
	v_mfma_f32_16x16x32_bf16 v[176:179], v[144:147], v[214:217], v[176:179]
	v_mfma_f32_16x16x32_bf16 v[12:15], v[36:39], v[226:229], v[12:15]
	v_mfma_f32_16x16x32_bf16 v[16:19], v[148:151], v[226:229], v[16:19]
	v_mfma_f32_16x16x32_bf16 v[156:159], v[36:39], v[192:195], v[156:159]
	v_mfma_f32_16x16x32_bf16 v[160:163], v[148:151], v[192:195], v[160:163]
	v_mfma_f32_16x16x32_bf16 v[164:167], v[36:39], v[206:209], v[164:167]
	v_mfma_f32_16x16x32_bf16 v[168:171], v[148:151], v[206:209], v[168:171]
	v_mfma_f32_16x16x32_bf16 v[172:175], v[36:39], v[218:221], v[172:175]
	v_mfma_f32_16x16x32_bf16 v[176:179], v[148:151], v[218:221], v[176:179]
	v_mfma_f32_16x16x32_bf16 v[20:23], v[152:155], v[60:63], v[20:23]
	v_mfma_f32_16x16x32_bf16 v[32:35], v[184:187], v[60:63], v[66:69]
	v_mfma_f32_16x16x32_bf16 v[36:39], v[152:155], v[196:199], v[114:117]
	v_mfma_f32_16x16x32_bf16 v[60:63], v[184:187], v[196:199], v[118:121]
	v_mfma_f32_16x16x32_bf16 v[66:69], v[152:155], v[214:217], v[122:125]
	v_mfma_f32_16x16x32_bf16 v[114:117], v[184:187], v[214:217], v[126:129]
	v_mfma_f32_16x16x32_bf16 v[24:27], v[152:155], v[222:225], v[24:27]
	v_mfma_f32_16x16x32_bf16 v[28:31], v[184:187], v[222:225], v[28:31]
	v_mfma_f32_16x16x32_bf16 v[20:23], v[180:183], v[192:195], v[20:23]
	v_mfma_f32_16x16x32_bf16 v[32:35], v[188:191], v[192:195], v[32:35]
	v_mfma_f32_16x16x32_bf16 v[36:39], v[180:183], v[206:209], v[36:39]
	v_mfma_f32_16x16x32_bf16 v[60:63], v[188:191], v[206:209], v[60:63]
	v_mfma_f32_16x16x32_bf16 v[66:69], v[180:183], v[218:221], v[66:69]
	v_mfma_f32_16x16x32_bf16 v[114:117], v[188:191], v[218:221], v[114:117]
	v_mfma_f32_16x16x32_bf16 v[24:27], v[180:183], v[226:229], v[24:27]
	v_mfma_f32_16x16x32_bf16 v[28:31], v[188:191], v[226:229], v[28:31]
	s_setprio 0
	s_barrier
	ds_read_b128 v[118:121], v8
	ds_read_b128 v[122:125], v8 offset:1024
	ds_read_b128 v[126:129], v8 offset:2048
	ds_read_b128 v[144:147], v8 offset:3072
	ds_read_b128 v[148:151], v9
	ds_read_b128 v[152:155], v9 offset:1024
	ds_read_b128 v[180:183], v9 offset:2048
	ds_read_b128 v[184:187], v9 offset:3072
	s_add_u32 s54, s14, 0x18180
	s_addc_u32 s55, s15, 0
	s_mov_b32 m0, s50
	v_lshl_add_u64 v[138:139], s[54:55], 0, v[136:137]
	ds_read_b128 v[188:191], v142
	ds_read_b128 v[192:195], v142 offset:1024
	ds_read_b128 v[196:199], v142 offset:2048
	ds_read_b128 v[206:209], v142 offset:3072
	ds_read_b128 v[214:217], v142 offset:4096
	ds_read_b128 v[218:221], v142 offset:5120
	ds_read_b128 v[222:225], v142 offset:6144
	ds_read_b128 v[226:229], v142 offset:7168
	global_load_lds_dwordx4 v[138:139], off
	v_lshl_add_u64 v[138:139], s[54:55], 0, v[132:133]
	s_mov_b32 m0, s2
	s_nop 0
	global_load_lds_dwordx4 v[138:139], off
	s_waitcnt vmcnt(8)
	s_waitcnt lgkmcnt(0)
	s_barrier
	s_setprio 1
	v_mfma_f32_16x16x32_bf16 v[70:73], v[118:121], v[188:191], v[70:73]
	v_mfma_f32_16x16x32_bf16 v[74:77], v[126:129], v[188:191], v[74:77]
	v_mfma_f32_16x16x32_bf16 v[78:81], v[118:121], v[196:199], v[78:81]
	v_mfma_f32_16x16x32_bf16 v[82:85], v[126:129], v[196:199], v[82:85]
	v_mfma_f32_16x16x32_bf16 v[86:89], v[118:121], v[214:217], v[86:89]
	v_mfma_f32_16x16x32_bf16 v[90:93], v[126:129], v[214:217], v[90:93]
	v_mfma_f32_16x16x32_bf16 v[94:97], v[118:121], v[222:225], v[94:97]
	v_mfma_f32_16x16x32_bf16 v[98:101], v[126:129], v[222:225], v[98:101]
	v_mfma_f32_16x16x32_bf16 v[70:73], v[122:125], v[192:195], v[70:73]
	v_mfma_f32_16x16x32_bf16 v[74:77], v[144:147], v[192:195], v[74:77]
	v_mfma_f32_16x16x32_bf16 v[78:81], v[122:125], v[206:209], v[78:81]
	v_mfma_f32_16x16x32_bf16 v[82:85], v[144:147], v[206:209], v[82:85]
	v_mfma_f32_16x16x32_bf16 v[86:89], v[122:125], v[218:221], v[86:89]
	v_mfma_f32_16x16x32_bf16 v[90:93], v[144:147], v[218:221], v[90:93]
	v_mfma_f32_16x16x32_bf16 v[94:97], v[122:125], v[226:229], v[94:97]
	v_mfma_f32_16x16x32_bf16 v[98:101], v[144:147], v[226:229], v[98:101]
	v_mfma_f32_16x16x32_bf16 v[102:105], v[148:151], v[188:191], v[102:105]
	v_mfma_f32_16x16x32_bf16 v[106:109], v[180:183], v[188:191], v[106:109]
	v_mfma_f32_16x16x32_bf16 v[110:113], v[148:151], v[196:199], v[110:113]
	v_mfma_f32_16x16x32_bf16 v[40:43], v[180:183], v[196:199], v[40:43]
	v_mfma_f32_16x16x32_bf16 v[44:47], v[148:151], v[214:217], v[44:47]
	v_mfma_f32_16x16x32_bf16 v[48:51], v[180:183], v[214:217], v[48:51]
	v_mfma_f32_16x16x32_bf16 v[52:55], v[148:151], v[222:225], v[52:55]
	v_mfma_f32_16x16x32_bf16 v[56:59], v[180:183], v[222:225], v[56:59]
	v_mfma_f32_16x16x32_bf16 v[102:105], v[152:155], v[192:195], v[102:105]
	v_mfma_f32_16x16x32_bf16 v[106:109], v[184:187], v[192:195], v[106:109]
	v_mfma_f32_16x16x32_bf16 v[110:113], v[152:155], v[206:209], v[110:113]
	v_mfma_f32_16x16x32_bf16 v[40:43], v[184:187], v[206:209], v[40:43]
	v_mfma_f32_16x16x32_bf16 v[44:47], v[152:155], v[218:221], v[44:47]
	v_mfma_f32_16x16x32_bf16 v[48:51], v[184:187], v[218:221], v[48:51]
	v_mfma_f32_16x16x32_bf16 v[52:55], v[152:155], v[226:229], v[52:55]
	v_mfma_f32_16x16x32_bf16 v[56:59], v[184:187], v[226:229], v[56:59]
	s_setprio 0
	s_barrier
; #define PG8_STAGE(bufoff, gbase, voff) do { _Pragma("unroll") for (int _i = 0; _i < 2; ++_i) \
;         __builtin_amdgcn_global_load_lds((const unsigned*)((const char*)(gbase) + (voff)[_i]), (PG8_LAS unsigned*)(lds + (bufoff) + ldsw + _i * 8192), 16, 0, 0); } while (0)
; #define PG8_LDA(dst, b, h) do { _Pragma("unroll") for (int m = 0; m < 4; ++m) _Pragma("unroll") for (int k = 0; k < 2; ++k) dst[m][k] = *(const PG8_LAS bf16x8*)(lds + PG8_SA(b, h) + aoff + m * 2048 + k * 1024); } while (0)
; #define PG8_LDB(dst, b, h) do { _Pragma("unroll") for (int n = 0; n < 2; ++n) _Pragma("unroll") for (int k = 0; k < 2; ++k) dst[n][k] = *(const PG8_LAS bf16x8*)(lds + PG8_SB(b, h) + boff + n * 2048 + k * 1024); } while (0)
; #define PG8_MMA(ai, bj, At, Bt) do { __builtin_amdgcn_s_setprio(1); _Pragma("unroll") for (int m = 0; m < 4; ++m) _Pragma("unroll") for (int n = 0; n < 2; ++n) _Pragma("unroll") for (int k = 0; k < 2; ++k) \
;         acc[ai][bj][m][n] = __builtin_amdgcn_mfma_f32_16x16x32_bf16(Bt[n][k], At[m][k], acc[ai][bj][m][n], 0, 0, 0); __builtin_amdgcn_s_setprio(0); } while (0)
; #define PG8_WAIT_V(n) asm volatile("s_waitcnt vmcnt(" #n ")" ::: "memory")
; #define PG8_WAIT_L(n) asm volatile("s_waitcnt lgkmcnt(" #n ")" ::: "memory")
; #define PG8_BAR __builtin_amdgcn_s_barrier()
; #define PG8_SCHED __builtin_amdgcn_sched_barrier(0)
; template <class Epi, class Sched, bool ALIGN_EPI = false, bool SP2 = false>
; __device__ __forceinline__ void gemm_phase(PG8_LAS unsigned char* lds, const Gemm g, const Sched& S, const Epi& E, const int tid) {
;     ...
;             PG8_LDA(At, 0, 1); PG8_STAGE(PG8_SB(0, 0), b2, voffB); PG8_STAGE(PG8_SB(0, 1), b2 + hstep, voffB); PG8_STAGE(PG8_SA(0, 0), a2, voffA);
;             PG8_WAIT_V(8); PG8_WAIT_L(0); PG8_BAR; PG8_MMA(1, 0, At, B0); PG8_MMA(1, 1, At, B1); PG8_BAR; PG8_SCHED;
;             PG8_LDB(B0, 1, 0); PG8_LDB(B1, 1, 1); PG8_SCHED; PG8_LDA(At, 1, 0); PG8_STAGE(PG8_SA(0, 1), a2 + hstep, voffA);
;             PG8_WAIT_V(8); PG8_WAIT_L(0); PG8_BAR; PG8_MMA(0, 0, At, B0); PG8_MMA(0, 1, At, B1); PG8_BAR; PG8_SCHED;
	s_mov_b64 s[56:57], 0x200
	s_mov_b32 m0, s47
	v_lshl_add_u64 v[138:139], v[0:1], 0, s[56:57]
	s_add_u32 s54, s16, 0x18200
	ds_read_b128 v[188:191], v142 offset:16384
	ds_read_b128 v[192:195], v142 offset:17408
	ds_read_b128 v[196:199], v142 offset:18432
	ds_read_b128 v[206:209], v142 offset:19456
	ds_read_b128 v[214:217], v142 offset:20480
	ds_read_b128 v[218:221], v142 offset:21504
	ds_read_b128 v[222:225], v142 offset:22528
	ds_read_b128 v[226:229], v142 offset:23552
	global_load_lds_dwordx4 v[138:139], off
	v_lshl_add_u64 v[138:139], v[2:3], 0, s[56:57]
	s_mov_b32 m0, s3
	s_addc_u32 s55, s17, 0
	global_load_lds_dwordx4 v[138:139], off
	v_lshl_add_u64 v[138:139], s[54:55], 0, v[134:135]
	s_mov_b32 m0, s45
	s_nop 0
	global_load_lds_dwordx4 v[138:139], off
	v_lshl_add_u64 v[138:139], s[54:55], 0, v[130:131]
	s_mov_b32 m0, s46
	s_nop 0
	global_load_lds_dwordx4 v[138:139], off
	v_lshl_add_u64 v[138:139], v[4:5], 0, s[56:57]
	s_mov_b32 m0, s23
	s_nop 0
	global_load_lds_dwordx4 v[138:139], off
	v_lshl_add_u64 v[138:139], v[6:7], 0, s[56:57]
	s_mov_b32 m0, s24
	s_nop 0
	global_load_lds_dwordx4 v[138:139], off
	s_waitcnt vmcnt(8)
	s_waitcnt lgkmcnt(0)
	s_barrier
	s_setprio 1
	v_mfma_f32_16x16x32_bf16 v[12:15], v[118:121], v[222:225], v[12:15]
	v_mfma_f32_16x16x32_bf16 v[16:19], v[126:129], v[222:225], v[16:19]
	v_mfma_f32_16x16x32_bf16 v[156:159], v[118:121], v[188:191], v[156:159]
	v_mfma_f32_16x16x32_bf16 v[160:163], v[126:129], v[188:191], v[160:163]
	v_mfma_f32_16x16x32_bf16 v[164:167], v[118:121], v[196:199], v[164:167]
	v_mfma_f32_16x16x32_bf16 v[168:171], v[126:129], v[196:199], v[168:171]
	v_mfma_f32_16x16x32_bf16 v[172:175], v[118:121], v[214:217], v[172:175]
	v_mfma_f32_16x16x32_bf16 v[176:179], v[126:129], v[214:217], v[176:179]
	v_mfma_f32_16x16x32_bf16 v[12:15], v[122:125], v[226:229], v[12:15]
	v_mfma_f32_16x16x32_bf16 v[16:19], v[144:147], v[226:229], v[16:19]
	v_mfma_f32_16x16x32_bf16 v[156:159], v[122:125], v[192:195], v[156:159]
	v_mfma_f32_16x16x32_bf16 v[160:163], v[144:147], v[192:195], v[160:163]
	v_mfma_f32_16x16x32_bf16 v[164:167], v[122:125], v[206:209], v[164:167]
	v_mfma_f32_16x16x32_bf16 v[168:171], v[144:147], v[206:209], v[168:171]
	v_mfma_f32_16x16x32_bf16 v[172:175], v[122:125], v[218:221], v[172:175]
	v_mfma_f32_16x16x32_bf16 v[176:179], v[144:147], v[218:221], v[176:179]
	v_mfma_f32_16x16x32_bf16 v[20:23], v[148:151], v[188:191], v[20:23]
	v_mfma_f32_16x16x32_bf16 v[32:35], v[180:183], v[188:191], v[32:35]
	v_mfma_f32_16x16x32_bf16 v[36:39], v[148:151], v[196:199], v[36:39]
	v_mfma_f32_16x16x32_bf16 v[60:63], v[180:183], v[196:199], v[60:63]
	v_mfma_f32_16x16x32_bf16 v[66:69], v[148:151], v[214:217], v[66:69]
	v_mfma_f32_16x16x32_bf16 v[114:117], v[180:183], v[214:217], v[114:117]
	v_mfma_f32_16x16x32_bf16 v[24:27], v[148:151], v[222:225], v[24:27]
	v_mfma_f32_16x16x32_bf16 v[28:31], v[180:183], v[222:225], v[28:31]
	v_mfma_f32_16x16x32_bf16 v[20:23], v[152:155], v[192:195], v[20:23]
	v_mfma_f32_16x16x32_bf16 v[32:35], v[184:187], v[192:195], v[32:35]
	v_mfma_f32_16x16x32_bf16 v[36:39], v[152:155], v[206:209], v[36:39]
	v_mfma_f32_16x16x32_bf16 v[60:63], v[184:187], v[206:209], v[60:63]
	v_mfma_f32_16x16x32_bf16 v[66:69], v[152:155], v[218:221], v[66:69]
	v_mfma_f32_16x16x32_bf16 v[114:117], v[184:187], v[218:221], v[114:117]
	v_mfma_f32_16x16x32_bf16 v[24:27], v[152:155], v[226:229], v[24:27]
	v_mfma_f32_16x16x32_bf16 v[28:31], v[184:187], v[226:229], v[28:31]
	s_setprio 0
	s_barrier
	ds_read_b128 v[118:121], v10
	ds_read_b128 v[122:125], v10 offset:1024
	ds_read_b128 v[126:129], v10 offset:2048
	ds_read_b128 v[144:147], v10 offset:3072
	ds_read_b128 v[148:151], v11
	ds_read_b128 v[152:155], v11 offset:1024
	ds_read_b128 v[180:183], v11 offset:2048
	ds_read_b128 v[184:187], v11 offset:3072
	s_add_u32 s54, s14, 0x18200
	s_addc_u32 s55, s15, 0
	s_mov_b32 m0, s25
	v_lshl_add_u64 v[138:139], s[54:55], 0, v[136:137]
	ds_read_b128 v[188:191], v142 offset:32768
	ds_read_b128 v[192:195], v142 offset:33792
	ds_read_b128 v[196:199], v142 offset:34816
	ds_read_b128 v[206:209], v142 offset:35840
	ds_read_b128 v[214:217], v142 offset:36864
	ds_read_b128 v[218:221], v142 offset:37888
	ds_read_b128 v[222:225], v142 offset:38912
	ds_read_b128 v[226:229], v142 offset:39936
	global_load_lds_dwordx4 v[138:139], off
	v_lshl_add_u64 v[138:139], s[54:55], 0, v[132:133]
	s_mov_b32 m0, s26
	s_nop 0
	global_load_lds_dwordx4 v[138:139], off
	s_waitcnt vmcnt(8)
	s_waitcnt lgkmcnt(0)
	s_barrier
	s_setprio 1
	v_mfma_f32_16x16x32_bf16 v[70:73], v[118:121], v[188:191], v[70:73]
	v_mfma_f32_16x16x32_bf16 v[74:77], v[126:129], v[188:191], v[74:77]
	v_mfma_f32_16x16x32_bf16 v[78:81], v[118:121], v[196:199], v[78:81]
	v_mfma_f32_16x16x32_bf16 v[82:85], v[126:129], v[196:199], v[82:85]
	v_mfma_f32_16x16x32_bf16 v[86:89], v[118:121], v[214:217], v[86:89]
	v_mfma_f32_16x16x32_bf16 v[90:93], v[126:129], v[214:217], v[90:93]
	v_mfma_f32_16x16x32_bf16 v[94:97], v[118:121], v[222:225], v[94:97]
	v_mfma_f32_16x16x32_bf16 v[98:101], v[126:129], v[222:225], v[98:101]
	v_mfma_f32_16x16x32_bf16 v[70:73], v[122:125], v[192:195], v[70:73]
	v_mfma_f32_16x16x32_bf16 v[74:77], v[144:147], v[192:195], v[74:77]
	v_mfma_f32_16x16x32_bf16 v[78:81], v[122:125], v[206:209], v[78:81]
	v_mfma_f32_16x16x32_bf16 v[82:85], v[144:147], v[206:209], v[82:85]
	v_mfma_f32_16x16x32_bf16 v[86:89], v[122:125], v[218:221], v[86:89]
	v_mfma_f32_16x16x32_bf16 v[90:93], v[144:147], v[218:221], v[90:93]
	v_mfma_f32_16x16x32_bf16 v[94:97], v[122:125], v[226:229], v[94:97]
	v_mfma_f32_16x16x32_bf16 v[98:101], v[144:147], v[226:229], v[98:101]
	v_mfma_f32_16x16x32_bf16 v[102:105], v[148:151], v[188:191], v[102:105]
	v_mfma_f32_16x16x32_bf16 v[106:109], v[180:183], v[188:191], v[106:109]
	v_mfma_f32_16x16x32_bf16 v[110:113], v[148:151], v[196:199], v[110:113]
	v_mfma_f32_16x16x32_bf16 v[40:43], v[180:183], v[196:199], v[40:43]
	v_mfma_f32_16x16x32_bf16 v[44:47], v[148:151], v[214:217], v[44:47]
	v_mfma_f32_16x16x32_bf16 v[48:51], v[180:183], v[214:217], v[48:51]
	v_mfma_f32_16x16x32_bf16 v[52:55], v[148:151], v[222:225], v[52:55]
	v_mfma_f32_16x16x32_bf16 v[56:59], v[180:183], v[222:225], v[56:59]
	v_mfma_f32_16x16x32_bf16 v[102:105], v[152:155], v[192:195], v[102:105]
	v_mfma_f32_16x16x32_bf16 v[106:109], v[184:187], v[192:195], v[106:109]
	v_mfma_f32_16x16x32_bf16 v[110:113], v[152:155], v[206:209], v[110:113]
	v_mfma_f32_16x16x32_bf16 v[40:43], v[184:187], v[206:209], v[40:43]
	v_mfma_f32_16x16x32_bf16 v[44:47], v[152:155], v[218:221], v[44:47]
	v_mfma_f32_16x16x32_bf16 v[48:51], v[184:187], v[218:221], v[48:51]
	v_mfma_f32_16x16x32_bf16 v[52:55], v[152:155], v[226:229], v[52:55]
	v_mfma_f32_16x16x32_bf16 v[56:59], v[184:187], v[226:229], v[56:59]
	s_setprio 0
	s_barrier
; #define PG8_STAGE(bufoff, gbase, voff) do { _Pragma("unroll") for (int _i = 0; _i < 2; ++_i) \
;         __builtin_amdgcn_global_load_lds((const unsigned*)((const char*)(gbase) + (voff)[_i]), (PG8_LAS unsigned*)(lds + (bufoff) + ldsw + _i * 8192), 16, 0, 0); } while (0)
; #define PG8_LDA(dst, b, h) do { _Pragma("unroll") for (int m = 0; m < 4; ++m) _Pragma("unroll") for (int k = 0; k < 2; ++k) dst[m][k] = *(const PG8_LAS bf16x8*)(lds + PG8_SA(b, h) + aoff + m * 2048 + k * 1024); } while (0)
; #define PG8_LDB(dst, b, h) do { _Pragma("unroll") for (int n = 0; n < 2; ++n) _Pragma("unroll") for (int k = 0; k < 2; ++k) dst[n][k] = *(const PG8_LAS bf16x8*)(lds + PG8_SB(b, h) + boff + n * 2048 + k * 1024); } while (0)
; #define PG8_MMA(ai, bj, At, Bt) do { __builtin_amdgcn_s_setprio(1); _Pragma("unroll") for (int m = 0; m < 4; ++m) _Pragma("unroll") for (int n = 0; n < 2; ++n) _Pragma("unroll") for (int k = 0; k < 2; ++k) \
;         acc[ai][bj][m][n] = __builtin_amdgcn_mfma_f32_16x16x32_bf16(Bt[n][k], At[m][k], acc[ai][bj][m][n], 0, 0, 0); __builtin_amdgcn_s_setprio(0); } while (0)
; #define PG8_BAR __builtin_amdgcn_s_barrier()
; template <class Epi, class Sched, bool ALIGN_EPI = false, bool SP2 = false>
; __device__ __forceinline__ void gemm_phase(PG8_LAS unsigned char* lds, const Gemm g, const Sched& S, const Epi& E, const int tid) {
;     ...
;             PG8_LDB(B0, 0, 0); PG8_LDB(B1, 0, 1); PG8_SCHED; PG8_LDA(At, 0, 0); PG8_STAGE(PG8_SA(1, 1), a1 + hstep, voffA);
;             PG8_WAIT_V(8); PG8_WAIT_L(0); PG8_BAR; PG8_MMA(0, 0, At, B0); PG8_MMA(0, 1, At, B1); PG8_BAR; PG8_SCHED;
;             PG8_LDA(At, 0, 1); PG8_STAGE(PG8_SB(0, 0), b2, voffB); PG8_STAGE(PG8_SB(0, 1), b2 + hstep, voffB); PG8_STAGE(PG8_SA(0, 0), a2, voffA);
;             PG8_WAIT_V(8); PG8_WAIT_L(0); PG8_BAR; PG8_MMA(1, 0, At, B0); PG8_MMA(1, 1, At, B1); PG8_BAR; PG8_SCHED;
;             PG8_LDB(B0, 1, 0); PG8_LDB(B1, 1, 1); PG8_SCHED; PG8_LDA(At, 1, 0); PG8_STAGE(PG8_SA(0, 1), a2 + hstep, voffA);
;             PG8_WAIT_V(8); PG8_WAIT_L(0); PG8_BAR; PG8_MMA(0, 0, At, B0); PG8_MMA(0, 1, At, B1); PG8_BAR; PG8_SCHED;
;             PG8_LDA(At, 1, 1); PG8_STAGE(PG8_SB(1, 0), b3, voffB); PG8_STAGE(PG8_SB(1, 1), b3 + hstep, voffB); PG8_STAGE(PG8_SA(1, 0), a3, voffA);
;             PG8_WAIT_V(8); PG8_WAIT_L(0); PG8_BAR; PG8_MMA(1, 0, At, B0); PG8_MMA(1, 1, At, B1); PG8_BAR; PG8_SCHED;
	s_mov_b64 s[54:55], 0x280
	s_mov_b32 m0, s52
	v_lshl_add_u64 v[0:1], v[0:1], 0, s[54:55]
	s_add_u32 s16, s16, 0x18280
	ds_read_b128 v[188:191], v142 offset:49152
	ds_read_b128 v[192:195], v142 offset:50176
	ds_read_b128 v[196:199], v142 offset:51200
	ds_read_b128 v[206:209], v142 offset:52224
	ds_read_b128 v[214:217], v142 offset:53248
	ds_read_b128 v[218:221], v142 offset:54272
	ds_read_b128 v[222:225], v142 offset:55296
	ds_read_b128 v[226:229], v142 offset:56320
	global_load_lds_dwordx4 v[0:1], off
	v_lshl_add_u64 v[0:1], v[2:3], 0, s[54:55]
	s_mov_b32 m0, s48
	s_addc_u32 s17, s17, 0
	global_load_lds_dwordx4 v[0:1], off
	v_lshl_add_u64 v[0:1], s[16:17], 0, v[134:135]
	s_mov_b32 m0, s49
	s_nop 0
	global_load_lds_dwordx4 v[0:1], off
	v_lshl_add_u64 v[0:1], s[16:17], 0, v[130:131]
	s_mov_b32 m0, s51
	s_nop 0
	global_load_lds_dwordx4 v[0:1], off
	v_lshl_add_u64 v[0:1], v[4:5], 0, s[54:55]
	s_mov_b32 m0, s28
	s_nop 0
	global_load_lds_dwordx4 v[0:1], off
	v_lshl_add_u64 v[0:1], v[6:7], 0, s[54:55]
	s_mov_b32 m0, s29
	s_nop 0
	global_load_lds_dwordx4 v[0:1], off
	s_waitcnt vmcnt(8)
	s_waitcnt lgkmcnt(0)
	s_barrier
	s_setprio 1
	v_mfma_f32_16x16x32_bf16 v[0:3], v[118:121], v[188:191], v[156:159]
	v_mfma_f32_16x16x32_bf16 v[4:7], v[126:129], v[188:191], v[160:163]
	v_mfma_f32_16x16x32_bf16 v[12:15], v[118:121], v[222:225], v[12:15]
	v_mfma_f32_16x16x32_bf16 v[16:19], v[126:129], v[222:225], v[16:19]
	v_mfma_f32_16x16x32_bf16 v[0:3], v[122:125], v[192:195], v[0:3]
	v_mfma_f32_16x16x32_bf16 v[4:7], v[144:147], v[192:195], v[4:7]
	v_mfma_f32_16x16x32_bf16 v[156:159], v[118:121], v[196:199], v[164:167]
	v_mfma_f32_16x16x32_bf16 v[160:163], v[126:129], v[196:199], v[168:171]
	v_mfma_f32_16x16x32_bf16 v[164:167], v[118:121], v[214:217], v[172:175]
	v_mfma_f32_16x16x32_bf16 v[168:171], v[126:129], v[214:217], v[176:179]
	v_mfma_f32_16x16x32_bf16 v[12:15], v[122:125], v[226:229], v[12:15]
	v_mfma_f32_16x16x32_bf16 v[16:19], v[144:147], v[226:229], v[16:19]
	v_mfma_f32_16x16x32_bf16 v[156:159], v[122:125], v[206:209], v[156:159]
	v_mfma_f32_16x16x32_bf16 v[160:163], v[144:147], v[206:209], v[160:163]
	v_mfma_f32_16x16x32_bf16 v[164:167], v[122:125], v[218:221], v[164:167]
	v_mfma_f32_16x16x32_bf16 v[168:171], v[144:147], v[218:221], v[168:171]
	v_mfma_f32_16x16x32_bf16 v[20:23], v[148:151], v[188:191], v[20:23]
	v_mfma_f32_16x16x32_bf16 v[32:35], v[180:183], v[188:191], v[32:35]
	v_mfma_f32_16x16x32_bf16 v[36:39], v[148:151], v[196:199], v[36:39]
	v_mfma_f32_16x16x32_bf16 v[60:63], v[180:183], v[196:199], v[60:63]
	v_mfma_f32_16x16x32_bf16 v[66:69], v[148:151], v[214:217], v[66:69]
	v_mfma_f32_16x16x32_bf16 v[114:117], v[180:183], v[214:217], v[114:117]
	v_mfma_f32_16x16x32_bf16 v[24:27], v[148:151], v[222:225], v[24:27]
	v_mfma_f32_16x16x32_bf16 v[28:31], v[180:183], v[222:225], v[28:31]
	v_mfma_f32_16x16x32_bf16 v[20:23], v[152:155], v[192:195], v[20:23]
	v_mfma_f32_16x16x32_bf16 v[32:35], v[184:187], v[192:195], v[32:35]
	v_mfma_f32_16x16x32_bf16 v[36:39], v[152:155], v[206:209], v[36:39]
	v_mfma_f32_16x16x32_bf16 v[60:63], v[184:187], v[206:209], v[60:63]
	v_mfma_f32_16x16x32_bf16 v[66:69], v[152:155], v[218:221], v[66:69]
	v_mfma_f32_16x16x32_bf16 v[114:117], v[184:187], v[218:221], v[114:117]
	v_mfma_f32_16x16x32_bf16 v[24:27], v[152:155], v[226:229], v[24:27]
	v_mfma_f32_16x16x32_bf16 v[28:31], v[184:187], v[226:229], v[28:31]
	s_setprio 0
	s_barrier
	ds_read_b128 v[118:121], v8
	ds_read_b128 v[122:125], v8 offset:1024
	ds_read_b128 v[126:129], v8 offset:2048
	ds_read_b128 v[144:147], v8 offset:3072
	ds_read_b128 v[148:151], v9
	ds_read_b128 v[152:155], v9 offset:1024
	ds_read_b128 v[172:175], v9 offset:2048
	ds_read_b128 v[176:179], v9 offset:3072
	s_add_u32 s14, s14, 0x18280
	s_addc_u32 s15, s15, 0
	s_mov_b32 m0, s50
	v_lshl_add_u64 v[8:9], s[14:15], 0, v[136:137]
	ds_read_b128 v[180:183], v142
	ds_read_b128 v[184:187], v142 offset:1024
	ds_read_b128 v[188:191], v142 offset:2048
	ds_read_b128 v[192:195], v142 offset:3072
	ds_read_b128 v[196:199], v142 offset:4096
	ds_read_b128 v[206:209], v142 offset:5120
	ds_read_b128 v[214:217], v142 offset:6144
	ds_read_b128 v[218:221], v142 offset:7168
	global_load_lds_dwordx4 v[8:9], off
	v_lshl_add_u64 v[8:9], s[14:15], 0, v[132:133]
	s_mov_b32 m0, s2
	s_nop 0
	global_load_lds_dwordx4 v[8:9], off
	s_waitcnt vmcnt(8)
	s_waitcnt lgkmcnt(0)
	s_barrier
	s_setprio 1
	v_mfma_f32_16x16x32_bf16 v[94:97], v[118:121], v[214:217], v[94:97]
	v_mfma_f32_16x16x32_bf16 v[70:73], v[118:121], v[180:183], v[70:73]
	v_mfma_f32_16x16x32_bf16 v[74:77], v[126:129], v[180:183], v[74:77]
	v_mfma_f32_16x16x32_bf16 v[78:81], v[118:121], v[188:191], v[78:81]
	v_mfma_f32_16x16x32_bf16 v[82:85], v[126:129], v[188:191], v[82:85]
	v_mfma_f32_16x16x32_bf16 v[86:89], v[118:121], v[196:199], v[86:89]
	v_mfma_f32_16x16x32_bf16 v[90:93], v[126:129], v[196:199], v[90:93]
	v_mfma_f32_16x16x32_bf16 v[222:225], v[122:125], v[218:221], v[94:97]
	v_mfma_f32_16x16x32_bf16 v[94:97], v[126:129], v[214:217], v[98:101]
	v_mfma_f32_16x16x32_bf16 v[70:73], v[122:125], v[184:187], v[70:73]
	v_mfma_f32_16x16x32_bf16 v[74:77], v[144:147], v[184:187], v[74:77]
	v_mfma_f32_16x16x32_bf16 v[78:81], v[122:125], v[192:195], v[78:81]
	v_mfma_f32_16x16x32_bf16 v[82:85], v[144:147], v[192:195], v[82:85]
	v_mfma_f32_16x16x32_bf16 v[86:89], v[122:125], v[206:209], v[86:89]
	v_mfma_f32_16x16x32_bf16 v[90:93], v[144:147], v[206:209], v[90:93]
	v_mfma_f32_16x16x32_bf16 v[98:101], v[144:147], v[218:221], v[94:97]
	v_mfma_f32_16x16x32_bf16 v[94:97], v[148:151], v[180:183], v[102:105]
	v_mfma_f32_16x16x32_bf16 v[102:105], v[152:155], v[184:187], v[94:97]
	v_mfma_f32_16x16x32_bf16 v[94:97], v[172:175], v[180:183], v[106:109]
	v_mfma_f32_16x16x32_bf16 v[40:43], v[172:175], v[188:191], v[40:43]
	v_mfma_f32_16x16x32_bf16 v[44:47], v[148:151], v[196:199], v[44:47]
	v_mfma_f32_16x16x32_bf16 v[48:51], v[172:175], v[196:199], v[48:51]
	v_mfma_f32_16x16x32_bf16 v[52:55], v[148:151], v[214:217], v[52:55]
	v_mfma_f32_16x16x32_bf16 v[56:59], v[172:175], v[214:217], v[56:59]
	v_mfma_f32_16x16x32_bf16 v[180:183], v[176:179], v[184:187], v[94:97]
	v_mfma_f32_16x16x32_bf16 v[94:97], v[148:151], v[188:191], v[110:113]
	v_mfma_f32_16x16x32_bf16 v[40:43], v[176:179], v[192:195], v[40:43]
	v_mfma_f32_16x16x32_bf16 v[44:47], v[152:155], v[206:209], v[44:47]
	v_mfma_f32_16x16x32_bf16 v[48:51], v[176:179], v[206:209], v[48:51]
	v_mfma_f32_16x16x32_bf16 v[52:55], v[152:155], v[218:221], v[52:55]
	v_mfma_f32_16x16x32_bf16 v[56:59], v[176:179], v[218:221], v[56:59]
	v_mfma_f32_16x16x32_bf16 v[184:187], v[152:155], v[192:195], v[94:97]
	s_setprio 0
	s_barrier
; #define PG8_STAGE(bufoff, gbase, voff) do { _Pragma("unroll") for (int _i = 0; _i < 2; ++_i) \
;         __builtin_amdgcn_global_load_lds((const unsigned*)((const char*)(gbase) + (voff)[_i]), (PG8_LAS unsigned*)(lds + (bufoff) + ldsw + _i * 8192), 16, 0, 0); } while (0)
; #define PG8_LDA(dst, b, h) do { _Pragma("unroll") for (int m = 0; m < 4; ++m) _Pragma("unroll") for (int k = 0; k < 2; ++k) dst[m][k] = *(const PG8_LAS bf16x8*)(lds + PG8_SA(b, h) + aoff + m * 2048 + k * 1024); } while (0)
; #define PG8_LDB(dst, b, h) do { _Pragma("unroll") for (int n = 0; n < 2; ++n) _Pragma("unroll") for (int k = 0; k < 2; ++k) dst[n][k] = *(const PG8_LAS bf16x8*)(lds + PG8_SB(b, h) + boff + n * 2048 + k * 1024); } while (0)
; #define PG8_MMA(ai, bj, At, Bt) do { __builtin_amdgcn_s_setprio(1); _Pragma("unroll") for (int m = 0; m < 4; ++m) _Pragma("unroll") for (int n = 0; n < 2; ++n) _Pragma("unroll") for (int k = 0; k < 2; ++k) \
;         acc[ai][bj][m][n] = __builtin_amdgcn_mfma_f32_16x16x32_bf16(Bt[n][k], At[m][k], acc[ai][bj][m][n], 0, 0, 0); __builtin_amdgcn_s_setprio(0); } while (0)
; #define PG8_WAIT_V(n) asm volatile("s_waitcnt vmcnt(" #n ")" ::: "memory")
; #define PG8_WAIT_L(n) asm volatile("s_waitcnt lgkmcnt(" #n ")" ::: "memory")
; #define PG8_BAR __builtin_amdgcn_s_barrier()
; #define PG8_SCHED __builtin_amdgcn_sched_barrier(0)
; template <class Epi, class Sched, bool ALIGN_EPI = false, bool SP2 = false>
; __device__ __forceinline__ void gemm_phase(PG8_LAS unsigned char* lds, const Gemm g, const Sched& S, const Epi& E, const int tid) {
;     ...
;             const char* a2 = last ? nA : cA + (size_t)(t + 2) * kstep; const char* b2 = last ? nB : cB + (size_t)(t + 2) * kstep;
;     ...
;             PG8_LDA(At, 0, 1); PG8_STAGE(PG8_SB(0, 0), b2, voffB); PG8_STAGE(PG8_SB(0, 1), b2 + hstep, voffB); PG8_STAGE(PG8_SA(0, 0), a2, voffA);
;             PG8_WAIT_V(8); PG8_WAIT_L(0); PG8_BAR; PG8_MMA(1, 0, At, B0); PG8_MMA(1, 1, At, B1); PG8_BAR; PG8_SCHED;
;             PG8_LDB(B0, 1, 0); PG8_LDB(B1, 1, 1); PG8_SCHED; PG8_LDA(At, 1, 0); PG8_STAGE(PG8_SA(0, 1), a2 + hstep, voffA);
;             PG8_WAIT_V(8); PG8_WAIT_L(0); PG8_BAR; PG8_MMA(0, 0, At, B0); PG8_MMA(0, 1, At, B1); PG8_BAR; PG8_SCHED;
	s_mov_b32 m0, s47
	v_lshl_add_u64 v[138:139], s[12:13], 0, v[134:135]
	s_add_u32 s2, s12, 0x18000
	ds_read_b128 v[94:97], v142 offset:16384
	ds_read_b128 v[106:109], v142 offset:17408
	ds_read_b128 v[110:113], v142 offset:18432
	ds_read_b128 v[188:191], v142 offset:19456
	ds_read_b128 v[192:195], v142 offset:20480
	ds_read_b128 v[196:199], v142 offset:21504
	ds_read_b128 v[206:209], v142 offset:22528
	ds_read_b128 v[214:217], v142 offset:23552
	global_load_lds_dwordx4 v[138:139], off
	v_lshl_add_u64 v[252:253], s[12:13], 0, v[130:131]
	s_mov_b32 m0, s3
	s_addc_u32 s3, s13, 0
	global_load_lds_dwordx4 v[252:253], off
	v_lshl_add_u64 v[8:9], s[2:3], 0, v[134:135]
	s_mov_b32 m0, s45
	v_lshl_add_u64 v[246:247], s[10:11], 0, v[136:137]
	global_load_lds_dwordx4 v[8:9], off
	v_lshl_add_u64 v[8:9], s[2:3], 0, v[130:131]
	s_mov_b32 m0, s46
	v_lshl_add_u64 v[210:211], s[10:11], 0, v[132:133]
	global_load_lds_dwordx4 v[8:9], off
	s_mov_b32 m0, s23
	s_nop 0
	global_load_lds_dwordx4 v[246:247], off
	s_mov_b32 m0, s24
	s_nop 0
	global_load_lds_dwordx4 v[210:211], off
	s_waitcnt vmcnt(8)
	s_waitcnt lgkmcnt(0)
	s_barrier
	s_setprio 1
	v_mfma_f32_16x16x32_bf16 v[0:3], v[118:121], v[94:97], v[0:3]
	v_mfma_f32_16x16x32_bf16 v[4:7], v[126:129], v[94:97], v[4:7]
	v_mfma_f32_16x16x32_bf16 v[12:15], v[118:121], v[206:209], v[12:15]
	v_mfma_f32_16x16x32_bf16 v[16:19], v[126:129], v[206:209], v[16:19]
	v_mfma_f32_16x16x32_bf16 v[0:3], v[122:125], v[106:109], v[0:3]
	v_mfma_f32_16x16x32_bf16 v[4:7], v[144:147], v[106:109], v[4:7]
	v_mfma_f32_16x16x32_bf16 v[156:159], v[118:121], v[110:113], v[156:159]
	v_mfma_f32_16x16x32_bf16 v[160:163], v[126:129], v[110:113], v[160:163]
	v_mfma_f32_16x16x32_bf16 v[164:167], v[118:121], v[192:195], v[164:167]
	v_mfma_f32_16x16x32_bf16 v[168:171], v[126:129], v[192:195], v[168:171]
	v_mfma_f32_16x16x32_bf16 v[12:15], v[122:125], v[214:217], v[12:15]
	v_mfma_f32_16x16x32_bf16 v[16:19], v[144:147], v[214:217], v[16:19]
	v_mfma_f32_16x16x32_bf16 v[156:159], v[122:125], v[188:191], v[156:159]
	v_mfma_f32_16x16x32_bf16 v[160:163], v[144:147], v[188:191], v[160:163]
	v_mfma_f32_16x16x32_bf16 v[164:167], v[122:125], v[196:199], v[164:167]
	v_mfma_f32_16x16x32_bf16 v[168:171], v[144:147], v[196:199], v[168:171]
	v_mfma_f32_16x16x32_bf16 v[60:63], v[172:175], v[110:113], v[60:63]
	v_mfma_f32_16x16x32_bf16 v[20:23], v[148:151], v[94:97], v[20:23]
	v_mfma_f32_16x16x32_bf16 v[32:35], v[172:175], v[94:97], v[32:35]
	v_mfma_f32_16x16x32_bf16 v[36:39], v[148:151], v[110:113], v[36:39]
	v_mfma_f32_16x16x32_bf16 v[144:147], v[176:179], v[188:191], v[60:63]
	v_mfma_f32_16x16x32_bf16 v[60:63], v[148:151], v[192:195], v[66:69]
	v_mfma_f32_16x16x32_bf16 v[24:27], v[148:151], v[206:209], v[24:27]
	v_mfma_f32_16x16x32_bf16 v[20:23], v[152:155], v[106:109], v[20:23]
	v_mfma_f32_16x16x32_bf16 v[32:35], v[176:179], v[106:109], v[32:35]
	v_mfma_f32_16x16x32_bf16 v[36:39], v[152:155], v[188:191], v[36:39]
	v_mfma_f32_16x16x32_bf16 v[188:191], v[152:155], v[196:199], v[60:63]
	v_mfma_f32_16x16x32_bf16 v[60:63], v[172:175], v[192:195], v[114:117]
	v_mfma_f32_16x16x32_bf16 v[148:151], v[152:155], v[214:217], v[24:27]
	v_mfma_f32_16x16x32_bf16 v[24:27], v[172:175], v[206:209], v[28:31]
	v_mfma_f32_16x16x32_bf16 v[192:195], v[176:179], v[196:199], v[60:63]
	v_mfma_f32_16x16x32_bf16 v[152:155], v[176:179], v[214:217], v[24:27]
	s_setprio 0
	s_barrier
	ds_read_b128 v[172:175], v10
	ds_read_b128 v[176:179], v10 offset:1024
	ds_read_b128 v[196:199], v10 offset:2048
	ds_read_b128 v[206:209], v10 offset:3072
	ds_read_b128 v[214:217], v11
	ds_read_b128 v[218:221], v11 offset:1024
	ds_read_b128 v[226:229], v11 offset:2048
	ds_read_b128 v[248:251], v11 offset:3072
	s_add_u32 s2, s10, 0x18000
	s_addc_u32 s3, s11, 0
	s_mov_b32 m0, s25
	v_lshl_add_u64 v[94:95], s[2:3], 0, v[136:137]
	ds_read_b128 v[8:11], v142 offset:32768
	ds_read_b128 v[24:27], v142 offset:33792
	ds_read_b128 v[28:31], v142 offset:34816
	ds_read_b128 v[60:63], v142 offset:35840
	ds_read_b128 v[66:69], v142 offset:36864
	ds_read_b128 v[234:237], v142 offset:37888
	ds_read_b128 v[238:241], v142 offset:38912
	ds_read_b128 v[230:233], v142 offset:39936
	global_load_lds_dwordx4 v[94:95], off
	v_lshl_add_u64 v[94:95], s[2:3], 0, v[132:133]
	s_mov_b32 m0, s26
	s_nop 0
	global_load_lds_dwordx4 v[94:95], off
	s_waitcnt vmcnt(8)
	s_waitcnt lgkmcnt(0)
	s_barrier
; #define PG8_STAGE(bufoff, gbase, voff) do { _Pragma("unroll") for (int _i = 0; _i < 2; ++_i) \
;         __builtin_amdgcn_global_load_lds((const unsigned*)((const char*)(gbase) + (voff)[_i]), (PG8_LAS unsigned*)(lds + (bufoff) + ldsw + _i * 8192), 16, 0, 0); } while (0)
; #define PG8_LDA(dst, b, h) do { _Pragma("unroll") for (int m = 0; m < 4; ++m) _Pragma("unroll") for (int k = 0; k < 2; ++k) dst[m][k] = *(const PG8_LAS bf16x8*)(lds + PG8_SA(b, h) + aoff + m * 2048 + k * 1024); } while (0)
; #define PG8_MMA(ai, bj, At, Bt) do { __builtin_amdgcn_s_setprio(1); _Pragma("unroll") for (int m = 0; m < 4; ++m) _Pragma("unroll") for (int n = 0; n < 2; ++n) _Pragma("unroll") for (int k = 0; k < 2; ++k) \
;         acc[ai][bj][m][n] = __builtin_amdgcn_mfma_f32_16x16x32_bf16(Bt[n][k], At[m][k], acc[ai][bj][m][n], 0, 0, 0); __builtin_amdgcn_s_setprio(0); } while (0)
; #define PG8_WAIT_V(n) asm volatile("s_waitcnt vmcnt(" #n ")" ::: "memory")
; #define PG8_WAIT_L(n) asm volatile("s_waitcnt lgkmcnt(" #n ")" ::: "memory")
; #define PG8_BAR __builtin_amdgcn_s_barrier()
; #define PG8_SCHED __builtin_amdgcn_sched_barrier(0)
; template <class Epi, class Sched, bool ALIGN_EPI = false, bool SP2 = false>
; __device__ __forceinline__ void gemm_phase(PG8_LAS unsigned char* lds, const Gemm g, const Sched& S, const Epi& E, const int tid) {
;     ...
;             PG8_WAIT_V(8); PG8_WAIT_L(0); PG8_BAR; PG8_MMA(0, 0, At, B0); PG8_MMA(0, 1, At, B1); PG8_BAR; PG8_SCHED;
;             PG8_LDA(At, 1, 1); PG8_STAGE(PG8_SB(1, 0), b3, voffB); PG8_STAGE(PG8_SB(1, 1), b3 + hstep, voffB); PG8_STAGE(PG8_SA(1, 0), a3, voffA);
;             PG8_WAIT_V(8); PG8_WAIT_L(0); PG8_BAR; PG8_MMA(1, 0, At, B0); PG8_MMA(1, 1, At, B1); PG8_BAR; PG8_SCHED;
;     ...
;         if constexpr (ALIGN_EPI) { if (wr == 0) PG8_BAR; }
	s_setprio 1
	v_mfma_f32_16x16x32_bf16 v[70:73], v[172:175], v[8:11], v[70:73]
	v_mfma_f32_16x16x32_bf16 v[126:129], v[176:179], v[24:27], v[70:73]
	v_mfma_f32_16x16x32_bf16 v[70:73], v[196:199], v[8:11], v[74:77]
	v_mfma_f32_16x16x32_bf16 v[122:125], v[206:209], v[24:27], v[70:73]
	v_mfma_f32_16x16x32_bf16 v[70:73], v[172:175], v[28:31], v[78:81]
	v_mfma_f32_16x16x32_bf16 v[110:113], v[176:179], v[60:63], v[70:73]
	v_mfma_f32_16x16x32_bf16 v[70:73], v[196:199], v[28:31], v[82:85]
	v_mfma_f32_16x16x32_bf16 v[106:109], v[206:209], v[60:63], v[70:73]
	v_mfma_f32_16x16x32_bf16 v[70:73], v[172:175], v[66:69], v[86:89]
	v_mfma_f32_16x16x32_bf16 v[94:97], v[176:179], v[234:237], v[70:73]
	v_mfma_f32_16x16x32_bf16 v[70:73], v[196:199], v[66:69], v[90:93]
	v_mfma_f32_16x16x32_bf16 v[90:93], v[206:209], v[234:237], v[70:73]
	v_mfma_f32_16x16x32_bf16 v[70:73], v[172:175], v[238:241], v[222:225]
	v_mfma_f32_16x16x32_bf16 v[78:81], v[176:179], v[230:233], v[70:73]
	v_mfma_f32_16x16x32_bf16 v[70:73], v[196:199], v[238:241], v[98:101]
	v_mfma_f32_16x16x32_bf16 v[74:77], v[206:209], v[230:233], v[70:73]
	v_mfma_f32_16x16x32_bf16 v[70:73], v[214:217], v[8:11], v[102:105]
	v_mfma_f32_16x16x32_bf16 v[8:11], v[226:229], v[8:11], v[180:183]
	v_mfma_f32_16x16x32_bf16 v[118:121], v[248:251], v[24:27], v[8:11]
	v_mfma_f32_16x16x32_bf16 v[8:11], v[214:217], v[28:31], v[184:187]
	v_mfma_f32_16x16x32_bf16 v[98:101], v[218:221], v[60:63], v[8:11]
	v_mfma_f32_16x16x32_bf16 v[8:11], v[226:229], v[28:31], v[40:43]
	v_mfma_f32_16x16x32_bf16 v[102:105], v[248:251], v[60:63], v[8:11]
	v_mfma_f32_16x16x32_bf16 v[8:11], v[214:217], v[66:69], v[44:47]
	v_mfma_f32_16x16x32_bf16 v[82:85], v[218:221], v[234:237], v[8:11]
	v_mfma_f32_16x16x32_bf16 v[8:11], v[226:229], v[66:69], v[48:51]
	v_mfma_f32_16x16x32_bf16 v[86:89], v[248:251], v[234:237], v[8:11]
	v_mfma_f32_16x16x32_bf16 v[8:11], v[214:217], v[238:241], v[52:55]
	v_mfma_f32_16x16x32_bf16 v[66:69], v[218:221], v[230:233], v[8:11]
	v_mfma_f32_16x16x32_bf16 v[8:11], v[226:229], v[238:241], v[56:59]
	v_mfma_f32_16x16x32_bf16 v[114:117], v[218:221], v[24:27], v[70:73]
	v_mfma_f32_16x16x32_bf16 v[70:73], v[248:251], v[230:233], v[8:11]
	s_setprio 0
	s_barrier
	s_mov_b32 m0, s52
	s_nop 2
	v_lshl_add_u64 v[8:9], v[138:139], 0, s[94:95]
	s_add_u32 s2, s12, 0x18080
	ds_read_b128 v[52:55], v142 offset:49152
	ds_read_b128 v[180:183], v142 offset:50176
	ds_read_b128 v[184:187], v142 offset:51200
	ds_read_b128 v[222:225], v142 offset:52224
	ds_read_b128 v[230:233], v142 offset:53248
	ds_read_b128 v[234:237], v142 offset:54272
	ds_read_b128 v[238:241], v142 offset:55296
	ds_read_b128 v[200:203], v142 offset:56320
	global_load_lds_dwordx4 v[8:9], off
	v_lshl_add_u64 v[8:9], v[252:253], 0, s[94:95]
	s_mov_b32 m0, s48
	s_addc_u32 s3, s13, 0
	global_load_lds_dwordx4 v[8:9], off
	v_lshl_add_u64 v[8:9], s[2:3], 0, v[134:135]
	s_mov_b32 m0, s49
	s_nop 0
	global_load_lds_dwordx4 v[8:9], off
	v_lshl_add_u64 v[8:9], s[2:3], 0, v[130:131]
	s_mov_b32 m0, s51
	s_nop 0
	global_load_lds_dwordx4 v[8:9], off
	v_lshl_add_u64 v[8:9], v[246:247], 0, s[94:95]
	s_mov_b32 m0, s28
	s_nop 0
	global_load_lds_dwordx4 v[8:9], off
	v_lshl_add_u64 v[8:9], v[210:211], 0, s[94:95]
	s_mov_b32 m0, s29
	s_nop 0
	global_load_lds_dwordx4 v[8:9], off
	s_waitcnt vmcnt(8)
	s_waitcnt lgkmcnt(0)
	s_barrier
	s_setprio 1
	v_mfma_f32_16x16x32_bf16 v[0:3], v[172:175], v[52:55], v[0:3]
	v_mfma_f32_16x16x32_bf16 v[60:63], v[176:179], v[180:183], v[0:3]
	v_mfma_f32_16x16x32_bf16 v[0:3], v[196:199], v[52:55], v[4:7]
	v_mfma_f32_16x16x32_bf16 v[56:59], v[206:209], v[180:183], v[0:3]
	v_mfma_f32_16x16x32_bf16 v[0:3], v[172:175], v[184:187], v[156:159]
	v_mfma_f32_16x16x32_bf16 v[44:47], v[176:179], v[222:225], v[0:3]
	v_mfma_f32_16x16x32_bf16 v[0:3], v[196:199], v[184:187], v[160:163]
	v_mfma_f32_16x16x32_bf16 v[40:43], v[206:209], v[222:225], v[0:3]
	v_mfma_f32_16x16x32_bf16 v[0:3], v[172:175], v[230:233], v[164:167]
	v_mfma_f32_16x16x32_bf16 v[28:31], v[176:179], v[234:237], v[0:3]
	v_mfma_f32_16x16x32_bf16 v[0:3], v[196:199], v[230:233], v[168:171]
	v_mfma_f32_16x16x32_bf16 v[24:27], v[206:209], v[234:237], v[0:3]
	v_mfma_f32_16x16x32_bf16 v[0:3], v[172:175], v[238:241], v[12:15]
	v_mfma_f32_16x16x32_bf16 v[8:11], v[176:179], v[200:203], v[0:3]
	v_mfma_f32_16x16x32_bf16 v[0:3], v[196:199], v[238:241], v[16:19]
	v_mfma_f32_16x16x32_bf16 v[12:15], v[206:209], v[200:203], v[0:3]
	v_mfma_f32_16x16x32_bf16 v[0:3], v[214:217], v[52:55], v[20:23]
	v_mfma_f32_16x16x32_bf16 v[48:51], v[218:221], v[180:183], v[0:3]
	v_mfma_f32_16x16x32_bf16 v[0:3], v[226:229], v[52:55], v[32:35]
	v_mfma_f32_16x16x32_bf16 v[52:55], v[248:251], v[180:183], v[0:3]
	v_mfma_f32_16x16x32_bf16 v[0:3], v[214:217], v[184:187], v[36:39]
	v_mfma_f32_16x16x32_bf16 v[32:35], v[218:221], v[222:225], v[0:3]
	v_mfma_f32_16x16x32_bf16 v[0:3], v[226:229], v[184:187], v[144:147]
	v_mfma_f32_16x16x32_bf16 v[36:39], v[248:251], v[222:225], v[0:3]
	v_mfma_f32_16x16x32_bf16 v[0:3], v[214:217], v[230:233], v[188:191]
	v_mfma_f32_16x16x32_bf16 v[16:19], v[218:221], v[234:237], v[0:3]
	v_mfma_f32_16x16x32_bf16 v[0:3], v[226:229], v[230:233], v[192:195]
	v_mfma_f32_16x16x32_bf16 v[20:23], v[248:251], v[234:237], v[0:3]
	v_mfma_f32_16x16x32_bf16 v[0:3], v[214:217], v[238:241], v[148:151]
	v_mfma_f32_16x16x32_bf16 v[4:7], v[226:229], v[238:241], v[152:155]
	v_mfma_f32_16x16x32_bf16 v[0:3], v[218:221], v[200:203], v[0:3]
	v_mfma_f32_16x16x32_bf16 v[4:7], v[248:251], v[200:203], v[4:7]
	s_setprio 0
	s_barrier
	s_andn2_b64 vcc, exec, s[8:9]
	s_cbranch_vccnz .LBB0_350
	s_barrier

; #define PG8_STAGE(bufoff, gbase, voff) do { _Pragma("unroll") for (int _i = 0; _i < 2; ++_i) \
;         __builtin_amdgcn_global_load_lds((const unsigned*)((const char*)(gbase) + (voff)[_i]), (PG8_LAS unsigned*)(lds + (bufoff) + ldsw + _i * 8192), 16, 0, 0); } while (0)
; #define PG8_LDA(dst, b, h) do { _Pragma("unroll") for (int m = 0; m < 4; ++m) _Pragma("unroll") for (int k = 0; k < 2; ++k) dst[m][k] = *(const PG8_LAS bf16x8*)(lds + PG8_SA(b, h) + aoff + m * 2048 + k * 1024); } while (0)
; #define PG8_LDB(dst, b, h) do { _Pragma("unroll") for (int n = 0; n < 2; ++n) _Pragma("unroll") for (int k = 0; k < 2; ++k) dst[n][k] = *(const PG8_LAS bf16x8*)(lds + PG8_SB(b, h) + boff + n * 2048 + k * 1024); } while (0)
; #define PG8_MMA(ai, bj, At, Bt) do { __builtin_amdgcn_s_setprio(1); _Pragma("unroll") for (int m = 0; m < 4; ++m) _Pragma("unroll") for (int n = 0; n < 2; ++n) _Pragma("unroll") for (int k = 0; k < 2; ++k) \
;         acc[ai][bj][m][n] = __builtin_amdgcn_mfma_f32_16x16x32_bf16(Bt[n][k], At[m][k], acc[ai][bj][m][n], 0, 0, 0); __builtin_amdgcn_s_setprio(0); } while (0)
; #define PG8_WAIT_V(n) asm volatile("s_waitcnt vmcnt(" #n ")" ::: "memory")
; #define PG8_WAIT_L(n) asm volatile("s_waitcnt lgkmcnt(" #n ")" ::: "memory")
; template <class Epi, class Sched, bool ALIGN_EPI = false, bool SP2 = false>
; __device__ __forceinline__ void gemm_phase(PG8_LAS unsigned char* lds, const Gemm g, const Sched& S, const Epi& E, const int tid) {
;     ...
;             const bool last = (t == nt - 2);
;             const char* a1 = cA + (size_t)(t + 1) * kstep;
;             const char* a2 = last ? nA : cA + (size_t)(t + 2) * kstep; const char* b2 = last ? nB : cB + (size_t)(t + 2) * kstep;
;             const char* a3 = a2 + kstep; const char* b3 = b2 + kstep;
;             if (last && has_next) S.a_ready(nxt);
;             if constexpr (SP2) {
;             PG8_LDB(B0, 0, 0); PG8_LDB(B1, 0, 1); PG8_SCHED; PG8_LDA(At, 0, 0); PG8_STAGE(PG8_SA(1, 1), a1 + hstep, voffA);
;             PG8_WAIT_V(8); PG8_WAIT_L(0); PG8_BAR; PG8_MMA(0, 0, At, B0); PG8_MMA(0, 1, At, B1); PG8_BAR; PG8_SCHED;
;             PG8_LDA(At, 0, 1); PG8_STAGE(PG8_SB(0, 0), b2, voffB); PG8_STAGE(PG8_SB(0, 1), b2 + hstep, voffB); PG8_STAGE(PG8_SA(0, 0), a2, voffA);
;             PG8_WAIT_V(8); PG8_WAIT_L(0); PG8_BAR; PG8_MMA(1, 0, At, B0); PG8_MMA(1, 1, At, B1); PG8_BAR; PG8_SCHED;
.LBB0_511:
	s_add_u32 s6, s24, s4
	s_addc_u32 s7, s25, s5
	s_add_u32 s6, s6, 0x2c00100
	s_addc_u32 s7, s7, 0
	s_add_u32 s27, s22, s4
	s_addc_u32 s28, s23, s5
	s_add_i32 s29, 0, 0x10000
	s_cmpk_eq_i32 s4, 0x700
	s_cselect_b32 s9, s3, s7
	s_cselect_b32 s8, s2, s6
	v_add_u32_e32 v149, s29, v142
	s_cselect_b32 s7, s1, s28
	s_cselect_b32 s6, s0, s27
	s_add_i32 s27, 0, 0x14000
	ds_read_b128 v[144:147], v149
	ds_read_b128 v[150:153], v149 offset:1024
	ds_read_b128 v[154:157], v149 offset:2048
	ds_read_b128 v[158:161], v149 offset:3072
	v_add_u32_e32 v149, s27, v142
	ds_read_b128 v[162:165], v149
	ds_read_b128 v[166:169], v149 offset:1024
	ds_read_b128 v[170:173], v149 offset:2048
	ds_read_b128 v[174:177], v149 offset:3072
	v_lshl_add_u64 v[202:203], v[138:139], 0, s[4:5]
	s_add_i32 m0, s13, 0xc000
	ds_read_b128 v[178:181], v143
	ds_read_b128 v[182:185], v143 offset:1024
	ds_read_b128 v[186:189], v143 offset:2048
	ds_read_b128 v[190:193], v143 offset:3072
	ds_read_b128 v[194:197], v143 offset:4096
	ds_read_b128 v[198:201], v143 offset:5120
	ds_read_b128 v[214:217], v143 offset:6144
	ds_read_b128 v[218:221], v143 offset:7168
	global_load_lds_dwordx4 v[202:203], off
	v_lshl_add_u64 v[202:203], v[136:137], 0, s[4:5]
	s_add_i32 m0, s13, 0xe000
	s_nop 0
	global_load_lds_dwordx4 v[202:203], off
	s_waitcnt vmcnt(8)
	s_waitcnt lgkmcnt(0)
	s_barrier
	s_setprio 1
	v_mfma_f32_16x16x32_bf16 v[126:129], v[144:147], v[178:181], v[126:129]
	v_mfma_f32_16x16x32_bf16 v[122:125], v[154:157], v[178:181], v[122:125]
	v_mfma_f32_16x16x32_bf16 v[118:121], v[144:147], v[186:189], v[118:121]
	v_mfma_f32_16x16x32_bf16 v[114:117], v[154:157], v[186:189], v[114:117]
	v_mfma_f32_16x16x32_bf16 v[110:113], v[144:147], v[194:197], v[110:113]
	v_mfma_f32_16x16x32_bf16 v[106:109], v[154:157], v[194:197], v[106:109]
	v_mfma_f32_16x16x32_bf16 v[102:105], v[144:147], v[214:217], v[102:105]
	v_mfma_f32_16x16x32_bf16 v[98:101], v[154:157], v[214:217], v[98:101]
	v_mfma_f32_16x16x32_bf16 v[126:129], v[150:153], v[182:185], v[126:129]
	v_mfma_f32_16x16x32_bf16 v[122:125], v[158:161], v[182:185], v[122:125]
	v_mfma_f32_16x16x32_bf16 v[118:121], v[150:153], v[190:193], v[118:121]
	v_mfma_f32_16x16x32_bf16 v[114:117], v[158:161], v[190:193], v[114:117]
	v_mfma_f32_16x16x32_bf16 v[110:113], v[150:153], v[198:201], v[110:113]
	v_mfma_f32_16x16x32_bf16 v[106:109], v[158:161], v[198:201], v[106:109]
	v_mfma_f32_16x16x32_bf16 v[102:105], v[150:153], v[218:221], v[102:105]
	v_mfma_f32_16x16x32_bf16 v[98:101], v[158:161], v[218:221], v[98:101]
	v_mfma_f32_16x16x32_bf16 v[60:63], v[162:165], v[178:181], v[60:63]
	v_mfma_f32_16x16x32_bf16 v[56:59], v[170:173], v[178:181], v[56:59]
	v_mfma_f32_16x16x32_bf16 v[52:55], v[162:165], v[186:189], v[52:55]
	v_mfma_f32_16x16x32_bf16 v[48:51], v[170:173], v[186:189], v[48:51]
	v_mfma_f32_16x16x32_bf16 v[44:47], v[162:165], v[194:197], v[44:47]
	v_mfma_f32_16x16x32_bf16 v[40:43], v[170:173], v[194:197], v[40:43]
	v_mfma_f32_16x16x32_bf16 v[36:39], v[162:165], v[214:217], v[36:39]
	v_mfma_f32_16x16x32_bf16 v[32:35], v[170:173], v[214:217], v[32:35]
	v_mfma_f32_16x16x32_bf16 v[60:63], v[166:169], v[182:185], v[60:63]
	v_mfma_f32_16x16x32_bf16 v[56:59], v[174:177], v[182:185], v[56:59]
	v_mfma_f32_16x16x32_bf16 v[52:55], v[166:169], v[190:193], v[52:55]
	v_mfma_f32_16x16x32_bf16 v[48:51], v[174:177], v[190:193], v[48:51]
	v_mfma_f32_16x16x32_bf16 v[44:47], v[166:169], v[198:201], v[44:47]
	v_mfma_f32_16x16x32_bf16 v[40:43], v[174:177], v[198:201], v[40:43]
	v_mfma_f32_16x16x32_bf16 v[36:39], v[166:169], v[218:221], v[36:39]
	v_mfma_f32_16x16x32_bf16 v[32:35], v[174:177], v[218:221], v[32:35]
	s_setprio 0
	s_barrier
	s_add_i32 s28, s29, s12
	v_lshl_add_u64 v[202:203], s[6:7], 0, v[64:65]
	s_mov_b32 m0, s28
	ds_read_b128 v[178:181], v143 offset:16384
	ds_read_b128 v[182:185], v143 offset:17408
	ds_read_b128 v[186:189], v143 offset:18432
	ds_read_b128 v[190:193], v143 offset:19456
	ds_read_b128 v[194:197], v143 offset:20480
	ds_read_b128 v[198:201], v143 offset:21504
	ds_read_b128 v[214:217], v143 offset:22528
	ds_read_b128 v[218:221], v143 offset:23552
	global_load_lds_dwordx4 v[202:203], off
	s_add_i32 m0, s28, 0x2000
	s_add_u32 s28, s6, 0x40000
	v_lshl_add_u64 v[206:207], s[6:7], 0, v[134:135]
	s_addc_u32 s29, s7, 0
	s_add_i32 s27, s27, s12
	global_load_lds_dwordx4 v[206:207], off
	v_lshl_add_u64 v[208:209], s[28:29], 0, v[64:65]
	s_mov_b32 m0, s27
	v_lshl_add_u64 v[222:223], s[8:9], 0, v[132:133]
	global_load_lds_dwordx4 v[208:209], off
	v_lshl_add_u64 v[208:209], s[28:29], 0, v[134:135]
	s_add_i32 m0, s27, 0x2000
	s_nop 0
	global_load_lds_dwordx4 v[208:209], off
	v_lshl_add_u64 v[208:209], s[8:9], 0, v[130:131]
	s_mov_b32 m0, s13
	s_nop 0
	global_load_lds_dwordx4 v[208:209], off
	s_mov_b32 m0, s16
	s_nop 0
	global_load_lds_dwordx4 v[222:223], off
	s_waitcnt vmcnt(8)
	s_waitcnt lgkmcnt(0)
	s_barrier
; #define PG8_STAGE(bufoff, gbase, voff) do { _Pragma("unroll") for (int _i = 0; _i < 2; ++_i) \
;         __builtin_amdgcn_global_load_lds((const unsigned*)((const char*)(gbase) + (voff)[_i]), (PG8_LAS unsigned*)(lds + (bufoff) + ldsw + _i * 8192), 16, 0, 0); } while (0)
; #define PG8_LDA(dst, b, h) do { _Pragma("unroll") for (int m = 0; m < 4; ++m) _Pragma("unroll") for (int k = 0; k < 2; ++k) dst[m][k] = *(const PG8_LAS bf16x8*)(lds + PG8_SA(b, h) + aoff + m * 2048 + k * 1024); } while (0)
; #define PG8_LDB(dst, b, h) do { _Pragma("unroll") for (int n = 0; n < 2; ++n) _Pragma("unroll") for (int k = 0; k < 2; ++k) dst[n][k] = *(const PG8_LAS bf16x8*)(lds + PG8_SB(b, h) + boff + n * 2048 + k * 1024); } while (0)
; #define PG8_MMA(ai, bj, At, Bt) do { __builtin_amdgcn_s_setprio(1); _Pragma("unroll") for (int m = 0; m < 4; ++m) _Pragma("unroll") for (int n = 0; n < 2; ++n) _Pragma("unroll") for (int k = 0; k < 2; ++k) \
;         acc[ai][bj][m][n] = __builtin_amdgcn_mfma_f32_16x16x32_bf16(Bt[n][k], At[m][k], acc[ai][bj][m][n], 0, 0, 0); __builtin_amdgcn_s_setprio(0); } while (0)
; #define PG8_WAIT_V(n) asm volatile("s_waitcnt vmcnt(" #n ")" ::: "memory")
; #define PG8_WAIT_L(n) asm volatile("s_waitcnt lgkmcnt(" #n ")" ::: "memory")
; #define PG8_BAR __builtin_amdgcn_s_barrier()
; #define PG8_SCHED __builtin_amdgcn_sched_barrier(0)
; template <class Epi, class Sched, bool ALIGN_EPI = false, bool SP2 = false>
; __device__ __forceinline__ void gemm_phase(PG8_LAS unsigned char* lds, const Gemm g, const Sched& S, const Epi& E, const int tid) {
;     ...
;             PG8_WAIT_V(8); PG8_WAIT_L(0); PG8_BAR; PG8_MMA(1, 0, At, B0); PG8_MMA(1, 1, At, B1); PG8_BAR; PG8_SCHED;
;             PG8_LDB(B0, 1, 0); PG8_LDB(B1, 1, 1); PG8_SCHED; PG8_LDA(At, 1, 0); PG8_STAGE(PG8_SA(0, 1), a2 + hstep, voffA);
;             PG8_WAIT_V(8); PG8_WAIT_L(0); PG8_BAR; PG8_MMA(0, 0, At, B0); PG8_MMA(0, 1, At, B1); PG8_BAR; PG8_SCHED;
	s_setprio 1
	v_mfma_f32_16x16x32_bf16 v[94:97], v[144:147], v[178:181], v[94:97]
	v_mfma_f32_16x16x32_bf16 v[90:93], v[154:157], v[178:181], v[90:93]
	v_mfma_f32_16x16x32_bf16 v[86:89], v[144:147], v[186:189], v[86:89]
	v_mfma_f32_16x16x32_bf16 v[82:85], v[154:157], v[186:189], v[82:85]
	v_mfma_f32_16x16x32_bf16 v[78:81], v[144:147], v[194:197], v[78:81]
	v_mfma_f32_16x16x32_bf16 v[74:77], v[154:157], v[194:197], v[74:77]
	v_mfma_f32_16x16x32_bf16 v[70:73], v[144:147], v[214:217], v[70:73]
	v_mfma_f32_16x16x32_bf16 v[66:69], v[154:157], v[214:217], v[66:69]
	v_mfma_f32_16x16x32_bf16 v[94:97], v[150:153], v[182:185], v[94:97]
	v_mfma_f32_16x16x32_bf16 v[90:93], v[158:161], v[182:185], v[90:93]
	v_mfma_f32_16x16x32_bf16 v[86:89], v[150:153], v[190:193], v[86:89]
	v_mfma_f32_16x16x32_bf16 v[82:85], v[158:161], v[190:193], v[82:85]
	v_mfma_f32_16x16x32_bf16 v[78:81], v[150:153], v[198:201], v[78:81]
	v_mfma_f32_16x16x32_bf16 v[74:77], v[158:161], v[198:201], v[74:77]
	v_mfma_f32_16x16x32_bf16 v[70:73], v[150:153], v[218:221], v[70:73]
	v_mfma_f32_16x16x32_bf16 v[66:69], v[158:161], v[218:221], v[66:69]
	v_mfma_f32_16x16x32_bf16 v[28:31], v[162:165], v[178:181], v[28:31]
	v_mfma_f32_16x16x32_bf16 v[24:27], v[170:173], v[178:181], v[24:27]
	v_mfma_f32_16x16x32_bf16 v[20:23], v[162:165], v[186:189], v[20:23]
	v_mfma_f32_16x16x32_bf16 v[16:19], v[170:173], v[186:189], v[16:19]
	v_mfma_f32_16x16x32_bf16 v[12:15], v[162:165], v[194:197], v[12:15]
	v_mfma_f32_16x16x32_bf16 v[8:11], v[170:173], v[194:197], v[8:11]
	v_mfma_f32_16x16x32_bf16 v[4:7], v[162:165], v[214:217], v[4:7]
	v_mfma_f32_16x16x32_bf16 v[0:3], v[170:173], v[214:217], v[0:3]
	v_mfma_f32_16x16x32_bf16 v[28:31], v[166:169], v[182:185], v[28:31]
	v_mfma_f32_16x16x32_bf16 v[24:27], v[174:177], v[182:185], v[24:27]
	v_mfma_f32_16x16x32_bf16 v[20:23], v[166:169], v[190:193], v[20:23]
	v_mfma_f32_16x16x32_bf16 v[16:19], v[174:177], v[190:193], v[16:19]
	v_mfma_f32_16x16x32_bf16 v[12:15], v[166:169], v[198:201], v[12:15]
	v_mfma_f32_16x16x32_bf16 v[8:11], v[174:177], v[198:201], v[8:11]
	v_mfma_f32_16x16x32_bf16 v[4:7], v[166:169], v[218:221], v[4:7]
	v_mfma_f32_16x16x32_bf16 v[0:3], v[174:177], v[218:221], v[0:3]
	s_setprio 0
	s_barrier
	s_add_i32 s27, 0, 0x18000
	v_add_u32_e32 v149, s27, v142
	s_add_i32 s28, 0, 0x1c000
	ds_read_b128 v[144:147], v149
	ds_read_b128 v[150:153], v149 offset:1024
	ds_read_b128 v[154:157], v149 offset:2048
	ds_read_b128 v[158:161], v149 offset:3072
	v_add_u32_e32 v149, s28, v142
	ds_read_b128 v[162:165], v149
	ds_read_b128 v[166:169], v149 offset:1024
	ds_read_b128 v[170:173], v149 offset:2048
	ds_read_b128 v[174:177], v149 offset:3072
	s_add_u32 s8, s8, 0x40000
	s_addc_u32 s9, s9, 0
	s_mov_b32 m0, s17
	v_lshl_add_u64 v[224:225], s[8:9], 0, v[130:131]
	ds_read_b128 v[178:181], v143 offset:32768
	ds_read_b128 v[182:185], v143 offset:33792
	ds_read_b128 v[186:189], v143 offset:34816
	ds_read_b128 v[190:193], v143 offset:35840
	ds_read_b128 v[194:197], v143 offset:36864
	ds_read_b128 v[198:201], v143 offset:37888
	ds_read_b128 v[214:217], v143 offset:38912
	ds_read_b128 v[218:221], v143 offset:39936
	global_load_lds_dwordx4 v[224:225], off
	v_lshl_add_u64 v[224:225], s[8:9], 0, v[132:133]
	s_mov_b32 m0, s18
	s_nop 0
	global_load_lds_dwordx4 v[224:225], off
	s_waitcnt vmcnt(8)
	s_waitcnt lgkmcnt(0)
	s_barrier
	s_setprio 1
	v_mfma_f32_16x16x32_bf16 v[126:129], v[144:147], v[178:181], v[126:129]
	v_mfma_f32_16x16x32_bf16 v[122:125], v[154:157], v[178:181], v[122:125]
	v_mfma_f32_16x16x32_bf16 v[118:121], v[144:147], v[186:189], v[118:121]
	v_mfma_f32_16x16x32_bf16 v[114:117], v[154:157], v[186:189], v[114:117]
	v_mfma_f32_16x16x32_bf16 v[110:113], v[144:147], v[194:197], v[110:113]
	v_mfma_f32_16x16x32_bf16 v[106:109], v[154:157], v[194:197], v[106:109]
	v_mfma_f32_16x16x32_bf16 v[102:105], v[144:147], v[214:217], v[102:105]
	v_mfma_f32_16x16x32_bf16 v[98:101], v[154:157], v[214:217], v[98:101]
	v_mfma_f32_16x16x32_bf16 v[126:129], v[150:153], v[182:185], v[126:129]
	v_mfma_f32_16x16x32_bf16 v[122:125], v[158:161], v[182:185], v[122:125]
	v_mfma_f32_16x16x32_bf16 v[118:121], v[150:153], v[190:193], v[118:121]
	v_mfma_f32_16x16x32_bf16 v[114:117], v[158:161], v[190:193], v[114:117]
	v_mfma_f32_16x16x32_bf16 v[110:113], v[150:153], v[198:201], v[110:113]
	v_mfma_f32_16x16x32_bf16 v[106:109], v[158:161], v[198:201], v[106:109]
	v_mfma_f32_16x16x32_bf16 v[102:105], v[150:153], v[218:221], v[102:105]
	v_mfma_f32_16x16x32_bf16 v[98:101], v[158:161], v[218:221], v[98:101]
	v_mfma_f32_16x16x32_bf16 v[60:63], v[162:165], v[178:181], v[60:63]
	v_mfma_f32_16x16x32_bf16 v[56:59], v[170:173], v[178:181], v[56:59]
	v_mfma_f32_16x16x32_bf16 v[52:55], v[162:165], v[186:189], v[52:55]
	v_mfma_f32_16x16x32_bf16 v[48:51], v[170:173], v[186:189], v[48:51]
	v_mfma_f32_16x16x32_bf16 v[44:47], v[162:165], v[194:197], v[44:47]
	v_mfma_f32_16x16x32_bf16 v[40:43], v[170:173], v[194:197], v[40:43]
	v_mfma_f32_16x16x32_bf16 v[36:39], v[162:165], v[214:217], v[36:39]
	v_mfma_f32_16x16x32_bf16 v[32:35], v[170:173], v[214:217], v[32:35]
	v_mfma_f32_16x16x32_bf16 v[60:63], v[166:169], v[182:185], v[60:63]
	v_mfma_f32_16x16x32_bf16 v[56:59], v[174:177], v[182:185], v[56:59]
	v_mfma_f32_16x16x32_bf16 v[52:55], v[166:169], v[190:193], v[52:55]
	v_mfma_f32_16x16x32_bf16 v[48:51], v[174:177], v[190:193], v[48:51]
	v_mfma_f32_16x16x32_bf16 v[44:47], v[166:169], v[198:201], v[44:47]
	v_mfma_f32_16x16x32_bf16 v[40:43], v[174:177], v[198:201], v[40:43]
	v_mfma_f32_16x16x32_bf16 v[36:39], v[166:169], v[218:221], v[36:39]
	v_mfma_f32_16x16x32_bf16 v[32:35], v[174:177], v[218:221], v[32:35]
	s_setprio 0
	s_barrier
; #define PG8_STAGE(bufoff, gbase, voff) do { _Pragma("unroll") for (int _i = 0; _i < 2; ++_i) \
;         __builtin_amdgcn_global_load_lds((const unsigned*)((const char*)(gbase) + (voff)[_i]), (PG8_LAS unsigned*)(lds + (bufoff) + ldsw + _i * 8192), 16, 0, 0); } while (0)
; #define PG8_LDA(dst, b, h) do { _Pragma("unroll") for (int m = 0; m < 4; ++m) _Pragma("unroll") for (int k = 0; k < 2; ++k) dst[m][k] = *(const PG8_LAS bf16x8*)(lds + PG8_SA(b, h) + aoff + m * 2048 + k * 1024); } while (0)
; #define PG8_MMA(ai, bj, At, Bt) do { __builtin_amdgcn_s_setprio(1); _Pragma("unroll") for (int m = 0; m < 4; ++m) _Pragma("unroll") for (int n = 0; n < 2; ++n) _Pragma("unroll") for (int k = 0; k < 2; ++k) \
;         acc[ai][bj][m][n] = __builtin_amdgcn_mfma_f32_16x16x32_bf16(Bt[n][k], At[m][k], acc[ai][bj][m][n], 0, 0, 0); __builtin_amdgcn_s_setprio(0); } while (0)
; #define PG8_WAIT_V(n) asm volatile("s_waitcnt vmcnt(" #n ")" ::: "memory")
; template <class Epi, class Sched, bool ALIGN_EPI = false, bool SP2 = false>
; __device__ __forceinline__ void gemm_phase(PG8_LAS unsigned char* lds, const Gemm g, const Sched& S, const Epi& E, const int tid) {
;     ...
;             PG8_LDA(At, 1, 1); PG8_STAGE(PG8_SB(1, 0), b3, voffB); PG8_STAGE(PG8_SB(1, 1), b3 + hstep, voffB); PG8_STAGE(PG8_SA(1, 0), a3, voffA);
;             PG8_WAIT_V(8); PG8_WAIT_L(0); PG8_BAR; PG8_MMA(1, 0, At, B0); PG8_MMA(1, 1, At, B1); PG8_BAR; PG8_SCHED;
;     __device__ __forceinline__ void operator()(const f32x4 (&acc)[2][2][4][2], const Unit& u, int wr, int wc, int fr, int fq) const {
;     ...
;                 const int gcol = col - LDQ;
;                 const f32x4 b0 = *(const f32x4*)(bgate + gcol), b1 = *(const f32x4*)(bgate + gcol + 4);
; #pragma unroll
;                 for (int ai = 0; ai < 2; ++ai)
; #pragma unroll
;                     for (int m = 0; m < 4; ++m) {
;                         const int row = row0 + ai * 128 + m * 16;
;                         const f32x4 v0 = acc[ai][bj][m][0] + b0, v1 = acc[ai][bj][m][1] + b1;
;                         u32x4 w; w.x = pk2(sigmoidf_(v0[0]), sigmoidf_(v0[1])); w.y = pk2(sigmoidf_(v0[2]), sigmoidf_(v0[3]));
;                         w.z = pk2(sigmoidf_(v1[0]), sigmoidf_(v1[1])); w.w = pk2(sigmoidf_(v1[2]), sigmoidf_(v1[3]));
;                         __builtin_nontemporal_store(w, (u32x4*)(gates + (unsigned)(row * NG + gcol)));
	s_add_i32 s8, s27, s12
	v_lshl_add_u64 v[202:203], v[202:203], 0, s[94:95]
	s_mov_b32 m0, s8
	ds_read_b128 v[178:181], v143 offset:49152
	ds_read_b128 v[182:185], v143 offset:50176
	ds_read_b128 v[186:189], v143 offset:51200
	ds_read_b128 v[190:193], v143 offset:52224
	ds_read_b128 v[194:197], v143 offset:53248
	ds_read_b128 v[198:201], v143 offset:54272
	ds_read_b128 v[214:217], v143 offset:55296
	ds_read_b128 v[218:221], v143 offset:56320
	global_load_lds_dwordx4 v[202:203], off
	s_add_i32 m0, s8, 0x2000
	s_add_u32 s6, s6, 0x40080
	v_lshl_add_u64 v[202:203], v[206:207], 0, s[94:95]
	s_addc_u32 s7, s7, 0
	s_add_i32 s8, s28, s12
	global_load_lds_dwordx4 v[202:203], off
	v_lshl_add_u64 v[202:203], s[6:7], 0, v[64:65]
	s_mov_b32 m0, s8
	s_nop 0
	global_load_lds_dwordx4 v[202:203], off
	v_lshl_add_u64 v[202:203], s[6:7], 0, v[134:135]
	s_add_i32 m0, s8, 0x2000
	s_nop 0
	global_load_lds_dwordx4 v[202:203], off
	v_lshl_add_u64 v[202:203], v[208:209], 0, s[94:95]
	s_mov_b32 m0, s20
	s_nop 0
	global_load_lds_dwordx4 v[202:203], off
	v_lshl_add_u64 v[202:203], v[222:223], 0, s[94:95]
	s_mov_b32 m0, s21
	s_nop 0
	global_load_lds_dwordx4 v[202:203], off
	s_waitcnt vmcnt(8)
	s_waitcnt lgkmcnt(0)
	s_barrier
	s_setprio 1
	v_mfma_f32_16x16x32_bf16 v[94:97], v[144:147], v[178:181], v[94:97]
	v_mfma_f32_16x16x32_bf16 v[90:93], v[154:157], v[178:181], v[90:93]
	v_mfma_f32_16x16x32_bf16 v[86:89], v[144:147], v[186:189], v[86:89]
	v_mfma_f32_16x16x32_bf16 v[82:85], v[154:157], v[186:189], v[82:85]
	v_mfma_f32_16x16x32_bf16 v[78:81], v[144:147], v[194:197], v[78:81]
	v_mfma_f32_16x16x32_bf16 v[74:77], v[154:157], v[194:197], v[74:77]
	v_mfma_f32_16x16x32_bf16 v[70:73], v[144:147], v[214:217], v[70:73]
	v_mfma_f32_16x16x32_bf16 v[66:69], v[154:157], v[214:217], v[66:69]
	v_mfma_f32_16x16x32_bf16 v[94:97], v[150:153], v[182:185], v[94:97]
	v_mfma_f32_16x16x32_bf16 v[90:93], v[158:161], v[182:185], v[90:93]
	v_mfma_f32_16x16x32_bf16 v[86:89], v[150:153], v[190:193], v[86:89]
	v_mfma_f32_16x16x32_bf16 v[82:85], v[158:161], v[190:193], v[82:85]
	v_mfma_f32_16x16x32_bf16 v[78:81], v[150:153], v[198:201], v[78:81]
	v_mfma_f32_16x16x32_bf16 v[74:77], v[158:161], v[198:201], v[74:77]
	v_mfma_f32_16x16x32_bf16 v[70:73], v[150:153], v[218:221], v[70:73]
	v_mfma_f32_16x16x32_bf16 v[66:69], v[158:161], v[218:221], v[66:69]
	v_mfma_f32_16x16x32_bf16 v[28:31], v[162:165], v[178:181], v[28:31]
	v_mfma_f32_16x16x32_bf16 v[24:27], v[170:173], v[178:181], v[24:27]
	v_mfma_f32_16x16x32_bf16 v[20:23], v[162:165], v[186:189], v[20:23]
	v_mfma_f32_16x16x32_bf16 v[16:19], v[170:173], v[186:189], v[16:19]
	v_mfma_f32_16x16x32_bf16 v[12:15], v[162:165], v[194:197], v[12:15]
	v_mfma_f32_16x16x32_bf16 v[8:11], v[170:173], v[194:197], v[8:11]
	v_mfma_f32_16x16x32_bf16 v[4:7], v[162:165], v[214:217], v[4:7]
	v_mfma_f32_16x16x32_bf16 v[0:3], v[170:173], v[214:217], v[0:3]
	v_mfma_f32_16x16x32_bf16 v[28:31], v[166:169], v[182:185], v[28:31]
	v_mfma_f32_16x16x32_bf16 v[24:27], v[174:177], v[182:185], v[24:27]
	v_mfma_f32_16x16x32_bf16 v[20:23], v[166:169], v[190:193], v[20:23]
	v_mfma_f32_16x16x32_bf16 v[16:19], v[174:177], v[190:193], v[16:19]
	v_mfma_f32_16x16x32_bf16 v[12:15], v[166:169], v[198:201], v[12:15]
	v_mfma_f32_16x16x32_bf16 v[8:11], v[174:177], v[198:201], v[8:11]
	v_mfma_f32_16x16x32_bf16 v[4:7], v[166:169], v[218:221], v[4:7]
	v_mfma_f32_16x16x32_bf16 v[0:3], v[174:177], v[218:221], v[0:3]
	s_setprio 0
	s_barrier
	s_add_i32 s26, s26, 2
	s_add_u32 s4, s4, 0x100
	s_addc_u32 s5, s5, 0
	s_cmp_gt_u32 s26, 13
	s_cbranch_scc0 .LBB0_511
	s_and_b32 s12, 0xffff, s11
	s_lshl_b32 s13, s19, 8
	s_lshl_b32 s11, s12, 8
	s_and_b32 s2, s13, 0xff00
	s_and_b32 s14, 0xffff, s14
	v_or_b32_e32 v64, s15, v148
	s_cmpk_gt_u32 s14, 0x8f
	v_or_b32_e32 v186, s2, v64
	s_cselect_b64 s[2:3], -1, 0
	v_cmp_eq_u32_e64 s[0:1], 0, v141
	v_add_u32_e32 v187, s11, v140
	s_mov_b64 s[4:5], -1
	s_and_b64 vcc, exec, s[2:3]
	s_cbranch_vccz .LBB0_514
	v_add_u32_e32 v138, 0xffffee00, v186
	v_ashrrev_i32_e32 v139, 31, v138
	v_lshl_add_u64 v[134:135], v[138:139], 2, s[52:53]
	global_load_dwordx4 v[130:133], v[134:135], off offset:16
	s_nop 0
	global_load_dwordx4 v[134:137], v[134:135], off
	s_waitcnt vmcnt(0)
	v_pk_add_f32 v[146:147], v[122:123], v[130:131]
	v_pk_add_f32 v[140:141], v[126:127], v[134:135]
	v_pk_add_f32 v[142:143], v[128:129], v[136:137]
	v_mul_f32_e32 v64, 0xbfb8aa3b, v140
	v_mul_f32_e32 v139, 0xbfb8aa3b, v141
	v_exp_f32_e32 v64, v64
	v_exp_f32_e32 v139, v139
	v_pk_add_f32 v[144:145], v[124:125], v[132:133]
	v_add_f32_e32 v64, 1.0, v64
	v_add_f32_e32 v139, 1.0, v139
	v_rcp_f32_e32 v64, v64
	v_rcp_f32_e32 v139, v139
	s_nop 0
	v_cvt_pk_bf16_f32 v140, v64, v139
	v_mul_f32_e32 v64, 0xbfb8aa3b, v142
	v_mul_f32_e32 v139, 0xbfb8aa3b, v143
	v_exp_f32_e32 v64, v64
	v_exp_f32_e32 v139, v139
	v_add_f32_e32 v64, 1.0, v64
	v_add_f32_e32 v139, 1.0, v139
	v_rcp_f32_e32 v64, v64
	v_rcp_f32_e32 v139, v139
	s_nop 0
	v_cvt_pk_bf16_f32 v141, v64, v139
	v_mul_f32_e32 v64, 0xbfb8aa3b, v146
	v_mul_f32_e32 v139, 0xbfb8aa3b, v147
	v_exp_f32_e32 v64, v64
	v_exp_f32_e32 v139, v139
	v_pk_add_f32 v[146:147], v[114:115], v[130:131]
	v_add_f32_e32 v64, 1.0, v64
	v_add_f32_e32 v139, 1.0, v139
	v_rcp_f32_e32 v64, v64
	v_rcp_f32_e32 v139, v139
	s_nop 0
	v_cvt_pk_bf16_f32 v142, v64, v139
	v_mul_f32_e32 v64, 0xbfb8aa3b, v144
	v_mul_f32_e32 v139, 0xbfb8aa3b, v145
	v_exp_f32_e32 v64, v64
	v_exp_f32_e32 v139, v139
	v_add_f32_e32 v64, 1.0, v64
	v_add_f32_e32 v139, 1.0, v139
	v_rcp_f32_e32 v64, v64
	v_rcp_f32_e32 v139, v139
	s_nop 0
	v_cvt_pk_bf16_f32 v143, v64, v139
	v_mad_u64_u32 v[138:139], s[4:5], v187, s76, v[138:139]
	v_mov_b32_e32 v139, v65
; __device__ __forceinline__ unsigned pk2(float lo, float hi) { f32x2_t v = {lo, hi}; bf16x2_t b = __builtin_convertvector(v, bf16x2_t); return __builtin_bit_cast(unsigned, b); }
; __device__ __forceinline__ float sigmoidf_(float x) { return __builtin_amdgcn_rcpf(1.0f + __expf(-x)); }
;     __device__ __forceinline__ void operator()(const f32x4 (&acc)[2][2][4][2], const Unit& u, int wr, int wc, int fr, int fq) const {
;     ...
;                 const int gcol = col - LDQ;
;                 const f32x4 b0 = *(const f32x4*)(bgate + gcol), b1 = *(const f32x4*)(bgate + gcol + 4);
; #pragma unroll
;                 for (int ai = 0; ai < 2; ++ai)
; #pragma unroll
;                     for (int m = 0; m < 4; ++m) {
;                         const int row = row0 + ai * 128 + m * 16;
;                         const f32x4 v0 = acc[ai][bj][m][0] + b0, v1 = acc[ai][bj][m][1] + b1;
;                         u32x4 w; w.x = pk2(sigmoidf_(v0[0]), sigmoidf_(v0[1])); w.y = pk2(sigmoidf_(v0[2]), sigmoidf_(v0[3]));
;                         w.z = pk2(sigmoidf_(v1[0]), sigmoidf_(v1[1])); w.w = pk2(sigmoidf_(v1[2]), sigmoidf_(v1[3]));
;                         __builtin_nontemporal_store(w, (u32x4*)(gates + (unsigned)(row * NG + gcol)));
;                     }
	v_lshl_add_u64 v[144:145], v[138:139], 1, s[36:37]
	flat_store_dwordx4 v[144:145], v[140:143] nt
	v_pk_add_f32 v[144:145], v[116:117], v[132:133]
	s_mov_b64 s[4:5], 0
	v_pk_add_f32 v[140:141], v[118:119], v[134:135]
	v_pk_add_f32 v[142:143], v[120:121], v[136:137]
	v_mul_f32_e32 v64, 0xbfb8aa3b, v140
	v_mul_f32_e32 v139, 0xbfb8aa3b, v141
	v_exp_f32_e32 v64, v64
	v_exp_f32_e32 v139, v139
	v_add_f32_e32 v64, 1.0, v64
	v_add_f32_e32 v139, 1.0, v139
	v_rcp_f32_e32 v64, v64
	v_rcp_f32_e32 v139, v139
	s_nop 0
	v_cvt_pk_bf16_f32 v140, v64, v139
	v_mul_f32_e32 v64, 0xbfb8aa3b, v142
	v_mul_f32_e32 v139, 0xbfb8aa3b, v143
	v_exp_f32_e32 v64, v64
	v_exp_f32_e32 v139, v139
	v_add_f32_e32 v64, 1.0, v64
	v_add_f32_e32 v139, 1.0, v139
	v_rcp_f32_e32 v64, v64
	v_rcp_f32_e32 v139, v139
	s_nop 0
	v_cvt_pk_bf16_f32 v141, v64, v139
	v_mul_f32_e32 v64, 0xbfb8aa3b, v146
	v_mul_f32_e32 v139, 0xbfb8aa3b, v147
	v_exp_f32_e32 v64, v64
	v_exp_f32_e32 v139, v139
	v_pk_add_f32 v[146:147], v[110:111], v[134:135]
	v_add_f32_e32 v64, 1.0, v64
	v_add_f32_e32 v139, 1.0, v139
	v_rcp_f32_e32 v64, v64
	v_rcp_f32_e32 v139, v139
	s_nop 0
	v_cvt_pk_bf16_f32 v142, v64, v139
	v_mul_f32_e32 v64, 0xbfb8aa3b, v144
	v_mul_f32_e32 v139, 0xbfb8aa3b, v145
	v_exp_f32_e32 v64, v64
	v_exp_f32_e32 v139, v139
	v_add_f32_e32 v64, 1.0, v64
	v_add_f32_e32 v139, 1.0, v139
	v_rcp_f32_e32 v64, v64
	v_rcp_f32_e32 v139, v139
	s_nop 0
	v_cvt_pk_bf16_f32 v143, v64, v139
	v_add_u32_e32 v64, 0xc000, v138
	v_lshl_add_u64 v[144:145], v[64:65], 1, s[36:37]
	v_mul_f32_e32 v64, 0xbfb8aa3b, v146
	v_mul_f32_e32 v139, 0xbfb8aa3b, v147
	v_exp_f32_e32 v64, v64
	v_exp_f32_e32 v139, v139
	flat_store_dwordx4 v[144:145], v[140:143] nt
	v_pk_add_f32 v[144:145], v[112:113], v[136:137]
	v_add_f32_e32 v64, 1.0, v64
	v_add_f32_e32 v139, 1.0, v139
	v_rcp_f32_e32 v64, v64
	v_rcp_f32_e32 v139, v139
	v_pk_add_f32 v[142:143], v[106:107], v[130:131]
	v_pk_add_f32 v[140:141], v[108:109], v[132:133]
	v_pk_add_f32 v[146:147], v[98:99], v[130:131]
	v_cvt_pk_bf16_f32 v150, v64, v139
	v_mul_f32_e32 v64, 0xbfb8aa3b, v144
	v_mul_f32_e32 v139, 0xbfb8aa3b, v145
	v_exp_f32_e32 v64, v64
	v_exp_f32_e32 v139, v139
	v_pk_add_f32 v[144:145], v[100:101], v[132:133]
	v_add_f32_e32 v64, 1.0, v64
	v_add_f32_e32 v139, 1.0, v139
	v_rcp_f32_e32 v64, v64
	v_rcp_f32_e32 v139, v139
	s_nop 0
	v_cvt_pk_bf16_f32 v151, v64, v139
	v_mul_f32_e32 v64, 0xbfb8aa3b, v142
	v_mul_f32_e32 v139, 0xbfb8aa3b, v143
	v_exp_f32_e32 v64, v64
	v_exp_f32_e32 v139, v139
	v_pk_add_f32 v[142:143], v[104:105], v[136:137]
	v_add_f32_e32 v64, 1.0, v64
	v_add_f32_e32 v139, 1.0, v139
	v_rcp_f32_e32 v64, v64
	v_rcp_f32_e32 v139, v139
	s_nop 0
	v_cvt_pk_bf16_f32 v152, v64, v139
	v_mul_f32_e32 v64, 0xbfb8aa3b, v140
	v_mul_f32_e32 v139, 0xbfb8aa3b, v141
	v_exp_f32_e32 v64, v64
	v_exp_f32_e32 v139, v139
	v_add_f32_e32 v64, 1.0, v64
	v_add_f32_e32 v139, 1.0, v139
	v_rcp_f32_e32 v64, v64
	v_rcp_f32_e32 v139, v139
	s_nop 0
	v_cvt_pk_bf16_f32 v153, v64, v139
	v_add_u32_e32 v64, 0x18000, v138
	v_lshl_add_u64 v[140:141], v[64:65], 1, s[36:37]
	flat_store_dwordx4 v[140:141], v[150:153] nt
	v_pk_add_f32 v[140:141], v[102:103], v[134:135]
	s_nop 0
	v_mul_f32_e32 v64, 0xbfb8aa3b, v140
	v_mul_f32_e32 v139, 0xbfb8aa3b, v141
	v_exp_f32_e32 v64, v64
	v_exp_f32_e32 v139, v139
	v_add_f32_e32 v64, 1.0, v64
	v_add_f32_e32 v139, 1.0, v139
	v_rcp_f32_e32 v64, v64
	v_rcp_f32_e32 v139, v139
	s_nop 0
	v_cvt_pk_bf16_f32 v140, v64, v139
	v_mul_f32_e32 v64, 0xbfb8aa3b, v142
	v_mul_f32_e32 v139, 0xbfb8aa3b, v143
	v_exp_f32_e32 v64, v64
	v_exp_f32_e32 v139, v139
	v_add_f32_e32 v64, 1.0, v64
	v_add_f32_e32 v139, 1.0, v139
	v_rcp_f32_e32 v64, v64
	v_rcp_f32_e32 v139, v139
	s_nop 0
	v_cvt_pk_bf16_f32 v141, v64, v139
	v_mul_f32_e32 v64, 0xbfb8aa3b, v146
	v_mul_f32_e32 v139, 0xbfb8aa3b, v147
	v_exp_f32_e32 v64, v64
	v_exp_f32_e32 v139, v139
	v_pk_add_f32 v[146:147], v[90:91], v[130:131]
	v_add_f32_e32 v64, 1.0, v64
	v_add_f32_e32 v139, 1.0, v139
	v_rcp_f32_e32 v64, v64
	v_rcp_f32_e32 v139, v139
	s_nop 0
	v_cvt_pk_bf16_f32 v142, v64, v139
	v_mul_f32_e32 v64, 0xbfb8aa3b, v144
	v_mul_f32_e32 v139, 0xbfb8aa3b, v145
	v_exp_f32_e32 v64, v64
	v_exp_f32_e32 v139, v139
	v_add_f32_e32 v64, 1.0, v64
	v_add_f32_e32 v139, 1.0, v139
	v_rcp_f32_e32 v64, v64
	v_rcp_f32_e32 v139, v139
	s_nop 0
	v_cvt_pk_bf16_f32 v143, v64, v139
	v_add_u32_e32 v64, 0x24000, v138
	v_lshl_add_u64 v[144:145], v[64:65], 1, s[36:37]
	flat_store_dwordx4 v[144:145], v[140:143] nt
	v_pk_add_f32 v[144:145], v[92:93], v[132:133]
	s_nop 0
	v_pk_add_f32 v[140:141], v[94:95], v[134:135]
	v_pk_add_f32 v[142:143], v[96:97], v[136:137]
	v_mul_f32_e32 v64, 0xbfb8aa3b, v140
	v_mul_f32_e32 v139, 0xbfb8aa3b, v141
	v_exp_f32_e32 v64, v64
	v_exp_f32_e32 v139, v139
	v_add_f32_e32 v64, 1.0, v64
	v_add_f32_e32 v139, 1.0, v139
	v_rcp_f32_e32 v64, v64
	v_rcp_f32_e32 v139, v139
	s_nop 0
	v_cvt_pk_bf16_f32 v140, v64, v139
	v_mul_f32_e32 v64, 0xbfb8aa3b, v142
	v_mul_f32_e32 v139, 0xbfb8aa3b, v143
	v_exp_f32_e32 v64, v64
	v_exp_f32_e32 v139, v139
	v_add_f32_e32 v64, 1.0, v64
	v_add_f32_e32 v139, 1.0, v139
	v_rcp_f32_e32 v64, v64
; __device__ __forceinline__ unsigned pk2(float lo, float hi) { f32x2_t v = {lo, hi}; bf16x2_t b = __builtin_convertvector(v, bf16x2_t); return __builtin_bit_cast(unsigned, b); }
; __device__ __forceinline__ float sigmoidf_(float x) { return __builtin_amdgcn_rcpf(1.0f + __expf(-x)); }
;     __device__ __forceinline__ void operator()(const f32x4 (&acc)[2][2][4][2], const Unit& u, int wr, int wc, int fr, int fq) const {
;     ...
;                 const int gcol = col - LDQ;
;                 const f32x4 b0 = *(const f32x4*)(bgate + gcol), b1 = *(const f32x4*)(bgate + gcol + 4);
; #pragma unroll
;                 for (int ai = 0; ai < 2; ++ai)
; #pragma unroll
;                     for (int m = 0; m < 4; ++m) {
;                         const int row = row0 + ai * 128 + m * 16;
;                         const f32x4 v0 = acc[ai][bj][m][0] + b0, v1 = acc[ai][bj][m][1] + b1;
;                         u32x4 w; w.x = pk2(sigmoidf_(v0[0]), sigmoidf_(v0[1])); w.y = pk2(sigmoidf_(v0[2]), sigmoidf_(v0[3]));
;                         w.z = pk2(sigmoidf_(v1[0]), sigmoidf_(v1[1])); w.w = pk2(sigmoidf_(v1[2]), sigmoidf_(v1[3]));
;                         __builtin_nontemporal_store(w, (u32x4*)(gates + (unsigned)(row * NG + gcol)));
;                     }
	v_rcp_f32_e32 v139, v139
	s_nop 0
	v_cvt_pk_bf16_f32 v141, v64, v139
	v_mul_f32_e32 v64, 0xbfb8aa3b, v146
	v_mul_f32_e32 v139, 0xbfb8aa3b, v147
	v_exp_f32_e32 v64, v64
	v_exp_f32_e32 v139, v139
	v_pk_add_f32 v[146:147], v[82:83], v[130:131]
	v_add_f32_e32 v64, 1.0, v64
	v_add_f32_e32 v139, 1.0, v139
	v_rcp_f32_e32 v64, v64
	v_rcp_f32_e32 v139, v139
	s_nop 0
	v_cvt_pk_bf16_f32 v142, v64, v139
	v_mul_f32_e32 v64, 0xbfb8aa3b, v144
	v_mul_f32_e32 v139, 0xbfb8aa3b, v145
	v_exp_f32_e32 v64, v64
	v_exp_f32_e32 v139, v139
	v_add_f32_e32 v64, 1.0, v64
	v_add_f32_e32 v139, 1.0, v139
	v_rcp_f32_e32 v64, v64
	v_rcp_f32_e32 v139, v139
	s_nop 0
	v_cvt_pk_bf16_f32 v143, v64, v139
	v_add_u32_e32 v64, 0x60000, v138
	v_lshl_add_u64 v[144:145], v[64:65], 1, s[36:37]
	flat_store_dwordx4 v[144:145], v[140:143] nt
	v_pk_add_f32 v[144:145], v[84:85], v[132:133]
	s_nop 0
	v_pk_add_f32 v[140:141], v[86:87], v[134:135]
	v_pk_add_f32 v[142:143], v[88:89], v[136:137]
	v_mul_f32_e32 v64, 0xbfb8aa3b, v140
	v_mul_f32_e32 v139, 0xbfb8aa3b, v141
	v_exp_f32_e32 v64, v64
	v_exp_f32_e32 v139, v139
	v_add_f32_e32 v64, 1.0, v64
	v_add_f32_e32 v139, 1.0, v139
	v_rcp_f32_e32 v64, v64
	v_rcp_f32_e32 v139, v139
	s_nop 0
	v_cvt_pk_bf16_f32 v140, v64, v139
	v_mul_f32_e32 v64, 0xbfb8aa3b, v142
	v_mul_f32_e32 v139, 0xbfb8aa3b, v143
	v_exp_f32_e32 v64, v64
	v_exp_f32_e32 v139, v139
	v_add_f32_e32 v64, 1.0, v64
	v_add_f32_e32 v139, 1.0, v139
	v_rcp_f32_e32 v64, v64
	v_rcp_f32_e32 v139, v139
	s_nop 0
	v_cvt_pk_bf16_f32 v141, v64, v139
	v_mul_f32_e32 v64, 0xbfb8aa3b, v146
	v_mul_f32_e32 v139, 0xbfb8aa3b, v147
	v_exp_f32_e32 v64, v64
	v_exp_f32_e32 v139, v139
	v_pk_add_f32 v[146:147], v[74:75], v[130:131]
	v_add_f32_e32 v64, 1.0, v64
	v_add_f32_e32 v139, 1.0, v139
	v_rcp_f32_e32 v64, v64
	v_rcp_f32_e32 v139, v139
	s_nop 0
	v_cvt_pk_bf16_f32 v142, v64, v139
	v_mul_f32_e32 v64, 0xbfb8aa3b, v144
	v_mul_f32_e32 v139, 0xbfb8aa3b, v145
	v_exp_f32_e32 v64, v64
	v_exp_f32_e32 v139, v139
	v_add_f32_e32 v64, 1.0, v64
	v_add_f32_e32 v139, 1.0, v139
	v_rcp_f32_e32 v64, v64
	v_rcp_f32_e32 v139, v139
	s_nop 0
	v_cvt_pk_bf16_f32 v143, v64, v139
	v_add_u32_e32 v64, 0x6c000, v138
	v_lshl_add_u64 v[144:145], v[64:65], 1, s[36:37]
	flat_store_dwordx4 v[144:145], v[140:143] nt
	v_pk_add_f32 v[144:145], v[76:77], v[132:133]
	s_nop 0
	v_pk_add_f32 v[140:141], v[78:79], v[134:135]
	v_pk_add_f32 v[142:143], v[80:81], v[136:137]
	v_mul_f32_e32 v64, 0xbfb8aa3b, v140
	v_mul_f32_e32 v139, 0xbfb8aa3b, v141
	v_exp_f32_e32 v64, v64
	v_exp_f32_e32 v139, v139
	v_pk_add_f32 v[134:135], v[70:71], v[134:135]
	v_pk_add_f32 v[136:137], v[72:73], v[136:137]
	v_add_f32_e32 v64, 1.0, v64
	v_add_f32_e32 v139, 1.0, v139
	v_rcp_f32_e32 v64, v64
	v_rcp_f32_e32 v139, v139
	s_nop 0
	v_cvt_pk_bf16_f32 v140, v64, v139
	v_mul_f32_e32 v64, 0xbfb8aa3b, v142
	v_mul_f32_e32 v139, 0xbfb8aa3b, v143
	v_exp_f32_e32 v64, v64
	v_exp_f32_e32 v139, v139
	v_add_f32_e32 v64, 1.0, v64
	v_add_f32_e32 v139, 1.0, v139
	v_rcp_f32_e32 v64, v64
	v_rcp_f32_e32 v139, v139
	s_nop 0
	v_cvt_pk_bf16_f32 v141, v64, v139
	v_mul_f32_e32 v64, 0xbfb8aa3b, v146
	v_mul_f32_e32 v139, 0xbfb8aa3b, v147
	v_exp_f32_e32 v64, v64
	v_exp_f32_e32 v139, v139
	v_add_f32_e32 v64, 1.0, v64
	v_add_f32_e32 v139, 1.0, v139
	v_rcp_f32_e32 v64, v64
	v_rcp_f32_e32 v139, v139
	s_nop 0
	v_cvt_pk_bf16_f32 v142, v64, v139
	v_mul_f32_e32 v64, 0xbfb8aa3b, v144
	v_mul_f32_e32 v139, 0xbfb8aa3b, v145
	v_exp_f32_e32 v64, v64
	v_exp_f32_e32 v139, v139
	v_add_f32_e32 v64, 1.0, v64
	v_add_f32_e32 v139, 1.0, v139
	v_rcp_f32_e32 v64, v64
	v_rcp_f32_e32 v139, v139
	s_nop 0
	v_cvt_pk_bf16_f32 v143, v64, v139
	v_add_u32_e32 v64, 0x78000, v138
	v_lshl_add_u64 v[144:145], v[64:65], 1, s[36:37]
	flat_store_dwordx4 v[144:145], v[140:143] nt
	v_mul_f32_e32 v64, 0xbfb8aa3b, v134
	v_exp_f32_e32 v64, v64
	v_pk_add_f32 v[140:141], v[68:69], v[132:133]
	v_pk_add_f32 v[132:133], v[66:67], v[130:131]
	v_mul_f32_e32 v130, 0xbfb8aa3b, v135
	v_exp_f32_e32 v130, v130
	v_add_f32_e32 v64, 1.0, v64
	v_rcp_f32_e32 v64, v64
	v_mul_f32_e32 v131, 0xbfb8aa3b, v137
	v_add_f32_e32 v130, 1.0, v130
	v_rcp_f32_e32 v130, v130
	v_exp_f32_e32 v131, v131
	v_cvt_pk_bf16_f32 v130, v64, v130
	v_mul_f32_e32 v64, 0xbfb8aa3b, v136
	v_exp_f32_e32 v64, v64
	v_add_f32_e32 v131, 1.0, v131
	v_rcp_f32_e32 v131, v131
	v_add_f32_e32 v64, 1.0, v64
	v_rcp_f32_e32 v64, v64
	s_nop 0
	v_cvt_pk_bf16_f32 v131, v64, v131
	v_mul_f32_e32 v64, 0xbfb8aa3b, v132
	v_mul_f32_e32 v132, 0xbfb8aa3b, v133
	v_exp_f32_e32 v64, v64
	v_exp_f32_e32 v132, v132
	v_mul_f32_e32 v133, 0xbfb8aa3b, v141
	v_exp_f32_e32 v133, v133
	v_add_f32_e32 v64, 1.0, v64
	v_add_f32_e32 v132, 1.0, v132
	v_rcp_f32_e32 v64, v64
	v_rcp_f32_e32 v132, v132
	v_add_f32_e32 v133, 1.0, v133
	v_rcp_f32_e32 v133, v133
	v_cvt_pk_bf16_f32 v132, v64, v132
	v_mul_f32_e32 v64, 0xbfb8aa3b, v140
	v_exp_f32_e32 v64, v64
	s_nop 0
	v_add_f32_e32 v64, 1.0, v64
	v_rcp_f32_e32 v64, v64
	s_nop 0
	v_cvt_pk_bf16_f32 v133, v64, v133
	v_add_u32_e32 v64, 0x84000, v138
	v_lshl_add_u64 v[134:135], v[64:65], 1, s[36:37]
	flat_store_dwordx4 v[134:135], v[130:133] nt

; #define PG8_STAGE(bufoff, gbase, voff) do { _Pragma("unroll") for (int _i = 0; _i < 2; ++_i) \
;         __builtin_amdgcn_global_load_lds((const unsigned*)((const char*)(gbase) + (voff)[_i]), (PG8_LAS unsigned*)(lds + (bufoff) + ldsw + _i * 8192), 16, 0, 0); } while (0)
; #define PG8_LDA(dst, b, h) do { _Pragma("unroll") for (int m = 0; m < 4; ++m) _Pragma("unroll") for (int k = 0; k < 2; ++k) dst[m][k] = *(const PG8_LAS bf16x8*)(lds + PG8_SA(b, h) + aoff + m * 2048 + k * 1024); } while (0)
; #define PG8_LDB(dst, b, h) do { _Pragma("unroll") for (int n = 0; n < 2; ++n) _Pragma("unroll") for (int k = 0; k < 2; ++k) dst[n][k] = *(const PG8_LAS bf16x8*)(lds + PG8_SB(b, h) + boff + n * 2048 + k * 1024); } while (0)
; #define PG8_MMA(ai, bj, At, Bt) do { __builtin_amdgcn_s_setprio(1); _Pragma("unroll") for (int m = 0; m < 4; ++m) _Pragma("unroll") for (int n = 0; n < 2; ++n) _Pragma("unroll") for (int k = 0; k < 2; ++k) \
;         acc[ai][bj][m][n] = __builtin_amdgcn_mfma_f32_16x16x32_bf16(Bt[n][k], At[m][k], acc[ai][bj][m][n], 0, 0, 0); __builtin_amdgcn_s_setprio(0); } while (0)
; #define PG8_WAIT_V(n) asm volatile("s_waitcnt vmcnt(" #n ")" ::: "memory")
; #define PG8_WAIT_L(n) asm volatile("s_waitcnt lgkmcnt(" #n ")" ::: "memory")
; template <class Epi, class Sched, bool ALIGN_EPI = false, bool SP2 = false>
; __device__ __forceinline__ void gemm_phase(PG8_LAS unsigned char* lds, const Gemm g, const Sched& S, const Epi& E, const int tid) {
;     ...
;             const bool last = (t == nt - 2);
;             const char* a1 = cA + (size_t)(t + 1) * kstep;
;             const char* a2 = last ? nA : cA + (size_t)(t + 2) * kstep; const char* b2 = last ? nB : cB + (size_t)(t + 2) * kstep;
;             const char* a3 = a2 + kstep; const char* b3 = b2 + kstep;
;             if (last && has_next) S.a_ready(nxt);
;             if constexpr (SP2) {
;             PG8_LDB(B0, 0, 0); PG8_LDB(B1, 0, 1); PG8_SCHED; PG8_LDA(At, 0, 0); PG8_STAGE(PG8_SA(1, 1), a1 + hstep, voffA);
;             PG8_WAIT_V(8); PG8_WAIT_L(0); PG8_BAR; PG8_MMA(0, 0, At, B0); PG8_MMA(0, 1, At, B1); PG8_BAR; PG8_SCHED;
;             PG8_LDA(At, 0, 1); PG8_STAGE(PG8_SB(0, 0), b2, voffB); PG8_STAGE(PG8_SB(0, 1), b2 + hstep, voffB); PG8_STAGE(PG8_SA(0, 0), a2, voffA);
;             PG8_WAIT_V(8); PG8_WAIT_L(0); PG8_BAR; PG8_MMA(1, 0, At, B0); PG8_MMA(1, 1, At, B1); PG8_BAR; PG8_SCHED;
.LBB0_704:
	s_add_u32 s24, s2, 0xfffc0080
	s_addc_u32 s25, s3, -1
	s_add_i32 s51, 0, 0x10000
	s_cmp_eq_u32 s50, 12
	s_cselect_b32 s27, s17, s25
	s_cselect_b32 s26, s29, s24
	v_add_u32_e32 v64, s51, v213
	s_cselect_b32 s25, s15, s49
	s_cselect_b32 s24, s47, s48
	s_add_i32 s54, 0, 0x14000
	ds_read_b128 v[130:133], v64
	ds_read_b128 v[134:137], v64 offset:1024
	ds_read_b128 v[138:141], v64 offset:2048
	ds_read_b128 v[142:145], v64 offset:3072
	v_add_u32_e32 v64, s54, v213
	ds_read_b128 v[146:149], v64
	ds_read_b128 v[150:153], v64 offset:1024
	ds_read_b128 v[154:157], v64 offset:2048
	ds_read_b128 v[158:161], v64 offset:3072
	v_lshl_add_u64 v[202:203], s[2:3], 0, v[198:199]
	s_add_i32 m0, s35, 0xc000
	ds_read_b128 v[162:165], v227
	ds_read_b128 v[166:169], v227 offset:1024
	ds_read_b128 v[170:173], v227 offset:2048
	ds_read_b128 v[174:177], v227 offset:3072
	ds_read_b128 v[178:181], v227 offset:4096
	ds_read_b128 v[182:185], v227 offset:5120
	ds_read_b128 v[218:221], v227 offset:6144
	ds_read_b128 v[222:225], v227 offset:7168
	global_load_lds_dwordx4 v[202:203], off
	v_lshl_add_u64 v[202:203], s[2:3], 0, v[196:197]
	s_add_i32 m0, s35, 0xe000
	s_nop 0
	global_load_lds_dwordx4 v[202:203], off
	s_waitcnt vmcnt(8)
	s_waitcnt lgkmcnt(0)
	s_barrier
	s_setprio 1
	v_mfma_f32_16x16x32_bf16 v[126:129], v[130:133], v[162:165], v[126:129]
	v_mfma_f32_16x16x32_bf16 v[122:125], v[138:141], v[162:165], v[122:125]
	v_mfma_f32_16x16x32_bf16 v[118:121], v[130:133], v[170:173], v[118:121]
	v_mfma_f32_16x16x32_bf16 v[114:117], v[138:141], v[170:173], v[114:117]
	v_mfma_f32_16x16x32_bf16 v[110:113], v[130:133], v[178:181], v[110:113]
	v_mfma_f32_16x16x32_bf16 v[106:109], v[138:141], v[178:181], v[106:109]
	v_mfma_f32_16x16x32_bf16 v[102:105], v[130:133], v[218:221], v[102:105]
	v_mfma_f32_16x16x32_bf16 v[98:101], v[138:141], v[218:221], v[98:101]
	v_mfma_f32_16x16x32_bf16 v[126:129], v[134:137], v[166:169], v[126:129]
	v_mfma_f32_16x16x32_bf16 v[122:125], v[142:145], v[166:169], v[122:125]
	v_mfma_f32_16x16x32_bf16 v[118:121], v[134:137], v[174:177], v[118:121]
	v_mfma_f32_16x16x32_bf16 v[114:117], v[142:145], v[174:177], v[114:117]
	v_mfma_f32_16x16x32_bf16 v[110:113], v[134:137], v[182:185], v[110:113]
	v_mfma_f32_16x16x32_bf16 v[106:109], v[142:145], v[182:185], v[106:109]
	v_mfma_f32_16x16x32_bf16 v[102:105], v[134:137], v[222:225], v[102:105]
	v_mfma_f32_16x16x32_bf16 v[98:101], v[142:145], v[222:225], v[98:101]
	v_mfma_f32_16x16x32_bf16 v[60:63], v[146:149], v[162:165], v[60:63]
	v_mfma_f32_16x16x32_bf16 v[56:59], v[154:157], v[162:165], v[56:59]
	v_mfma_f32_16x16x32_bf16 v[52:55], v[146:149], v[170:173], v[52:55]
	v_mfma_f32_16x16x32_bf16 v[48:51], v[154:157], v[170:173], v[48:51]
	v_mfma_f32_16x16x32_bf16 v[44:47], v[146:149], v[178:181], v[44:47]
	v_mfma_f32_16x16x32_bf16 v[40:43], v[154:157], v[178:181], v[40:43]
	v_mfma_f32_16x16x32_bf16 v[36:39], v[146:149], v[218:221], v[36:39]
	v_mfma_f32_16x16x32_bf16 v[32:35], v[154:157], v[218:221], v[32:35]
	v_mfma_f32_16x16x32_bf16 v[60:63], v[150:153], v[166:169], v[60:63]
	v_mfma_f32_16x16x32_bf16 v[56:59], v[158:161], v[166:169], v[56:59]
	v_mfma_f32_16x16x32_bf16 v[52:55], v[150:153], v[174:177], v[52:55]
	v_mfma_f32_16x16x32_bf16 v[48:51], v[158:161], v[174:177], v[48:51]
	v_mfma_f32_16x16x32_bf16 v[44:47], v[150:153], v[182:185], v[44:47]
	v_mfma_f32_16x16x32_bf16 v[40:43], v[158:161], v[182:185], v[40:43]
	v_mfma_f32_16x16x32_bf16 v[36:39], v[150:153], v[222:225], v[36:39]
	v_mfma_f32_16x16x32_bf16 v[32:35], v[158:161], v[222:225], v[32:35]
	s_setprio 0
	s_barrier
	s_add_i32 s51, s51, s34
	v_lshl_add_u64 v[202:203], s[24:25], 0, v[190:191]
	s_mov_b32 m0, s51
	ds_read_b128 v[162:165], v227 offset:16384
	ds_read_b128 v[166:169], v227 offset:17408
	ds_read_b128 v[170:173], v227 offset:18432
	ds_read_b128 v[174:177], v227 offset:19456
	ds_read_b128 v[178:181], v227 offset:20480
	ds_read_b128 v[182:185], v227 offset:21504
	ds_read_b128 v[218:221], v227 offset:22528
	ds_read_b128 v[222:225], v227 offset:23552
	global_load_lds_dwordx4 v[202:203], off
	s_add_i32 m0, s51, 0x2000
	s_add_u32 s52, s24, 0x40000
	v_lshl_add_u64 v[206:207], s[24:25], 0, v[186:187]
	s_addc_u32 s53, s25, 0
	s_add_i32 s51, s54, s34
	global_load_lds_dwordx4 v[206:207], off
	v_lshl_add_u64 v[208:209], s[52:53], 0, v[190:191]
	s_mov_b32 m0, s51
	v_lshl_add_u64 v[214:215], s[26:27], 0, v[188:189]
	global_load_lds_dwordx4 v[208:209], off
	v_lshl_add_u64 v[208:209], s[52:53], 0, v[186:187]
	s_add_i32 m0, s51, 0x2000
	s_nop 0
	global_load_lds_dwordx4 v[208:209], off
	v_lshl_add_u64 v[208:209], s[26:27], 0, v[192:193]
	s_mov_b32 m0, s35
	s_nop 0
	global_load_lds_dwordx4 v[208:209], off
	s_mov_b32 m0, s39
	s_nop 0
	global_load_lds_dwordx4 v[214:215], off
	s_waitcnt vmcnt(8)
	s_waitcnt lgkmcnt(0)
	s_barrier
; #define PG8_STAGE(bufoff, gbase, voff) do { _Pragma("unroll") for (int _i = 0; _i < 2; ++_i) \
;         __builtin_amdgcn_global_load_lds((const unsigned*)((const char*)(gbase) + (voff)[_i]), (PG8_LAS unsigned*)(lds + (bufoff) + ldsw + _i * 8192), 16, 0, 0); } while (0)
; #define PG8_LDA(dst, b, h) do { _Pragma("unroll") for (int m = 0; m < 4; ++m) _Pragma("unroll") for (int k = 0; k < 2; ++k) dst[m][k] = *(const PG8_LAS bf16x8*)(lds + PG8_SA(b, h) + aoff + m * 2048 + k * 1024); } while (0)
; #define PG8_LDB(dst, b, h) do { _Pragma("unroll") for (int n = 0; n < 2; ++n) _Pragma("unroll") for (int k = 0; k < 2; ++k) dst[n][k] = *(const PG8_LAS bf16x8*)(lds + PG8_SB(b, h) + boff + n * 2048 + k * 1024); } while (0)
; #define PG8_MMA(ai, bj, At, Bt) do { __builtin_amdgcn_s_setprio(1); _Pragma("unroll") for (int m = 0; m < 4; ++m) _Pragma("unroll") for (int n = 0; n < 2; ++n) _Pragma("unroll") for (int k = 0; k < 2; ++k) \
;         acc[ai][bj][m][n] = __builtin_amdgcn_mfma_f32_16x16x32_bf16(Bt[n][k], At[m][k], acc[ai][bj][m][n], 0, 0, 0); __builtin_amdgcn_s_setprio(0); } while (0)
; #define PG8_WAIT_V(n) asm volatile("s_waitcnt vmcnt(" #n ")" ::: "memory")
; #define PG8_WAIT_L(n) asm volatile("s_waitcnt lgkmcnt(" #n ")" ::: "memory")
; #define PG8_BAR __builtin_amdgcn_s_barrier()
; #define PG8_SCHED __builtin_amdgcn_sched_barrier(0)
; template <class Epi, class Sched, bool ALIGN_EPI = false, bool SP2 = false>
; __device__ __forceinline__ void gemm_phase(PG8_LAS unsigned char* lds, const Gemm g, const Sched& S, const Epi& E, const int tid) {
;     ...
;             PG8_WAIT_V(8); PG8_WAIT_L(0); PG8_BAR; PG8_MMA(1, 0, At, B0); PG8_MMA(1, 1, At, B1); PG8_BAR; PG8_SCHED;
;             PG8_LDB(B0, 1, 0); PG8_LDB(B1, 1, 1); PG8_SCHED; PG8_LDA(At, 1, 0); PG8_STAGE(PG8_SA(0, 1), a2 + hstep, voffA);
;             PG8_WAIT_V(8); PG8_WAIT_L(0); PG8_BAR; PG8_MMA(0, 0, At, B0); PG8_MMA(0, 1, At, B1); PG8_BAR; PG8_SCHED;
	s_setprio 1
	v_mfma_f32_16x16x32_bf16 v[94:97], v[130:133], v[162:165], v[94:97]
	v_mfma_f32_16x16x32_bf16 v[90:93], v[138:141], v[162:165], v[90:93]
	v_mfma_f32_16x16x32_bf16 v[86:89], v[130:133], v[170:173], v[86:89]
	v_mfma_f32_16x16x32_bf16 v[82:85], v[138:141], v[170:173], v[82:85]
	v_mfma_f32_16x16x32_bf16 v[78:81], v[130:133], v[178:181], v[78:81]
	v_mfma_f32_16x16x32_bf16 v[74:77], v[138:141], v[178:181], v[74:77]
	v_mfma_f32_16x16x32_bf16 v[70:73], v[130:133], v[218:221], v[70:73]
	v_mfma_f32_16x16x32_bf16 v[66:69], v[138:141], v[218:221], v[66:69]
	v_mfma_f32_16x16x32_bf16 v[94:97], v[134:137], v[166:169], v[94:97]
	v_mfma_f32_16x16x32_bf16 v[90:93], v[142:145], v[166:169], v[90:93]
	v_mfma_f32_16x16x32_bf16 v[86:89], v[134:137], v[174:177], v[86:89]
	v_mfma_f32_16x16x32_bf16 v[82:85], v[142:145], v[174:177], v[82:85]
	v_mfma_f32_16x16x32_bf16 v[78:81], v[134:137], v[182:185], v[78:81]
	v_mfma_f32_16x16x32_bf16 v[74:77], v[142:145], v[182:185], v[74:77]
	v_mfma_f32_16x16x32_bf16 v[70:73], v[134:137], v[222:225], v[70:73]
	v_mfma_f32_16x16x32_bf16 v[66:69], v[142:145], v[222:225], v[66:69]
	v_mfma_f32_16x16x32_bf16 v[28:31], v[146:149], v[162:165], v[28:31]
	v_mfma_f32_16x16x32_bf16 v[24:27], v[154:157], v[162:165], v[24:27]
	v_mfma_f32_16x16x32_bf16 v[20:23], v[146:149], v[170:173], v[20:23]
	v_mfma_f32_16x16x32_bf16 v[16:19], v[154:157], v[170:173], v[16:19]
	v_mfma_f32_16x16x32_bf16 v[12:15], v[146:149], v[178:181], v[12:15]
	v_mfma_f32_16x16x32_bf16 v[8:11], v[154:157], v[178:181], v[8:11]
	v_mfma_f32_16x16x32_bf16 v[4:7], v[146:149], v[218:221], v[4:7]
	v_mfma_f32_16x16x32_bf16 v[0:3], v[154:157], v[218:221], v[0:3]
	v_mfma_f32_16x16x32_bf16 v[28:31], v[150:153], v[166:169], v[28:31]
	v_mfma_f32_16x16x32_bf16 v[24:27], v[158:161], v[166:169], v[24:27]
	v_mfma_f32_16x16x32_bf16 v[20:23], v[150:153], v[174:177], v[20:23]
	v_mfma_f32_16x16x32_bf16 v[16:19], v[158:161], v[174:177], v[16:19]
	v_mfma_f32_16x16x32_bf16 v[12:15], v[150:153], v[182:185], v[12:15]
	v_mfma_f32_16x16x32_bf16 v[8:11], v[158:161], v[182:185], v[8:11]
	v_mfma_f32_16x16x32_bf16 v[4:7], v[150:153], v[222:225], v[4:7]
	v_mfma_f32_16x16x32_bf16 v[0:3], v[158:161], v[222:225], v[0:3]
	s_setprio 0
	s_barrier
	s_add_i32 s51, 0, 0x18000
	v_add_u32_e32 v64, s51, v213
	s_add_i32 s52, 0, 0x1c000
	ds_read_b128 v[130:133], v64
	ds_read_b128 v[134:137], v64 offset:1024
	ds_read_b128 v[138:141], v64 offset:2048
	ds_read_b128 v[142:145], v64 offset:3072
	v_add_u32_e32 v64, s52, v213
	ds_read_b128 v[146:149], v64
	ds_read_b128 v[150:153], v64 offset:1024
	ds_read_b128 v[154:157], v64 offset:2048
	ds_read_b128 v[158:161], v64 offset:3072
	s_add_u32 s26, s26, 0x40000
	s_addc_u32 s27, s27, 0
	s_mov_b32 m0, s42
	v_lshl_add_u64 v[228:229], s[26:27], 0, v[192:193]
	ds_read_b128 v[162:165], v227 offset:32768
	ds_read_b128 v[166:169], v227 offset:33792
	ds_read_b128 v[170:173], v227 offset:34816
	ds_read_b128 v[174:177], v227 offset:35840
	ds_read_b128 v[178:181], v227 offset:36864
	ds_read_b128 v[182:185], v227 offset:37888
	ds_read_b128 v[218:221], v227 offset:38912
	ds_read_b128 v[222:225], v227 offset:39936
	global_load_lds_dwordx4 v[228:229], off
	v_lshl_add_u64 v[228:229], s[26:27], 0, v[188:189]
	s_mov_b32 m0, s43
	s_nop 0
	global_load_lds_dwordx4 v[228:229], off
	s_waitcnt vmcnt(8)
	s_waitcnt lgkmcnt(0)
	s_barrier
	s_setprio 1
	v_mfma_f32_16x16x32_bf16 v[126:129], v[130:133], v[162:165], v[126:129]
	v_mfma_f32_16x16x32_bf16 v[122:125], v[138:141], v[162:165], v[122:125]
	v_mfma_f32_16x16x32_bf16 v[118:121], v[130:133], v[170:173], v[118:121]
	v_mfma_f32_16x16x32_bf16 v[114:117], v[138:141], v[170:173], v[114:117]
	v_mfma_f32_16x16x32_bf16 v[110:113], v[130:133], v[178:181], v[110:113]
	v_mfma_f32_16x16x32_bf16 v[106:109], v[138:141], v[178:181], v[106:109]
	v_mfma_f32_16x16x32_bf16 v[102:105], v[130:133], v[218:221], v[102:105]
	v_mfma_f32_16x16x32_bf16 v[98:101], v[138:141], v[218:221], v[98:101]
	v_mfma_f32_16x16x32_bf16 v[126:129], v[134:137], v[166:169], v[126:129]
	v_mfma_f32_16x16x32_bf16 v[122:125], v[142:145], v[166:169], v[122:125]
	v_mfma_f32_16x16x32_bf16 v[118:121], v[134:137], v[174:177], v[118:121]
	v_mfma_f32_16x16x32_bf16 v[114:117], v[142:145], v[174:177], v[114:117]
	v_mfma_f32_16x16x32_bf16 v[110:113], v[134:137], v[182:185], v[110:113]
	v_mfma_f32_16x16x32_bf16 v[106:109], v[142:145], v[182:185], v[106:109]
	v_mfma_f32_16x16x32_bf16 v[102:105], v[134:137], v[222:225], v[102:105]
	v_mfma_f32_16x16x32_bf16 v[98:101], v[142:145], v[222:225], v[98:101]
	v_mfma_f32_16x16x32_bf16 v[60:63], v[146:149], v[162:165], v[60:63]
	v_mfma_f32_16x16x32_bf16 v[56:59], v[154:157], v[162:165], v[56:59]
	v_mfma_f32_16x16x32_bf16 v[52:55], v[146:149], v[170:173], v[52:55]
	v_mfma_f32_16x16x32_bf16 v[48:51], v[154:157], v[170:173], v[48:51]
	v_mfma_f32_16x16x32_bf16 v[44:47], v[146:149], v[178:181], v[44:47]
	v_mfma_f32_16x16x32_bf16 v[40:43], v[154:157], v[178:181], v[40:43]
	v_mfma_f32_16x16x32_bf16 v[36:39], v[146:149], v[218:221], v[36:39]
	v_mfma_f32_16x16x32_bf16 v[32:35], v[154:157], v[218:221], v[32:35]
	v_mfma_f32_16x16x32_bf16 v[60:63], v[150:153], v[166:169], v[60:63]
	v_mfma_f32_16x16x32_bf16 v[56:59], v[158:161], v[166:169], v[56:59]
	v_mfma_f32_16x16x32_bf16 v[52:55], v[150:153], v[174:177], v[52:55]
	v_mfma_f32_16x16x32_bf16 v[48:51], v[158:161], v[174:177], v[48:51]
	v_mfma_f32_16x16x32_bf16 v[44:47], v[150:153], v[182:185], v[44:47]
	v_mfma_f32_16x16x32_bf16 v[40:43], v[158:161], v[182:185], v[40:43]
	v_mfma_f32_16x16x32_bf16 v[36:39], v[150:153], v[222:225], v[36:39]
	v_mfma_f32_16x16x32_bf16 v[32:35], v[158:161], v[222:225], v[32:35]
	s_setprio 0
	s_barrier
; #define PG8_STAGE(bufoff, gbase, voff) do { _Pragma("unroll") for (int _i = 0; _i < 2; ++_i) \
;         __builtin_amdgcn_global_load_lds((const unsigned*)((const char*)(gbase) + (voff)[_i]), (PG8_LAS unsigned*)(lds + (bufoff) + ldsw + _i * 8192), 16, 0, 0); } while (0)
; #define PG8_LDA(dst, b, h) do { _Pragma("unroll") for (int m = 0; m < 4; ++m) _Pragma("unroll") for (int k = 0; k < 2; ++k) dst[m][k] = *(const PG8_LAS bf16x8*)(lds + PG8_SA(b, h) + aoff + m * 2048 + k * 1024); } while (0)
; #define PG8_WAIT_V(n) asm volatile("s_waitcnt vmcnt(" #n ")" ::: "memory")
; #define PG8_WAIT_L(n) asm volatile("s_waitcnt lgkmcnt(" #n ")" ::: "memory")
; template <class Epi, class Sched, bool ALIGN_EPI = false, bool SP2 = false>
; __device__ __forceinline__ void gemm_phase(PG8_LAS unsigned char* lds, const Gemm g, const Sched& S, const Epi& E, const int tid) {
;     ...
;         for (int t = 0; t < nt; t += 2) {
;             const bool last = (t == nt - 2);
;             const char* a1 = cA + (size_t)(t + 1) * kstep;
;             const char* a2 = last ? nA : cA + (size_t)(t + 2) * kstep; const char* b2 = last ? nB : cB + (size_t)(t + 2) * kstep;
;             const char* a3 = a2 + kstep; const char* b3 = b2 + kstep;
;             if (last && has_next) S.a_ready(nxt);
;             if constexpr (SP2) {
;             PG8_LDB(B0, 0, 0); PG8_LDB(B1, 0, 1); PG8_SCHED; PG8_LDA(At, 0, 0); PG8_STAGE(PG8_SA(1, 1), a1 + hstep, voffA);
;             PG8_WAIT_V(8); PG8_WAIT_L(0); PG8_BAR; PG8_MMA(0, 0, At, B0); PG8_MMA(0, 1, At, B1); PG8_BAR; PG8_SCHED;
;             PG8_LDA(At, 0, 1); PG8_STAGE(PG8_SB(0, 0), b2, voffB); PG8_STAGE(PG8_SB(0, 1), b2 + hstep, voffB); PG8_STAGE(PG8_SA(0, 0), a2, voffA);
;             PG8_WAIT_V(8); PG8_WAIT_L(0); PG8_BAR; PG8_MMA(1, 0, At, B0); PG8_MMA(1, 1, At, B1); PG8_BAR; PG8_SCHED;
;             PG8_LDB(B0, 1, 0); PG8_LDB(B1, 1, 1); PG8_SCHED; PG8_LDA(At, 1, 0); PG8_STAGE(PG8_SA(0, 1), a2 + hstep, voffA);
;             PG8_WAIT_V(8); PG8_WAIT_L(0); PG8_BAR; PG8_MMA(0, 0, At, B0); PG8_MMA(0, 1, At, B1); PG8_BAR; PG8_SCHED;
;             PG8_LDA(At, 1, 1); PG8_STAGE(PG8_SB(1, 0), b3, voffB); PG8_STAGE(PG8_SB(1, 1), b3 + hstep, voffB); PG8_STAGE(PG8_SA(1, 0), a3, voffA);
;             PG8_WAIT_V(8); PG8_WAIT_L(0); PG8_BAR; PG8_MMA(1, 0, At, B0); PG8_MMA(1, 1, At, B1); PG8_BAR; PG8_SCHED;
;     ...
;         if constexpr (ALIGN_EPI) { if (wr == 0) PG8_BAR; }
	s_add_i32 s26, s51, s34
	v_lshl_add_u64 v[202:203], v[202:203], 0, s[94:95]
	s_mov_b32 m0, s26
	ds_read_b128 v[162:165], v227 offset:49152
	ds_read_b128 v[166:169], v227 offset:50176
	ds_read_b128 v[170:173], v227 offset:51200
	ds_read_b128 v[174:177], v227 offset:52224
	ds_read_b128 v[178:181], v227 offset:53248
	ds_read_b128 v[182:185], v227 offset:54272
	ds_read_b128 v[218:221], v227 offset:55296
	ds_read_b128 v[222:225], v227 offset:56320
	global_load_lds_dwordx4 v[202:203], off
	s_add_i32 m0, s26, 0x2000
	s_add_u32 s24, s24, 0x40080
	v_lshl_add_u64 v[202:203], v[206:207], 0, s[94:95]
	s_addc_u32 s25, s25, 0
	s_add_i32 s26, s52, s34
	global_load_lds_dwordx4 v[202:203], off
	v_lshl_add_u64 v[202:203], s[24:25], 0, v[190:191]
	s_mov_b32 m0, s26
	s_nop 0
	global_load_lds_dwordx4 v[202:203], off
	v_lshl_add_u64 v[202:203], s[24:25], 0, v[186:187]
	s_add_i32 m0, s26, 0x2000
	s_nop 0
	global_load_lds_dwordx4 v[202:203], off
	v_lshl_add_u64 v[202:203], v[208:209], 0, s[94:95]
	s_mov_b32 m0, s38
	s_nop 0
	global_load_lds_dwordx4 v[202:203], off
	v_lshl_add_u64 v[202:203], v[214:215], 0, s[94:95]
	s_mov_b32 m0, s44
	s_nop 0
	global_load_lds_dwordx4 v[202:203], off
	s_waitcnt vmcnt(8)
	s_waitcnt lgkmcnt(0)
	s_barrier
	s_setprio 1
	v_mfma_f32_16x16x32_bf16 v[94:97], v[130:133], v[162:165], v[94:97]
	v_mfma_f32_16x16x32_bf16 v[90:93], v[138:141], v[162:165], v[90:93]
	v_mfma_f32_16x16x32_bf16 v[86:89], v[130:133], v[170:173], v[86:89]
	v_mfma_f32_16x16x32_bf16 v[82:85], v[138:141], v[170:173], v[82:85]
	v_mfma_f32_16x16x32_bf16 v[78:81], v[130:133], v[178:181], v[78:81]
	v_mfma_f32_16x16x32_bf16 v[74:77], v[138:141], v[178:181], v[74:77]
	v_mfma_f32_16x16x32_bf16 v[70:73], v[130:133], v[218:221], v[70:73]
	v_mfma_f32_16x16x32_bf16 v[66:69], v[138:141], v[218:221], v[66:69]
	v_mfma_f32_16x16x32_bf16 v[94:97], v[134:137], v[166:169], v[94:97]
	v_mfma_f32_16x16x32_bf16 v[90:93], v[142:145], v[166:169], v[90:93]
	v_mfma_f32_16x16x32_bf16 v[86:89], v[134:137], v[174:177], v[86:89]
	v_mfma_f32_16x16x32_bf16 v[82:85], v[142:145], v[174:177], v[82:85]
	v_mfma_f32_16x16x32_bf16 v[78:81], v[134:137], v[182:185], v[78:81]
	v_mfma_f32_16x16x32_bf16 v[74:77], v[142:145], v[182:185], v[74:77]
	v_mfma_f32_16x16x32_bf16 v[70:73], v[134:137], v[222:225], v[70:73]
	v_mfma_f32_16x16x32_bf16 v[66:69], v[142:145], v[222:225], v[66:69]
	v_mfma_f32_16x16x32_bf16 v[28:31], v[146:149], v[162:165], v[28:31]
	v_mfma_f32_16x16x32_bf16 v[24:27], v[154:157], v[162:165], v[24:27]
	v_mfma_f32_16x16x32_bf16 v[20:23], v[146:149], v[170:173], v[20:23]
	v_mfma_f32_16x16x32_bf16 v[16:19], v[154:157], v[170:173], v[16:19]
	v_mfma_f32_16x16x32_bf16 v[12:15], v[146:149], v[178:181], v[12:15]
	v_mfma_f32_16x16x32_bf16 v[8:11], v[154:157], v[178:181], v[8:11]
	v_mfma_f32_16x16x32_bf16 v[4:7], v[146:149], v[218:221], v[4:7]
	v_mfma_f32_16x16x32_bf16 v[0:3], v[154:157], v[218:221], v[0:3]
	v_mfma_f32_16x16x32_bf16 v[28:31], v[150:153], v[166:169], v[28:31]
	v_mfma_f32_16x16x32_bf16 v[24:27], v[158:161], v[166:169], v[24:27]
	v_mfma_f32_16x16x32_bf16 v[20:23], v[150:153], v[174:177], v[20:23]
	v_mfma_f32_16x16x32_bf16 v[16:19], v[158:161], v[174:177], v[16:19]
	v_mfma_f32_16x16x32_bf16 v[12:15], v[150:153], v[182:185], v[12:15]
	v_mfma_f32_16x16x32_bf16 v[8:11], v[158:161], v[182:185], v[8:11]
	v_mfma_f32_16x16x32_bf16 v[4:7], v[150:153], v[222:225], v[4:7]
	v_mfma_f32_16x16x32_bf16 v[0:3], v[158:161], v[222:225], v[0:3]
	s_setprio 0
	s_barrier
	s_add_i32 s50, s50, 2
	s_add_u32 s48, s48, 0x100
	s_addc_u32 s49, s49, 0
	s_add_u32 s2, s2, 0x100
	s_addc_u32 s3, s3, 0
	s_cmp_gt_u32 s50, 13
	s_cbranch_scc0 .LBB0_704
	s_and_b64 vcc, exec, s[12:13]
	s_cbranch_vccz .LBB0_707
	s_barrier
